# attention branch 0: K/V band of the whole unit staged once per workgroup in LDS (aliases OUT + per-wave stages), fragments read from LDS; rest as v46
# speedup vs baseline: 1.0267x; 1.0267x over previous
.Latt_entry:
	s_mov_b64 exec, -1
	v_readlane_b32 s4, v254, 0
	v_readlane_b32 s5, v254, 1
	v_readlane_b32 s6, v254, 42
	v_readlane_b32 s7, v254, 43
	v_readlane_b32 s8, v254, 46
	v_readlane_b32 s10, v254, 53
	v_readfirstlane_b32 s0, v145
	s_movk_i32 s78, 0x90
	s_movk_i32 s79, 0x110
	s_mov_b32 s80, 0x12100
	s_movk_i32 s82, 0x4000
	s_movk_i32 s83, 0x1000
	s_mov_b32 s84, 0xc000
	s_mov_b32 s85, 0x7ffff000
	s_lshr_b32 s0, s0, 6
	s_mul_i32 s1, s0, 0x1200
	s_add_i32 s1, s1, 0x12500
	s_mov_b32 s37, 0
	v_and_b32_e32 v142, 63, v145
	v_and_b32_e32 v160, 15, v145
	v_bfe_u32 v134, v145, 4, 2
	v_lshlrev_b32_e32 v161, 4, v134
	v_lshlrev_b32_e32 v169, 2, v134
	v_and_b32_e32 v135, 7, v145
	v_lshlrev_b32_e32 v162, 4, v135
	v_bfe_u32 v164, v145, 3, 3
	v_mad_u32_u24 v165, v164, s78, v162
	v_add_u32_e32 v165, s1, v165
	v_bfe_u32 v134, v145, 2, 2
	v_add_u32_e32 v134, v134, v169
	v_and_b32_e32 v135, 3, v145
	v_lshlrev_b32_e32 v135, 3, v135
	v_mad_u32_u24 v166, v134, s78, v135
	v_add_u32_e32 v166, s1, v166
	v_xor_b32_e32 v134, 16, v142
	v_lshlrev_b32_e32 v167, 2, v134
	v_xor_b32_e32 v134, 32, v142
	v_lshlrev_b32_e32 v168, 2, v134
	v_sub_u32_e32 v134, v169, v160
	v_cmp_ge_i32_e64 s[54:55], v134, 0
	v_cmp_le_i32_e64 s[62:63], v134, 0
	v_cmp_ge_i32_e64 s[56:57], v134, -1
	v_cmp_le_i32_e64 s[64:65], v134, -1
	v_cmp_ge_i32_e64 s[58:59], v134, -2
	v_cmp_le_i32_e64 s[66:67], v134, -2
	v_cmp_ge_i32_e64 s[60:61], v134, -3
	v_cmp_le_i32_e64 s[68:69], v134, -3
	v_lshrrev_b32_e32 v134, 1, v145
	v_lshrrev_b32_e32 v135, 4, v134
	v_add_u32_e32 v135, v135, v134
	v_and_b32_e32 v136, 1, v145
	v_lshlrev_b32_e32 v137, 7, v136
	v_mad_u32_u24 v170, v135, s79, v137
	v_lshl_add_u32 v171, v134, 2, s80
	v_lshlrev_b32_e32 v135, 11, v134
	v_lshl_add_u32 v172, v136, 6, v135
	s_lshl_b32 s2, s0, 5
	v_add_u32_e32 v134, s2, v160
	v_mad_u32_u24 v149, v134, s78, v161
	v_bfe_u32 v134, v145, 2, 2
	v_add_u32_e32 v134, v134, v169
	v_add_u32_e32 v134, s2, v134
	v_and_b32_e32 v135, 3, v145
	v_lshlrev_b32_e32 v135, 3, v135
	v_mad_u32_u24 v151, v134, s78, v135
	v_add_u32_e32 v151, 0xd800, v151
	s_mul_i32 s2, s0, 48
	v_add_u32_e32 v134, s2, v164
	v_mad_u32_u24 v253, v134, s78, v162
	v_mov_b32_e32 v130, 0
	v_mov_b32_e32 v131, 0
	v_mov_b32_e32 v184, 0
	v_mov_b32_e32 v185, 0
	s_lshr_b32 s2, s10, 3
	s_and_b32 s3, s10, 7
	s_and_b32 s30, s2, 31
	s_lshl_b32 s31, s3, 5
	s_or_b32 s31, s31, s30
	s_lshr_b32 s30, s10, 8
	s_cmp_eq_u32 s8, 0x100
	s_cselect_b32 s2, s31, s2
	s_cselect_b32 s17, s30, s3
	s_lshl_b32 s16, s2, 8
	s_cmp_lt_u32 s2, 0x80
	s_cselect_b32 s12, s82, s83
	s_cselect_b32 s13, 12, 10
	s_cselect_b32 s3, s84, s85
	s_and_b32 s3, s16, s3
	s_sub_i32 s15, s16, s3
	s_lshr_b32 s30, s12, 4
	s_add_i32 s14, s30, -1
	s_lshl_b32 s30, s17, 23
	s_lshl_b32 s3, s3, 7
	s_add_u32 s30, s30, s3
	s_add_u32 s18, s4, s30
	s_addc_u32 s19, s5, 0
	s_add_u32 s20, s18, 0x4000000
	s_addc_u32 s21, s19, 0
	s_add_u32 s22, s18, 0x8000000
	s_addc_u32 s23, s19, 0
	s_lshl_b32 s2, s0, 5
	s_add_i32 s42, s15, s2
	s_mov_b32 s43, 0
	v_add_u32_e32 v134, s42, v160
	v_add_u32_e32 v134, s43, v134
	v_subrev_u32_e32 v135, s15, v134
	v_lshrrev_b32_e32 v136, 4, v135
	v_add_u32_e32 v136, v136, v135
	v_mad_u32_u24 v176, v136, s79, v161
	v_lshl_add_u32 v177, v135, 2, s80
	s_sub_i32 s2, s42, 64
	v_add_u32_e32 v178, s2, v169
	v_and_b32_e32 v135, 3, v134
	v_lshlrev_b32_e32 v135, s13, v135
	v_lshrrev_b32_e32 v136, 2, v134
	v_add_u32_e32 v135, v135, v136
	v_lshl_add_u32 v135, v135, 7, v161
	global_load_dwordx4 v[48:51], v135, s[18:19]
	global_load_dwordx4 v[52:55], v135, s[18:19] offset:64
	v_add_u32_e32 v137, 16, v134
	v_and_b32_e32 v135, 3, v137
	v_lshlrev_b32_e32 v135, s13, v135
	v_lshrrev_b32_e32 v136, 2, v137
	v_add_u32_e32 v135, v135, v136
	v_lshl_add_u32 v135, v135, 7, v161
	global_load_dwordx4 v[56:59], v135, s[18:19]
	global_load_dwordx4 v[60:63], v135, s[18:19] offset:64
	s_mul_i32 s2, s0, 48
	s_add_i32 s2, s2, s15
	s_add_i32 s2, s2, -64
	v_add_u32_e32 v138, s2, v164
	v_and_b32_e32 v139, 3, v138
	v_lshlrev_b32_e32 v139, s13, v139
	v_bfe_u32 v140, v138, 2, 2
	v_add_u32_e32 v139, v139, v140
	v_lshl_add_u32 v139, v139, 7, v162
	v_ashrrev_i32_e32 v138, 4, v138
	v_med3_i32 v138, v138, 0, s14
	v_lshl_add_u32 v138, v138, 9, v139
	global_load_dwordx4 v[0:3], v138, s[20:21]
	s_mul_i32 s2, s0, 48
	s_add_i32 s2, s2, s15
	s_add_i32 s2, s2, -56
	v_add_u32_e32 v138, s2, v164
	v_and_b32_e32 v139, 3, v138
	v_lshlrev_b32_e32 v139, s13, v139
	v_bfe_u32 v140, v138, 2, 2
	v_add_u32_e32 v139, v139, v140
	v_lshl_add_u32 v139, v139, 7, v162
	v_ashrrev_i32_e32 v138, 4, v138
	v_med3_i32 v138, v138, 0, s14
	v_lshl_add_u32 v138, v138, 9, v139
	global_load_dwordx4 v[4:7], v138, s[20:21]
	s_mul_i32 s2, s0, 48
	s_add_i32 s2, s2, s15
	s_add_i32 s2, s2, -48
	v_add_u32_e32 v138, s2, v164
	v_and_b32_e32 v139, 3, v138
	v_lshlrev_b32_e32 v139, s13, v139
	v_bfe_u32 v140, v138, 2, 2
	v_add_u32_e32 v139, v139, v140
	v_lshl_add_u32 v139, v139, 7, v162
	v_ashrrev_i32_e32 v138, 4, v138
	v_med3_i32 v138, v138, 0, s14
	v_lshl_add_u32 v138, v138, 9, v139
	global_load_dwordx4 v[8:11], v138, s[20:21]
	s_mul_i32 s2, s0, 48
	s_add_i32 s2, s2, s15
	s_add_i32 s2, s2, -40
	v_add_u32_e32 v138, s2, v164
	v_and_b32_e32 v139, 3, v138
	v_lshlrev_b32_e32 v139, s13, v139
	v_bfe_u32 v140, v138, 2, 2
	v_add_u32_e32 v139, v139, v140
	v_lshl_add_u32 v139, v139, 7, v162
	v_ashrrev_i32_e32 v138, 4, v138
	v_med3_i32 v138, v138, 0, s14
	v_lshl_add_u32 v138, v138, 9, v139
	global_load_dwordx4 v[12:15], v138, s[20:21]
	s_mul_i32 s2, s0, 48
	s_add_i32 s2, s2, s15
	s_add_i32 s2, s2, -32
	v_add_u32_e32 v138, s2, v164
	v_and_b32_e32 v139, 3, v138
	v_lshlrev_b32_e32 v139, s13, v139
	v_bfe_u32 v140, v138, 2, 2
	v_add_u32_e32 v139, v139, v140
	v_lshl_add_u32 v139, v139, 7, v162
	v_ashrrev_i32_e32 v138, 4, v138
	v_med3_i32 v138, v138, 0, s14
	v_lshl_add_u32 v138, v138, 9, v139
	global_load_dwordx4 v[16:19], v138, s[20:21]
	s_mul_i32 s2, s0, 48
	s_add_i32 s2, s2, s15
	s_add_i32 s2, s2, -24
	v_add_u32_e32 v138, s2, v164
	v_and_b32_e32 v139, 3, v138
	v_lshlrev_b32_e32 v139, s13, v139
	v_bfe_u32 v140, v138, 2, 2
	v_add_u32_e32 v139, v139, v140
	v_lshl_add_u32 v139, v139, 7, v162
	v_ashrrev_i32_e32 v138, 4, v138
	v_med3_i32 v138, v138, 0, s14
	v_lshl_add_u32 v138, v138, 9, v139
	global_load_dwordx4 v[20:23], v138, s[20:21]
	s_mul_i32 s2, s0, 48
	s_add_i32 s2, s2, s15
	s_add_i32 s2, s2, -64
	v_add_u32_e32 v138, s2, v164
	v_and_b32_e32 v139, 3, v138
	v_lshlrev_b32_e32 v139, s13, v139
	v_bfe_u32 v140, v138, 2, 2
	v_add_u32_e32 v139, v139, v140
	v_lshl_add_u32 v139, v139, 7, v162
	v_ashrrev_i32_e32 v138, 4, v138
	v_med3_i32 v138, v138, 0, s14
	v_lshl_add_u32 v138, v138, 9, v139
	global_load_dwordx4 v[24:27], v138, s[22:23]
	s_mul_i32 s2, s0, 48
	s_add_i32 s2, s2, s15
	s_add_i32 s2, s2, -56
	v_add_u32_e32 v138, s2, v164
	v_and_b32_e32 v139, 3, v138
	v_lshlrev_b32_e32 v139, s13, v139
	v_bfe_u32 v140, v138, 2, 2
	v_add_u32_e32 v139, v139, v140
	v_lshl_add_u32 v139, v139, 7, v162
	v_ashrrev_i32_e32 v138, 4, v138
	v_med3_i32 v138, v138, 0, s14
	v_lshl_add_u32 v138, v138, 9, v139
	global_load_dwordx4 v[28:31], v138, s[22:23]
	s_mul_i32 s2, s0, 48
	s_add_i32 s2, s2, s15
	s_add_i32 s2, s2, -48
	v_add_u32_e32 v138, s2, v164
	v_and_b32_e32 v139, 3, v138
	v_lshlrev_b32_e32 v139, s13, v139
	v_bfe_u32 v140, v138, 2, 2
	v_add_u32_e32 v139, v139, v140
	v_lshl_add_u32 v139, v139, 7, v162
	v_ashrrev_i32_e32 v138, 4, v138
	v_med3_i32 v138, v138, 0, s14
	v_lshl_add_u32 v138, v138, 9, v139
	global_load_dwordx4 v[32:35], v138, s[22:23]
	s_mul_i32 s2, s0, 48
	s_add_i32 s2, s2, s15
	s_add_i32 s2, s2, -40
	v_add_u32_e32 v138, s2, v164
	v_and_b32_e32 v139, 3, v138
	v_lshlrev_b32_e32 v139, s13, v139
	v_bfe_u32 v140, v138, 2, 2
	v_add_u32_e32 v139, v139, v140
	v_lshl_add_u32 v139, v139, 7, v162
	v_ashrrev_i32_e32 v138, 4, v138
	v_med3_i32 v138, v138, 0, s14
	v_lshl_add_u32 v138, v138, 9, v139
	global_load_dwordx4 v[36:39], v138, s[22:23]
	s_mul_i32 s2, s0, 48
	s_add_i32 s2, s2, s15
	s_add_i32 s2, s2, -32
	v_add_u32_e32 v138, s2, v164
	v_and_b32_e32 v139, 3, v138
	v_lshlrev_b32_e32 v139, s13, v139
	v_bfe_u32 v140, v138, 2, 2
	v_add_u32_e32 v139, v139, v140
	v_lshl_add_u32 v139, v139, 7, v162
	v_ashrrev_i32_e32 v138, 4, v138
	v_med3_i32 v138, v138, 0, s14
	v_lshl_add_u32 v138, v138, 9, v139
	global_load_dwordx4 v[40:43], v138, s[22:23]
	s_mul_i32 s2, s0, 48
	s_add_i32 s2, s2, s15
	s_add_i32 s2, s2, -24
	v_add_u32_e32 v138, s2, v164
	v_and_b32_e32 v139, 3, v138
	v_lshlrev_b32_e32 v139, s13, v139
	v_bfe_u32 v140, v138, 2, 2
	v_add_u32_e32 v139, v139, v140
	v_lshl_add_u32 v139, v139, 7, v162
	v_ashrrev_i32_e32 v138, 4, v138
	v_med3_i32 v138, v138, 0, s14
	v_lshl_add_u32 v138, v138, 9, v139
	global_load_dwordx4 v[44:47], v138, s[22:23]
	s_waitcnt vmcnt(0)
.Latt_unit:
	s_mov_b32 s33, s12
	s_mov_b32 s34, s15
	s_mov_b32 s35, s16
	s_mov_b32 s36, s17
	s_mov_b32 s38, s14
	s_mov_b32 s39, s13
	s_mov_b32 s24, s20
	s_mov_b32 s25, s21
	s_mov_b32 s26, s22
	s_mov_b32 s27, s23
	s_mov_b32 s40, s42
	s_mov_b32 s41, s43
	v_mov_b32_e32 v173, v176
	v_mov_b32_e32 v174, v177
	v_mov_b32_e32 v175, v178
	v_mov_b32_e32 v179, v183
	v_mov_b32_e32 v182, v252
	s_lshr_b32 s44, s33, 0
	s_lshr_b32 s2, s0, 2
	s_lshl_b32 s2, s2, 5
	s_lshr_b32 s3, s15, 2
	s_add_i32 s42, s3, s2
	s_and_b32 s43, s0, 3
	s_waitcnt vmcnt(4)
	ds_write_b128 v253, v[0:3]
	ds_write_b128 v253, v[4:7] offset:1152
	ds_write_b128 v253, v[8:11] offset:2304
	ds_write_b128 v253, v[12:15] offset:3456
	ds_write_b128 v253, v[16:19] offset:4608
	ds_write_b128 v253, v[20:23] offset:5760
	ds_write_b128 v253, v[24:27] offset:55296
	ds_write_b128 v253, v[28:31] offset:56448
	ds_write_b128 v253, v[32:35] offset:57600
	ds_write_b128 v253, v[36:39] offset:58752
	ds_write_b128 v253, v[40:43] offset:59904
	ds_write_b128 v253, v[44:47] offset:61056
	s_waitcnt lgkmcnt(0)
	s_barrier
	v_mov_b32_e32 v132, 0
	v_mov_b32_e32 v133, 0
	ds_read_b128 v[0:3], v149
	ds_read_b128 v[4:7], v149 offset:64
	ds_read_b128 v[8:11], v149 offset:2304
	ds_read_b128 v[12:15], v149 offset:2368
	ds_read_b128 v[16:19], v149 offset:4608
	ds_read_b128 v[20:23], v149 offset:4672
	ds_read_b128 v[24:27], v149 offset:6912
	ds_read_b128 v[28:31], v149 offset:6976
	ds_read_b128 v[32:35], v149 offset:9216
	ds_read_b128 v[36:39], v149 offset:9280
	ds_read_b128 v[40:43], v149 offset:11520
	ds_read_b128 v[44:47], v149 offset:11584
	ds_read_b128 v[64:67], v149 offset:13824
	ds_read_b128 v[68:71], v149 offset:13888
	ds_read_b128 v[72:75], v149 offset:16128
	ds_read_b128 v[76:79], v149 offset:16192
	ds_read_b128 v[80:83], v149 offset:18432
	ds_read_b128 v[84:87], v149 offset:18496
	ds_read_b128 v[88:91], v149 offset:20736
	ds_read_b128 v[92:95], v149 offset:20800
	s_waitcnt lgkmcnt(0)
	v_mfma_f32_16x16x32_bf16 v[236:239], v[0:3], v[48:51], 0
	v_mfma_f32_16x16x32_bf16 v[236:239], v[4:7], v[52:55], v[236:239]
	v_mfma_f32_16x16x32_bf16 v[240:243], v[8:11], v[48:51], 0
	v_mfma_f32_16x16x32_bf16 v[240:243], v[12:15], v[52:55], v[240:243]
	v_mfma_f32_16x16x32_bf16 v[248:251], v[8:11], v[56:59], 0
	v_mfma_f32_16x16x32_bf16 v[248:251], v[12:15], v[60:63], v[248:251]
	s_nop 7
	v_min_f32_e32 v152, 0x42a00000, v236
	v_min_f32_e32 v153, 0x42a00000, v237
	v_min_f32_e32 v154, 0x42a00000, v238
	v_min_f32_e32 v155, 0x42a00000, v239
	v_mfma_f32_16x16x32_bf16 v[236:239], v[16:19], v[48:51], 0
	v_mfma_f32_16x16x32_bf16 v[236:239], v[20:23], v[52:55], v[236:239]
	v_mfma_f32_16x16x32_bf16 v[244:247], v[16:19], v[56:59], 0
	v_mfma_f32_16x16x32_bf16 v[244:247], v[20:23], v[60:63], v[244:247]
	v_mul_f32_e32 v152, 0x3fb8aa3b, v152
	v_mul_f32_e32 v153, 0x3fb8aa3b, v153
	v_mul_f32_e32 v154, 0x3fb8aa3b, v154
	v_mul_f32_e32 v155, 0x3fb8aa3b, v155
	v_exp_f32_e32 v152, v152
	v_exp_f32_e32 v153, v153
	v_exp_f32_e32 v154, v154
	v_exp_f32_e32 v155, v155
	v_add_u32_e32 v138, 0, v175
	v_add_u32_e32 v139, 1, v175
	v_add_u32_e32 v140, 2, v175
	v_add_u32_e32 v141, 3, v175
	v_cmp_gt_u32_e64 s[70:71], s44, v138
	v_cmp_gt_u32_e64 s[72:73], s44, v139
	v_cmp_gt_u32_e64 s[74:75], s44, v140
	v_cmp_gt_u32_e64 s[76:77], s44, v141
	v_cndmask_b32_e64 v152, 0, v152, s[54:55]
	v_cndmask_b32_e64 v153, 0, v153, s[56:57]
	v_cndmask_b32_e64 v154, 0, v154, s[58:59]
	v_cndmask_b32_e64 v155, 0, v155, s[60:61]
	v_cndmask_b32_e64 v152, 0, v152, s[70:71]
	v_cndmask_b32_e64 v153, 0, v153, s[72:73]
	v_cndmask_b32_e64 v154, 0, v154, s[74:75]
	v_cndmask_b32_e64 v155, 0, v155, s[76:77]
	v_add_f32_e32 v132, v132, v152
	v_add_f32_e32 v132, v132, v153
	v_add_f32_e32 v132, v132, v154
	v_add_f32_e32 v132, v132, v155
	v_cvt_pk_bf16_f32 v112, v152, v153
	v_cvt_pk_bf16_f32 v113, v154, v155
	v_min_f32_e32 v152, 0x42a00000, v240
	v_min_f32_e32 v153, 0x42a00000, v241
	v_min_f32_e32 v154, 0x42a00000, v242
	v_min_f32_e32 v155, 0x42a00000, v243
	v_min_f32_e32 v156, 0x42a00000, v248
	v_min_f32_e32 v157, 0x42a00000, v249
	v_min_f32_e32 v158, 0x42a00000, v250
	v_min_f32_e32 v159, 0x42a00000, v251
	v_mfma_f32_16x16x32_bf16 v[240:243], v[24:27], v[48:51], 0
	v_mfma_f32_16x16x32_bf16 v[240:243], v[28:31], v[52:55], v[240:243]
	v_mfma_f32_16x16x32_bf16 v[248:251], v[24:27], v[56:59], 0
	v_mfma_f32_16x16x32_bf16 v[248:251], v[28:31], v[60:63], v[248:251]
	v_mul_f32_e32 v152, 0x3fb8aa3b, v152
	v_mul_f32_e32 v153, 0x3fb8aa3b, v153
	v_mul_f32_e32 v154, 0x3fb8aa3b, v154
	v_mul_f32_e32 v155, 0x3fb8aa3b, v155
	v_exp_f32_e32 v152, v152
	v_exp_f32_e32 v153, v153
	v_exp_f32_e32 v154, v154
	v_exp_f32_e32 v155, v155
	v_add_u32_e32 v138, 16, v175
	v_add_u32_e32 v139, 17, v175
	v_add_u32_e32 v140, 18, v175
	v_add_u32_e32 v141, 19, v175
	v_cmp_gt_u32_e64 s[70:71], s44, v138
	v_cmp_gt_u32_e64 s[72:73], s44, v139
	v_cmp_gt_u32_e64 s[74:75], s44, v140
	v_cmp_gt_u32_e64 s[76:77], s44, v141
	v_cndmask_b32_e64 v152, 0, v152, s[70:71]
	v_cndmask_b32_e64 v153, 0, v153, s[72:73]
	v_cndmask_b32_e64 v154, 0, v154, s[74:75]
	v_cndmask_b32_e64 v155, 0, v155, s[76:77]
	v_add_f32_e32 v132, v132, v152
	v_add_f32_e32 v132, v132, v153
	v_add_f32_e32 v132, v132, v154
	v_add_f32_e32 v132, v132, v155
	v_cvt_pk_bf16_f32 v114, v152, v153
	v_cvt_pk_bf16_f32 v115, v154, v155
	v_mul_f32_e32 v156, 0x3fb8aa3b, v156
	v_mul_f32_e32 v157, 0x3fb8aa3b, v157
	v_mul_f32_e32 v158, 0x3fb8aa3b, v158
	v_mul_f32_e32 v159, 0x3fb8aa3b, v159
	v_exp_f32_e32 v156, v156
	v_exp_f32_e32 v157, v157
	v_exp_f32_e32 v158, v158
	v_exp_f32_e32 v159, v159
	v_add_u32_e32 v138, 16, v175
	v_add_u32_e32 v139, 17, v175
	v_add_u32_e32 v140, 18, v175
	v_add_u32_e32 v141, 19, v175
	v_cmp_gt_u32_e64 s[70:71], s44, v138
	v_cmp_gt_u32_e64 s[72:73], s44, v139
	v_cmp_gt_u32_e64 s[74:75], s44, v140
	v_cmp_gt_u32_e64 s[76:77], s44, v141
	v_cndmask_b32_e64 v156, 0, v156, s[54:55]
	v_cndmask_b32_e64 v157, 0, v157, s[56:57]
	v_cndmask_b32_e64 v158, 0, v158, s[58:59]
	v_cndmask_b32_e64 v159, 0, v159, s[60:61]
	v_cndmask_b32_e64 v156, 0, v156, s[70:71]
	v_cndmask_b32_e64 v157, 0, v157, s[72:73]
	v_cndmask_b32_e64 v158, 0, v158, s[74:75]
	v_cndmask_b32_e64 v159, 0, v159, s[76:77]
	v_add_f32_e32 v133, v133, v156
	v_add_f32_e32 v133, v133, v157
	v_add_f32_e32 v133, v133, v158
	v_add_f32_e32 v133, v133, v159
	v_cvt_pk_bf16_f32 v186, v156, v157
	v_cvt_pk_bf16_f32 v187, v158, v159
	v_min_f32_e32 v152, 0x42a00000, v236
	v_min_f32_e32 v153, 0x42a00000, v237
	v_min_f32_e32 v154, 0x42a00000, v238
	v_min_f32_e32 v155, 0x42a00000, v239
	v_min_f32_e32 v156, 0x42a00000, v244
	v_min_f32_e32 v157, 0x42a00000, v245
	v_min_f32_e32 v158, 0x42a00000, v246
	v_min_f32_e32 v159, 0x42a00000, v247
	v_mfma_f32_16x16x32_bf16 v[236:239], v[32:35], v[48:51], 0
	v_mfma_f32_16x16x32_bf16 v[236:239], v[36:39], v[52:55], v[236:239]
	v_mfma_f32_16x16x32_bf16 v[244:247], v[32:35], v[56:59], 0
	v_mfma_f32_16x16x32_bf16 v[244:247], v[36:39], v[60:63], v[244:247]
	v_mul_f32_e32 v152, 0x3fb8aa3b, v152
	v_mul_f32_e32 v153, 0x3fb8aa3b, v153
	v_mul_f32_e32 v154, 0x3fb8aa3b, v154
	v_mul_f32_e32 v155, 0x3fb8aa3b, v155
	v_exp_f32_e32 v152, v152
	v_exp_f32_e32 v153, v153
	v_exp_f32_e32 v154, v154
	v_exp_f32_e32 v155, v155
	v_add_u32_e32 v138, 32, v175
	v_add_u32_e32 v139, 33, v175
	v_add_u32_e32 v140, 34, v175
	v_add_u32_e32 v141, 35, v175
	v_cmp_gt_u32_e64 s[70:71], s44, v138
	v_cmp_gt_u32_e64 s[72:73], s44, v139
	v_cmp_gt_u32_e64 s[74:75], s44, v140
	v_cmp_gt_u32_e64 s[76:77], s44, v141
	v_cndmask_b32_e64 v152, 0, v152, s[70:71]
	v_cndmask_b32_e64 v153, 0, v153, s[72:73]
	v_cndmask_b32_e64 v154, 0, v154, s[74:75]
	v_cndmask_b32_e64 v155, 0, v155, s[76:77]
	v_add_f32_e32 v132, v132, v152
	v_add_f32_e32 v132, v132, v153
	v_add_f32_e32 v132, v132, v154
	v_add_f32_e32 v132, v132, v155
	v_cvt_pk_bf16_f32 v116, v152, v153
	v_cvt_pk_bf16_f32 v117, v154, v155
	v_mul_f32_e32 v156, 0x3fb8aa3b, v156
	v_mul_f32_e32 v157, 0x3fb8aa3b, v157
	v_mul_f32_e32 v158, 0x3fb8aa3b, v158
	v_mul_f32_e32 v159, 0x3fb8aa3b, v159
	v_exp_f32_e32 v156, v156
	v_exp_f32_e32 v157, v157
	v_exp_f32_e32 v158, v158
	v_exp_f32_e32 v159, v159
	v_add_u32_e32 v138, 32, v175
	v_add_u32_e32 v139, 33, v175
	v_add_u32_e32 v140, 34, v175
	v_add_u32_e32 v141, 35, v175
	v_cmp_gt_u32_e64 s[70:71], s44, v138
	v_cmp_gt_u32_e64 s[72:73], s44, v139
	v_cmp_gt_u32_e64 s[74:75], s44, v140
	v_cmp_gt_u32_e64 s[76:77], s44, v141
	v_cndmask_b32_e64 v156, 0, v156, s[70:71]
	v_cndmask_b32_e64 v157, 0, v157, s[72:73]
	v_cndmask_b32_e64 v158, 0, v158, s[74:75]
	v_cndmask_b32_e64 v159, 0, v159, s[76:77]
	v_add_f32_e32 v133, v133, v156
	v_add_f32_e32 v133, v133, v157
	v_add_f32_e32 v133, v133, v158
	v_add_f32_e32 v133, v133, v159
	v_cvt_pk_bf16_f32 v188, v156, v157
	v_cvt_pk_bf16_f32 v189, v158, v159
	v_min_f32_e32 v152, 0x42a00000, v240
	v_min_f32_e32 v153, 0x42a00000, v241
	v_min_f32_e32 v154, 0x42a00000, v242
	v_min_f32_e32 v155, 0x42a00000, v243
	v_min_f32_e32 v156, 0x42a00000, v248
	v_min_f32_e32 v157, 0x42a00000, v249
	v_min_f32_e32 v158, 0x42a00000, v250
	v_min_f32_e32 v159, 0x42a00000, v251
	v_mfma_f32_16x16x32_bf16 v[240:243], v[40:43], v[48:51], 0
	v_mfma_f32_16x16x32_bf16 v[240:243], v[44:47], v[52:55], v[240:243]
	v_mfma_f32_16x16x32_bf16 v[248:251], v[40:43], v[56:59], 0
	v_mfma_f32_16x16x32_bf16 v[248:251], v[44:47], v[60:63], v[248:251]
	v_mul_f32_e32 v152, 0x3fb8aa3b, v152
	v_mul_f32_e32 v153, 0x3fb8aa3b, v153
	v_mul_f32_e32 v154, 0x3fb8aa3b, v154
	v_mul_f32_e32 v155, 0x3fb8aa3b, v155
	v_exp_f32_e32 v152, v152
	v_exp_f32_e32 v153, v153
	v_exp_f32_e32 v154, v154
	v_exp_f32_e32 v155, v155
	v_add_u32_e32 v138, 48, v175
	v_add_u32_e32 v139, 49, v175
	v_add_u32_e32 v140, 50, v175
	v_add_u32_e32 v141, 51, v175
	v_cmp_gt_u32_e64 s[70:71], s44, v138
	v_cmp_gt_u32_e64 s[72:73], s44, v139
	v_cmp_gt_u32_e64 s[74:75], s44, v140
	v_cmp_gt_u32_e64 s[76:77], s44, v141
	v_cndmask_b32_e64 v152, 0, v152, s[70:71]
	v_cndmask_b32_e64 v153, 0, v153, s[72:73]
	v_cndmask_b32_e64 v154, 0, v154, s[74:75]
	v_cndmask_b32_e64 v155, 0, v155, s[76:77]
	v_add_f32_e32 v132, v132, v152
	v_add_f32_e32 v132, v132, v153
	v_add_f32_e32 v132, v132, v154
	v_add_f32_e32 v132, v132, v155
	v_cvt_pk_bf16_f32 v118, v152, v153
	v_cvt_pk_bf16_f32 v119, v154, v155
	v_mul_f32_e32 v156, 0x3fb8aa3b, v156
	v_mul_f32_e32 v157, 0x3fb8aa3b, v157
	v_mul_f32_e32 v158, 0x3fb8aa3b, v158
	v_mul_f32_e32 v159, 0x3fb8aa3b, v159
	v_exp_f32_e32 v156, v156
	v_exp_f32_e32 v157, v157
	v_exp_f32_e32 v158, v158
	v_exp_f32_e32 v159, v159
	v_add_u32_e32 v138, 48, v175
	v_add_u32_e32 v139, 49, v175
	v_add_u32_e32 v140, 50, v175
	v_add_u32_e32 v141, 51, v175
	v_cmp_gt_u32_e64 s[70:71], s44, v138
	v_cmp_gt_u32_e64 s[72:73], s44, v139
	v_cmp_gt_u32_e64 s[74:75], s44, v140
	v_cmp_gt_u32_e64 s[76:77], s44, v141
	v_cndmask_b32_e64 v156, 0, v156, s[70:71]
	v_cndmask_b32_e64 v157, 0, v157, s[72:73]
	v_cndmask_b32_e64 v158, 0, v158, s[74:75]
	v_cndmask_b32_e64 v159, 0, v159, s[76:77]
	v_add_f32_e32 v133, v133, v156
	v_add_f32_e32 v133, v133, v157
	v_add_f32_e32 v133, v133, v158
	v_add_f32_e32 v133, v133, v159
	v_cvt_pk_bf16_f32 v190, v156, v157
	v_cvt_pk_bf16_f32 v191, v158, v159
	v_min_f32_e32 v152, 0x42a00000, v236
	v_min_f32_e32 v153, 0x42a00000, v237
	v_min_f32_e32 v154, 0x42a00000, v238
	v_min_f32_e32 v155, 0x42a00000, v239
	v_min_f32_e32 v156, 0x42a00000, v244
	v_min_f32_e32 v157, 0x42a00000, v245
	v_min_f32_e32 v158, 0x42a00000, v246
	v_min_f32_e32 v159, 0x42a00000, v247
	v_mfma_f32_16x16x32_bf16 v[236:239], v[64:67], v[48:51], 0
	v_mfma_f32_16x16x32_bf16 v[236:239], v[68:71], v[52:55], v[236:239]
	v_mfma_f32_16x16x32_bf16 v[244:247], v[64:67], v[56:59], 0
	v_mfma_f32_16x16x32_bf16 v[244:247], v[68:71], v[60:63], v[244:247]
	v_mul_f32_e32 v152, 0x3fb8aa3b, v152
	v_mul_f32_e32 v153, 0x3fb8aa3b, v153
	v_mul_f32_e32 v154, 0x3fb8aa3b, v154
	v_mul_f32_e32 v155, 0x3fb8aa3b, v155
	v_exp_f32_e32 v152, v152
	v_exp_f32_e32 v153, v153
	v_exp_f32_e32 v154, v154
	v_exp_f32_e32 v155, v155
	v_add_u32_e32 v138, 64, v175
	v_add_u32_e32 v139, 0x41, v175
	v_add_u32_e32 v140, 0x42, v175
	v_add_u32_e32 v141, 0x43, v175
	v_cmp_gt_u32_e64 s[70:71], s44, v138
	v_cmp_gt_u32_e64 s[72:73], s44, v139
	v_cmp_gt_u32_e64 s[74:75], s44, v140
	v_cmp_gt_u32_e64 s[76:77], s44, v141
	v_cndmask_b32_e64 v152, 0, v152, s[70:71]
	v_cndmask_b32_e64 v153, 0, v153, s[72:73]
	v_cndmask_b32_e64 v154, 0, v154, s[74:75]
	v_cndmask_b32_e64 v155, 0, v155, s[76:77]
	v_add_f32_e32 v132, v132, v152
	v_add_f32_e32 v132, v132, v153
	v_add_f32_e32 v132, v132, v154
	v_add_f32_e32 v132, v132, v155
	v_cvt_pk_bf16_f32 v120, v152, v153
	v_cvt_pk_bf16_f32 v121, v154, v155
	v_mul_f32_e32 v156, 0x3fb8aa3b, v156
	v_mul_f32_e32 v157, 0x3fb8aa3b, v157
	v_mul_f32_e32 v158, 0x3fb8aa3b, v158
	v_mul_f32_e32 v159, 0x3fb8aa3b, v159
	v_exp_f32_e32 v156, v156
	v_exp_f32_e32 v157, v157
	v_exp_f32_e32 v158, v158
	v_exp_f32_e32 v159, v159
	v_add_u32_e32 v138, 64, v175
	v_add_u32_e32 v139, 0x41, v175
	v_add_u32_e32 v140, 0x42, v175
	v_add_u32_e32 v141, 0x43, v175
	v_cmp_gt_u32_e64 s[70:71], s44, v138
	v_cmp_gt_u32_e64 s[72:73], s44, v139
	v_cmp_gt_u32_e64 s[74:75], s44, v140
	v_cmp_gt_u32_e64 s[76:77], s44, v141
	v_cndmask_b32_e64 v156, 0, v156, s[70:71]
	v_cndmask_b32_e64 v157, 0, v157, s[72:73]
	v_cndmask_b32_e64 v158, 0, v158, s[74:75]
	v_cndmask_b32_e64 v159, 0, v159, s[76:77]
	v_add_f32_e32 v133, v133, v156
	v_add_f32_e32 v133, v133, v157
	v_add_f32_e32 v133, v133, v158
	v_add_f32_e32 v133, v133, v159
	v_cvt_pk_bf16_f32 v192, v156, v157
	v_cvt_pk_bf16_f32 v193, v158, v159
	v_min_f32_e32 v152, 0x42a00000, v240
	v_min_f32_e32 v153, 0x42a00000, v241
	v_min_f32_e32 v154, 0x42a00000, v242
	v_min_f32_e32 v155, 0x42a00000, v243
	v_min_f32_e32 v156, 0x42a00000, v248
	v_min_f32_e32 v157, 0x42a00000, v249
	v_min_f32_e32 v158, 0x42a00000, v250
	v_min_f32_e32 v159, 0x42a00000, v251
	v_mfma_f32_16x16x32_bf16 v[240:243], v[72:75], v[48:51], 0
	v_mfma_f32_16x16x32_bf16 v[240:243], v[76:79], v[52:55], v[240:243]
	v_mfma_f32_16x16x32_bf16 v[248:251], v[72:75], v[56:59], 0
	v_mfma_f32_16x16x32_bf16 v[248:251], v[76:79], v[60:63], v[248:251]
	v_mul_f32_e32 v152, 0x3fb8aa3b, v152
	v_mul_f32_e32 v153, 0x3fb8aa3b, v153
	v_mul_f32_e32 v154, 0x3fb8aa3b, v154
	v_mul_f32_e32 v155, 0x3fb8aa3b, v155
	v_exp_f32_e32 v152, v152
	v_exp_f32_e32 v153, v153
	v_exp_f32_e32 v154, v154
	v_exp_f32_e32 v155, v155
	v_add_u32_e32 v138, 0x50, v175
	v_add_u32_e32 v139, 0x51, v175
	v_add_u32_e32 v140, 0x52, v175
	v_add_u32_e32 v141, 0x53, v175
	v_cmp_gt_u32_e64 s[70:71], s44, v138
	v_cmp_gt_u32_e64 s[72:73], s44, v139
	v_cmp_gt_u32_e64 s[74:75], s44, v140
	v_cmp_gt_u32_e64 s[76:77], s44, v141
	v_cndmask_b32_e64 v152, 0, v152, s[70:71]
	v_cndmask_b32_e64 v153, 0, v153, s[72:73]
	v_cndmask_b32_e64 v154, 0, v154, s[74:75]
	v_cndmask_b32_e64 v155, 0, v155, s[76:77]
	v_add_f32_e32 v132, v132, v152
	v_add_f32_e32 v132, v132, v153
	v_add_f32_e32 v132, v132, v154
	v_add_f32_e32 v132, v132, v155
	v_cvt_pk_bf16_f32 v122, v152, v153
	v_cvt_pk_bf16_f32 v123, v154, v155
	v_mul_f32_e32 v156, 0x3fb8aa3b, v156
	v_mul_f32_e32 v157, 0x3fb8aa3b, v157
	v_mul_f32_e32 v158, 0x3fb8aa3b, v158
	v_mul_f32_e32 v159, 0x3fb8aa3b, v159
	v_exp_f32_e32 v156, v156
	v_exp_f32_e32 v157, v157
	v_exp_f32_e32 v158, v158
	v_exp_f32_e32 v159, v159
	v_add_u32_e32 v138, 0x50, v175
	v_add_u32_e32 v139, 0x51, v175
	v_add_u32_e32 v140, 0x52, v175
	v_add_u32_e32 v141, 0x53, v175
	v_cmp_gt_u32_e64 s[70:71], s44, v138
	v_cmp_gt_u32_e64 s[72:73], s44, v139
	v_cmp_gt_u32_e64 s[74:75], s44, v140
	v_cmp_gt_u32_e64 s[76:77], s44, v141
	v_cndmask_b32_e64 v156, 0, v156, s[70:71]
	v_cndmask_b32_e64 v157, 0, v157, s[72:73]
	v_cndmask_b32_e64 v158, 0, v158, s[74:75]
	v_cndmask_b32_e64 v159, 0, v159, s[76:77]
	v_add_f32_e32 v133, v133, v156
	v_add_f32_e32 v133, v133, v157
	v_add_f32_e32 v133, v133, v158
	v_add_f32_e32 v133, v133, v159
	v_cvt_pk_bf16_f32 v194, v156, v157
	v_cvt_pk_bf16_f32 v195, v158, v159
	v_min_f32_e32 v152, 0x42a00000, v236
	v_min_f32_e32 v153, 0x42a00000, v237
	v_min_f32_e32 v154, 0x42a00000, v238
	v_min_f32_e32 v155, 0x42a00000, v239
	v_min_f32_e32 v156, 0x42a00000, v244
	v_min_f32_e32 v157, 0x42a00000, v245
	v_min_f32_e32 v158, 0x42a00000, v246
	v_min_f32_e32 v159, 0x42a00000, v247
	v_mfma_f32_16x16x32_bf16 v[236:239], v[80:83], v[48:51], 0
	v_mfma_f32_16x16x32_bf16 v[236:239], v[84:87], v[52:55], v[236:239]
	v_mfma_f32_16x16x32_bf16 v[244:247], v[80:83], v[56:59], 0
	v_mfma_f32_16x16x32_bf16 v[244:247], v[84:87], v[60:63], v[244:247]
	v_mul_f32_e32 v152, 0x3fb8aa3b, v152
	v_mul_f32_e32 v153, 0x3fb8aa3b, v153
	v_mul_f32_e32 v154, 0x3fb8aa3b, v154
	v_mul_f32_e32 v155, 0x3fb8aa3b, v155
	v_exp_f32_e32 v152, v152
	v_exp_f32_e32 v153, v153
	v_exp_f32_e32 v154, v154
	v_exp_f32_e32 v155, v155
	v_add_u32_e32 v138, 0x60, v175
	v_add_u32_e32 v139, 0x61, v175
	v_add_u32_e32 v140, 0x62, v175
	v_add_u32_e32 v141, 0x63, v175
	v_cmp_gt_u32_e64 s[70:71], s44, v138
	v_cmp_gt_u32_e64 s[72:73], s44, v139
	v_cmp_gt_u32_e64 s[74:75], s44, v140
	v_cmp_gt_u32_e64 s[76:77], s44, v141
	v_cndmask_b32_e64 v152, 0, v152, s[70:71]
	v_cndmask_b32_e64 v153, 0, v153, s[72:73]
	v_cndmask_b32_e64 v154, 0, v154, s[74:75]
	v_cndmask_b32_e64 v155, 0, v155, s[76:77]
	v_add_f32_e32 v132, v132, v152
	v_add_f32_e32 v132, v132, v153
	v_add_f32_e32 v132, v132, v154
	v_add_f32_e32 v132, v132, v155
	v_cvt_pk_bf16_f32 v124, v152, v153
	v_cvt_pk_bf16_f32 v125, v154, v155
	v_mul_f32_e32 v156, 0x3fb8aa3b, v156
	v_mul_f32_e32 v157, 0x3fb8aa3b, v157
	v_mul_f32_e32 v158, 0x3fb8aa3b, v158
	v_mul_f32_e32 v159, 0x3fb8aa3b, v159
	v_exp_f32_e32 v156, v156
	v_exp_f32_e32 v157, v157
	v_exp_f32_e32 v158, v158
	v_exp_f32_e32 v159, v159
	v_add_u32_e32 v138, 0x60, v175
	v_add_u32_e32 v139, 0x61, v175
	v_add_u32_e32 v140, 0x62, v175
	v_add_u32_e32 v141, 0x63, v175
	v_cmp_gt_u32_e64 s[70:71], s44, v138
	v_cmp_gt_u32_e64 s[72:73], s44, v139
	v_cmp_gt_u32_e64 s[74:75], s44, v140
	v_cmp_gt_u32_e64 s[76:77], s44, v141
	v_cndmask_b32_e64 v156, 0, v156, s[70:71]
	v_cndmask_b32_e64 v157, 0, v157, s[72:73]
	v_cndmask_b32_e64 v158, 0, v158, s[74:75]
	v_cndmask_b32_e64 v159, 0, v159, s[76:77]
	v_add_f32_e32 v133, v133, v156
	v_add_f32_e32 v133, v133, v157
	v_add_f32_e32 v133, v133, v158
	v_add_f32_e32 v133, v133, v159
	v_cvt_pk_bf16_f32 v196, v156, v157
	v_cvt_pk_bf16_f32 v197, v158, v159
	v_min_f32_e32 v152, 0x42a00000, v240
	v_min_f32_e32 v153, 0x42a00000, v241
	v_min_f32_e32 v154, 0x42a00000, v242
	v_min_f32_e32 v155, 0x42a00000, v243
	v_min_f32_e32 v156, 0x42a00000, v248
	v_min_f32_e32 v157, 0x42a00000, v249
	v_min_f32_e32 v158, 0x42a00000, v250
	v_min_f32_e32 v159, 0x42a00000, v251
	v_mfma_f32_16x16x32_bf16 v[248:251], v[88:91], v[56:59], 0
	v_mfma_f32_16x16x32_bf16 v[248:251], v[92:95], v[60:63], v[248:251]
	v_mul_f32_e32 v152, 0x3fb8aa3b, v152
	v_mul_f32_e32 v153, 0x3fb8aa3b, v153
	v_mul_f32_e32 v154, 0x3fb8aa3b, v154
	v_mul_f32_e32 v155, 0x3fb8aa3b, v155
	v_exp_f32_e32 v152, v152
	v_exp_f32_e32 v153, v153
	v_exp_f32_e32 v154, v154
	v_exp_f32_e32 v155, v155
	v_add_u32_e32 v138, 0x70, v175
	v_add_u32_e32 v139, 0x71, v175
	v_add_u32_e32 v140, 0x72, v175
	v_add_u32_e32 v141, 0x73, v175
	v_cmp_gt_u32_e64 s[70:71], s44, v138
	v_cmp_gt_u32_e64 s[72:73], s44, v139
	v_cmp_gt_u32_e64 s[74:75], s44, v140
	v_cmp_gt_u32_e64 s[76:77], s44, v141
	v_cndmask_b32_e64 v152, 0, v152, s[70:71]
	v_cndmask_b32_e64 v153, 0, v153, s[72:73]
	v_cndmask_b32_e64 v154, 0, v154, s[74:75]
	v_cndmask_b32_e64 v155, 0, v155, s[76:77]
	v_add_f32_e32 v132, v132, v152
	v_add_f32_e32 v132, v132, v153
	v_add_f32_e32 v132, v132, v154
	v_add_f32_e32 v132, v132, v155
	v_cvt_pk_bf16_f32 v126, v152, v153
	v_cvt_pk_bf16_f32 v127, v154, v155
	v_mul_f32_e32 v156, 0x3fb8aa3b, v156
	v_mul_f32_e32 v157, 0x3fb8aa3b, v157
	v_mul_f32_e32 v158, 0x3fb8aa3b, v158
	v_mul_f32_e32 v159, 0x3fb8aa3b, v159
	v_exp_f32_e32 v156, v156
	v_exp_f32_e32 v157, v157
	v_exp_f32_e32 v158, v158
	v_exp_f32_e32 v159, v159
	v_add_u32_e32 v138, 0x70, v175
	v_add_u32_e32 v139, 0x71, v175
	v_add_u32_e32 v140, 0x72, v175
	v_add_u32_e32 v141, 0x73, v175
	v_cmp_gt_u32_e64 s[70:71], s44, v138
	v_cmp_gt_u32_e64 s[72:73], s44, v139
	v_cmp_gt_u32_e64 s[74:75], s44, v140
	v_cmp_gt_u32_e64 s[76:77], s44, v141
	v_cndmask_b32_e64 v156, 0, v156, s[70:71]
	v_cndmask_b32_e64 v157, 0, v157, s[72:73]
	v_cndmask_b32_e64 v158, 0, v158, s[74:75]
	v_cndmask_b32_e64 v159, 0, v159, s[76:77]
	v_add_f32_e32 v133, v133, v156
	v_add_f32_e32 v133, v133, v157
	v_add_f32_e32 v133, v133, v158
	v_add_f32_e32 v133, v133, v159
	v_cvt_pk_bf16_f32 v198, v156, v157
	v_cvt_pk_bf16_f32 v199, v158, v159
	v_min_f32_e32 v152, 0x42a00000, v236
	v_min_f32_e32 v153, 0x42a00000, v237
	v_min_f32_e32 v154, 0x42a00000, v238
	v_min_f32_e32 v155, 0x42a00000, v239
	v_min_f32_e32 v156, 0x42a00000, v244
	v_min_f32_e32 v157, 0x42a00000, v245
	v_min_f32_e32 v158, 0x42a00000, v246
	v_min_f32_e32 v159, 0x42a00000, v247
	v_mul_f32_e32 v152, 0x3fb8aa3b, v152
	v_mul_f32_e32 v153, 0x3fb8aa3b, v153
	v_mul_f32_e32 v154, 0x3fb8aa3b, v154
	v_mul_f32_e32 v155, 0x3fb8aa3b, v155
	v_exp_f32_e32 v152, v152
	v_exp_f32_e32 v153, v153
	v_exp_f32_e32 v154, v154
	v_exp_f32_e32 v155, v155
	v_add_u32_e32 v138, 0x80, v175
	v_add_u32_e32 v139, 0x81, v175
	v_add_u32_e32 v140, 0x82, v175
	v_add_u32_e32 v141, 0x83, v175
	v_cmp_gt_u32_e64 s[70:71], s44, v138
	v_cmp_gt_u32_e64 s[72:73], s44, v139
	v_cmp_gt_u32_e64 s[74:75], s44, v140
	v_cmp_gt_u32_e64 s[76:77], s44, v141
	v_cndmask_b32_e64 v152, 0, v152, s[62:63]
	v_cndmask_b32_e64 v153, 0, v153, s[64:65]
	v_cndmask_b32_e64 v154, 0, v154, s[66:67]
	v_cndmask_b32_e64 v155, 0, v155, s[68:69]
	v_cndmask_b32_e64 v152, 0, v152, s[70:71]
	v_cndmask_b32_e64 v153, 0, v153, s[72:73]
	v_cndmask_b32_e64 v154, 0, v154, s[74:75]
	v_cndmask_b32_e64 v155, 0, v155, s[76:77]
	v_add_f32_e32 v132, v132, v152
	v_add_f32_e32 v132, v132, v153
	v_add_f32_e32 v132, v132, v154
	v_add_f32_e32 v132, v132, v155
	v_cvt_pk_bf16_f32 v128, v152, v153
	v_cvt_pk_bf16_f32 v129, v154, v155
	v_mul_f32_e32 v156, 0x3fb8aa3b, v156
	v_mul_f32_e32 v157, 0x3fb8aa3b, v157
	v_mul_f32_e32 v158, 0x3fb8aa3b, v158
	v_mul_f32_e32 v159, 0x3fb8aa3b, v159
	v_exp_f32_e32 v156, v156
	v_exp_f32_e32 v157, v157
	v_exp_f32_e32 v158, v158
	v_exp_f32_e32 v159, v159
	v_add_u32_e32 v138, 0x80, v175
	v_add_u32_e32 v139, 0x81, v175
	v_add_u32_e32 v140, 0x82, v175
	v_add_u32_e32 v141, 0x83, v175
	v_cmp_gt_u32_e64 s[70:71], s44, v138
	v_cmp_gt_u32_e64 s[72:73], s44, v139
	v_cmp_gt_u32_e64 s[74:75], s44, v140
	v_cmp_gt_u32_e64 s[76:77], s44, v141
	v_cndmask_b32_e64 v156, 0, v156, s[70:71]
	v_cndmask_b32_e64 v157, 0, v157, s[72:73]
	v_cndmask_b32_e64 v158, 0, v158, s[74:75]
	v_cndmask_b32_e64 v159, 0, v159, s[76:77]
	v_add_f32_e32 v133, v133, v156
	v_add_f32_e32 v133, v133, v157
	v_add_f32_e32 v133, v133, v158
	v_add_f32_e32 v133, v133, v159
	v_cvt_pk_bf16_f32 v200, v156, v157
	v_cvt_pk_bf16_f32 v201, v158, v159
	v_min_f32_e32 v156, 0x42a00000, v248
	v_min_f32_e32 v157, 0x42a00000, v249
	v_min_f32_e32 v158, 0x42a00000, v250
	v_min_f32_e32 v159, 0x42a00000, v251
	v_mul_f32_e32 v156, 0x3fb8aa3b, v156
	v_mul_f32_e32 v157, 0x3fb8aa3b, v157
	v_mul_f32_e32 v158, 0x3fb8aa3b, v158
	v_mul_f32_e32 v159, 0x3fb8aa3b, v159
	v_exp_f32_e32 v156, v156
	v_exp_f32_e32 v157, v157
	v_exp_f32_e32 v158, v158
	v_exp_f32_e32 v159, v159
	v_add_u32_e32 v138, 0x90, v175
	v_add_u32_e32 v139, 0x91, v175
	v_add_u32_e32 v140, 0x92, v175
	v_add_u32_e32 v141, 0x93, v175
	v_cmp_gt_u32_e64 s[70:71], s44, v138
	v_cmp_gt_u32_e64 s[72:73], s44, v139
	v_cmp_gt_u32_e64 s[74:75], s44, v140
	v_cmp_gt_u32_e64 s[76:77], s44, v141
	v_cndmask_b32_e64 v156, 0, v156, s[62:63]
	v_cndmask_b32_e64 v157, 0, v157, s[64:65]
	v_cndmask_b32_e64 v158, 0, v158, s[66:67]
	v_cndmask_b32_e64 v159, 0, v159, s[68:69]
	v_cndmask_b32_e64 v156, 0, v156, s[70:71]
	v_cndmask_b32_e64 v157, 0, v157, s[72:73]
	v_cndmask_b32_e64 v158, 0, v158, s[74:75]
	v_cndmask_b32_e64 v159, 0, v159, s[76:77]
	v_add_f32_e32 v133, v133, v156
	v_add_f32_e32 v133, v133, v157
	v_add_f32_e32 v133, v133, v158
	v_add_f32_e32 v133, v133, v159
	v_cvt_pk_bf16_f32 v202, v156, v157
	v_cvt_pk_bf16_f32 v203, v158, v159
	v_add_u32_e32 v134, s42, v160
	v_lshlrev_b32_e32 v134, 2, v134
	v_add_u32_e32 v134, s43, v134
	v_subrev_u32_e32 v135, s15, v134
	v_lshrrev_b32_e32 v136, 4, v135
	v_add_u32_e32 v136, v136, v135
	v_mad_u32_u24 v176, v136, s79, v161
	v_lshl_add_u32 v177, v135, 2, s80
	s_sub_i32 s2, s42, 64
	v_add_u32_e32 v178, s2, v169
	v_and_b32_e32 v135, 3, v134
	v_lshlrev_b32_e32 v135, s13, v135
	v_lshrrev_b32_e32 v136, 2, v134
	v_add_u32_e32 v135, v135, v136
	v_lshl_add_u32 v135, v135, 7, v161
	global_load_dwordx4 v[48:51], v135, s[18:19]
	global_load_dwordx4 v[52:55], v135, s[18:19] offset:64
	v_add_u32_e32 v137, 64, v134
	v_and_b32_e32 v135, 3, v137
	v_lshlrev_b32_e32 v135, s13, v135
	v_lshrrev_b32_e32 v136, 2, v137
	v_add_u32_e32 v135, v135, v136
	v_lshl_add_u32 v135, v135, 7, v161
	global_load_dwordx4 v[56:59], v135, s[18:19]
	global_load_dwordx4 v[60:63], v135, s[18:19] offset:64
	v_subrev_u32_e32 v134, 0x100, v134
	v_and_b32_e32 v137, 3, v134
	v_lshlrev_b32_e32 v137, s13, v137
	v_bfe_u32 v135, v134, 2, 2
	v_add_u32_e32 v137, v137, v135
	v_lshl_add_u32 v183, v137, 7, v161
	v_ashrrev_i32_e32 v252, 4, v134
	v_med3_i32 v136, v252, 0, s14
	v_lshl_add_u32 v136, v136, 9, v183
	global_load_dwordx4 v[0:3], v136, s[20:21]
	global_load_dwordx4 v[4:7], v136, s[20:21] offset:64
	v_add_u32_e32 v135, 4, v252
	v_med3_i32 v135, v135, 0, s14
	v_lshl_add_u32 v135, v135, 9, v183
	global_load_dwordx4 v[8:11], v135, s[20:21]
	global_load_dwordx4 v[12:15], v135, s[20:21] offset:64
	v_add_u32_e32 v136, 8, v252
	v_med3_i32 v136, v136, 0, s14
	v_lshl_add_u32 v136, v136, 9, v183
	global_load_dwordx4 v[16:19], v136, s[20:21]
	global_load_dwordx4 v[20:23], v136, s[20:21] offset:64
	v_add_u32_e32 v135, 12, v252
	v_med3_i32 v135, v135, 0, s14
	v_lshl_add_u32 v135, v135, 9, v183
	global_load_dwordx4 v[24:27], v135, s[20:21]
	global_load_dwordx4 v[28:31], v135, s[20:21] offset:64
	v_add_u32_e32 v136, 16, v252
	v_med3_i32 v136, v136, 0, s14
	v_lshl_add_u32 v136, v136, 9, v183
	global_load_dwordx4 v[32:35], v136, s[20:21]
	global_load_dwordx4 v[36:39], v136, s[20:21] offset:64
	v_add_u32_e32 v135, 20, v252
	v_med3_i32 v135, v135, 0, s14
	v_lshl_add_u32 v135, v135, 9, v183
	global_load_dwordx4 v[40:43], v135, s[20:21]
	global_load_dwordx4 v[44:47], v135, s[20:21] offset:64
	s_add_i32 s2, s42, -64
	v_add_u32_e32 v138, s2, v164
	v_lshlrev_b32_e32 v138, 2, v138
	v_add_u32_e32 v138, s43, v138
	v_and_b32_e32 v139, 3, v138
	v_lshlrev_b32_e32 v139, s13, v139
	v_bfe_u32 v140, v138, 2, 2
	v_add_u32_e32 v139, v139, v140
	v_lshl_add_u32 v139, v139, 7, v162
	v_ashrrev_i32_e32 v138, 4, v138
	v_med3_i32 v138, v138, 0, s14
	v_lshl_add_u32 v138, v138, 9, v139
	global_load_dwordx4 v[64:67], v138, s[22:23]
	s_add_i32 s2, s42, -56
	v_add_u32_e32 v138, s2, v164
	v_lshlrev_b32_e32 v138, 2, v138
	v_add_u32_e32 v138, s43, v138
	v_and_b32_e32 v139, 3, v138
	v_lshlrev_b32_e32 v139, s13, v139
	v_bfe_u32 v140, v138, 2, 2
	v_add_u32_e32 v139, v139, v140
	v_lshl_add_u32 v139, v139, 7, v162
	v_ashrrev_i32_e32 v138, 4, v138
	v_med3_i32 v138, v138, 0, s14
	v_lshl_add_u32 v138, v138, 9, v139
	global_load_dwordx4 v[68:71], v138, s[22:23]
	s_add_i32 s2, s42, -48
	v_add_u32_e32 v138, s2, v164
	v_lshlrev_b32_e32 v138, 2, v138
	v_add_u32_e32 v138, s43, v138
	v_and_b32_e32 v139, 3, v138
	v_lshlrev_b32_e32 v139, s13, v139
	v_bfe_u32 v140, v138, 2, 2
	v_add_u32_e32 v139, v139, v140
	v_lshl_add_u32 v139, v139, 7, v162
	v_ashrrev_i32_e32 v138, 4, v138
	v_med3_i32 v138, v138, 0, s14
	v_lshl_add_u32 v138, v138, 9, v139
	global_load_dwordx4 v[72:75], v138, s[22:23]
	s_add_i32 s2, s42, -40
	v_add_u32_e32 v138, s2, v164
	v_lshlrev_b32_e32 v138, 2, v138
	v_add_u32_e32 v138, s43, v138
	v_and_b32_e32 v139, 3, v138
	v_lshlrev_b32_e32 v139, s13, v139
	v_bfe_u32 v140, v138, 2, 2
	v_add_u32_e32 v139, v139, v140
	v_lshl_add_u32 v139, v139, 7, v162
	v_ashrrev_i32_e32 v138, 4, v138
	v_med3_i32 v138, v138, 0, s14
	v_lshl_add_u32 v138, v138, 9, v139
	global_load_dwordx4 v[76:79], v138, s[22:23]
	s_add_i32 s2, s42, -32
	v_add_u32_e32 v138, s2, v164
	v_lshlrev_b32_e32 v138, 2, v138
	v_add_u32_e32 v138, s43, v138
	v_and_b32_e32 v139, 3, v138
	v_lshlrev_b32_e32 v139, s13, v139
	v_bfe_u32 v140, v138, 2, 2
	v_add_u32_e32 v139, v139, v140
	v_lshl_add_u32 v139, v139, 7, v162
	v_ashrrev_i32_e32 v138, 4, v138
	v_med3_i32 v138, v138, 0, s14
	v_lshl_add_u32 v138, v138, 9, v139
	global_load_dwordx4 v[80:83], v138, s[22:23]
	s_add_i32 s2, s42, -24
	v_add_u32_e32 v138, s2, v164
	v_lshlrev_b32_e32 v138, 2, v138
	v_add_u32_e32 v138, s43, v138
	v_and_b32_e32 v139, 3, v138
	v_lshlrev_b32_e32 v139, s13, v139
	v_bfe_u32 v140, v138, 2, 2
	v_add_u32_e32 v139, v139, v140
	v_lshl_add_u32 v139, v139, 7, v162
	v_ashrrev_i32_e32 v138, 4, v138
	v_med3_i32 v138, v138, 0, s14
	v_lshl_add_u32 v138, v138, 9, v139
	global_load_dwordx4 v[84:87], v138, s[22:23]
	s_add_i32 s2, s42, -16
	v_add_u32_e32 v138, s2, v164
	v_lshlrev_b32_e32 v138, 2, v138
	v_add_u32_e32 v138, s43, v138
	v_and_b32_e32 v139, 3, v138
	v_lshlrev_b32_e32 v139, s13, v139
	v_bfe_u32 v140, v138, 2, 2
	v_add_u32_e32 v139, v139, v140
	v_lshl_add_u32 v139, v139, 7, v162
	v_ashrrev_i32_e32 v138, 4, v138
	v_med3_i32 v138, v138, 0, s14
	v_lshl_add_u32 v138, v138, 9, v139
	global_load_dwordx4 v[88:91], v138, s[22:23]
	s_add_i32 s2, s42, -8
	v_add_u32_e32 v138, s2, v164
	v_lshlrev_b32_e32 v138, 2, v138
	v_add_u32_e32 v138, s43, v138
	v_and_b32_e32 v139, 3, v138
	v_lshlrev_b32_e32 v139, s13, v139
	v_bfe_u32 v140, v138, 2, 2
	v_add_u32_e32 v139, v139, v140
	v_lshl_add_u32 v139, v139, 7, v162
	v_ashrrev_i32_e32 v138, 4, v138
	v_med3_i32 v138, v138, 0, s14
	v_lshl_add_u32 v138, v138, 9, v139
	global_load_dwordx4 v[92:95], v138, s[22:23]
	s_add_i32 s2, s42, 0
	v_add_u32_e32 v138, s2, v164
	v_lshlrev_b32_e32 v138, 2, v138
	v_add_u32_e32 v138, s43, v138
	v_and_b32_e32 v139, 3, v138
	v_lshlrev_b32_e32 v139, s13, v139
	v_bfe_u32 v140, v138, 2, 2
	v_add_u32_e32 v139, v139, v140
	v_lshl_add_u32 v139, v139, 7, v162
	v_ashrrev_i32_e32 v138, 4, v138
	v_med3_i32 v138, v138, 0, s14
	v_lshl_add_u32 v138, v138, 9, v139
	global_load_dwordx4 v[96:99], v138, s[22:23]
	s_add_i32 s2, s42, 8
	v_add_u32_e32 v138, s2, v164
	v_lshlrev_b32_e32 v138, 2, v138
	v_add_u32_e32 v138, s43, v138
	v_and_b32_e32 v139, 3, v138
	v_lshlrev_b32_e32 v139, s13, v139
	v_bfe_u32 v140, v138, 2, 2
	v_add_u32_e32 v139, v139, v140
	v_lshl_add_u32 v139, v139, 7, v162
	v_ashrrev_i32_e32 v138, 4, v138
	v_med3_i32 v138, v138, 0, s14
	v_lshl_add_u32 v138, v138, 9, v139
	global_load_dwordx4 v[100:103], v138, s[22:23]
	s_add_i32 s2, s42, 16
	v_add_u32_e32 v138, s2, v164
	v_lshlrev_b32_e32 v138, 2, v138
	v_add_u32_e32 v138, s43, v138
	v_and_b32_e32 v139, 3, v138
	v_lshlrev_b32_e32 v139, s13, v139
	v_bfe_u32 v140, v138, 2, 2
	v_add_u32_e32 v139, v139, v140
	v_lshl_add_u32 v139, v139, 7, v162
	v_ashrrev_i32_e32 v138, 4, v138
	v_med3_i32 v138, v138, 0, s14
	v_lshl_add_u32 v138, v138, 9, v139
	global_load_dwordx4 v[104:107], v138, s[22:23]
	s_add_i32 s2, s42, 24
	v_add_u32_e32 v138, s2, v164
	v_lshlrev_b32_e32 v138, 2, v138
	v_add_u32_e32 v138, s43, v138
	v_and_b32_e32 v139, 3, v138
	v_lshlrev_b32_e32 v139, s13, v139
	v_bfe_u32 v140, v138, 2, 2
	v_add_u32_e32 v139, v139, v140
	v_lshl_add_u32 v139, v139, 7, v162
	v_ashrrev_i32_e32 v138, 4, v138
	v_med3_i32 v138, v138, 0, s14
	v_lshl_add_u32 v138, v138, 9, v139
	global_load_dwordx4 v[108:111], v138, s[22:23]
	ds_bpermute_b32 v142, v167, v132
	s_waitcnt lgkmcnt(0)
	v_add_f32_e32 v132, v132, v142
	ds_bpermute_b32 v142, v168, v132
	s_waitcnt lgkmcnt(0)
	v_add_f32_e32 v132, v132, v142
	ds_bpermute_b32 v142, v167, v133
	s_waitcnt lgkmcnt(0)
	v_add_f32_e32 v133, v133, v142
	ds_bpermute_b32 v142, v168, v133
	s_waitcnt lgkmcnt(0)
	v_add_f32_e32 v133, v133, v142
	ds_read_b64_tr_b16 v[236:237], v151 offset:0
	ds_read_b64_tr_b16 v[238:239], v151 offset:2304
	ds_read_b64_tr_b16 v[240:241], v151 offset:32
	ds_read_b64_tr_b16 v[242:243], v151 offset:2336
	ds_read_b64_tr_b16 v[244:245], v151 offset:64
	ds_read_b64_tr_b16 v[246:247], v151 offset:2368
	ds_read_b64_tr_b16 v[248:249], v151 offset:96
	ds_read_b64_tr_b16 v[250:251], v151 offset:2400
	s_waitcnt lgkmcnt(0)
	v_mfma_f32_16x16x32_bf16 v[204:207], v[236:239], v[112:115], 0
	v_mfma_f32_16x16x32_bf16 v[208:211], v[240:243], v[112:115], 0
	v_mfma_f32_16x16x32_bf16 v[212:215], v[244:247], v[112:115], 0
	v_mfma_f32_16x16x32_bf16 v[216:219], v[248:251], v[112:115], 0
	v_mfma_f32_16x16x32_bf16 v[220:223], v[236:239], v[184:187], 0
	v_mfma_f32_16x16x32_bf16 v[224:227], v[240:243], v[184:187], 0
	v_mfma_f32_16x16x32_bf16 v[228:231], v[244:247], v[184:187], 0
	v_mfma_f32_16x16x32_bf16 v[232:235], v[248:251], v[184:187], 0
	s_nop 7
	ds_read_b64_tr_b16 v[236:237], v151 offset:4608
	ds_read_b64_tr_b16 v[238:239], v151 offset:6912
	ds_read_b64_tr_b16 v[240:241], v151 offset:4640
	ds_read_b64_tr_b16 v[242:243], v151 offset:6944
	ds_read_b64_tr_b16 v[244:245], v151 offset:4672
	ds_read_b64_tr_b16 v[246:247], v151 offset:6976
	ds_read_b64_tr_b16 v[248:249], v151 offset:4704
	ds_read_b64_tr_b16 v[250:251], v151 offset:7008
	s_waitcnt lgkmcnt(0)
	v_mfma_f32_16x16x32_bf16 v[204:207], v[236:239], v[116:119], v[204:207]
	v_mfma_f32_16x16x32_bf16 v[208:211], v[240:243], v[116:119], v[208:211]
	v_mfma_f32_16x16x32_bf16 v[212:215], v[244:247], v[116:119], v[212:215]
	v_mfma_f32_16x16x32_bf16 v[216:219], v[248:251], v[116:119], v[216:219]
	v_mfma_f32_16x16x32_bf16 v[220:223], v[236:239], v[188:191], v[220:223]
	v_mfma_f32_16x16x32_bf16 v[224:227], v[240:243], v[188:191], v[224:227]
	v_mfma_f32_16x16x32_bf16 v[228:231], v[244:247], v[188:191], v[228:231]
	v_mfma_f32_16x16x32_bf16 v[232:235], v[248:251], v[188:191], v[232:235]
	s_nop 7
	ds_read_b64_tr_b16 v[236:237], v151 offset:9216
	ds_read_b64_tr_b16 v[238:239], v151 offset:11520
	ds_read_b64_tr_b16 v[240:241], v151 offset:9248
	ds_read_b64_tr_b16 v[242:243], v151 offset:11552
	ds_read_b64_tr_b16 v[244:245], v151 offset:9280
	ds_read_b64_tr_b16 v[246:247], v151 offset:11584
	ds_read_b64_tr_b16 v[248:249], v151 offset:9312
	ds_read_b64_tr_b16 v[250:251], v151 offset:11616
	s_waitcnt lgkmcnt(0)
	v_mfma_f32_16x16x32_bf16 v[204:207], v[236:239], v[120:123], v[204:207]
	v_mfma_f32_16x16x32_bf16 v[208:211], v[240:243], v[120:123], v[208:211]
	v_mfma_f32_16x16x32_bf16 v[212:215], v[244:247], v[120:123], v[212:215]
	v_mfma_f32_16x16x32_bf16 v[216:219], v[248:251], v[120:123], v[216:219]
	v_mfma_f32_16x16x32_bf16 v[220:223], v[236:239], v[192:195], v[220:223]
	v_mfma_f32_16x16x32_bf16 v[224:227], v[240:243], v[192:195], v[224:227]
	v_mfma_f32_16x16x32_bf16 v[228:231], v[244:247], v[192:195], v[228:231]
	v_mfma_f32_16x16x32_bf16 v[232:235], v[248:251], v[192:195], v[232:235]
	s_nop 7
	ds_read_b64_tr_b16 v[236:237], v151 offset:13824
	ds_read_b64_tr_b16 v[238:239], v151 offset:16128
	ds_read_b64_tr_b16 v[240:241], v151 offset:13856
	ds_read_b64_tr_b16 v[242:243], v151 offset:16160
	ds_read_b64_tr_b16 v[244:245], v151 offset:13888
	ds_read_b64_tr_b16 v[246:247], v151 offset:16192
	ds_read_b64_tr_b16 v[248:249], v151 offset:13920
	ds_read_b64_tr_b16 v[250:251], v151 offset:16224
	s_waitcnt lgkmcnt(0)
	v_mfma_f32_16x16x32_bf16 v[204:207], v[236:239], v[124:127], v[204:207]
	v_mfma_f32_16x16x32_bf16 v[208:211], v[240:243], v[124:127], v[208:211]
	v_mfma_f32_16x16x32_bf16 v[212:215], v[244:247], v[124:127], v[212:215]
	v_mfma_f32_16x16x32_bf16 v[216:219], v[248:251], v[124:127], v[216:219]
	v_mfma_f32_16x16x32_bf16 v[220:223], v[236:239], v[196:199], v[220:223]
	v_mfma_f32_16x16x32_bf16 v[224:227], v[240:243], v[196:199], v[224:227]
	v_mfma_f32_16x16x32_bf16 v[228:231], v[244:247], v[196:199], v[228:231]
	v_mfma_f32_16x16x32_bf16 v[232:235], v[248:251], v[196:199], v[232:235]
	s_nop 7
	ds_read_b64_tr_b16 v[236:237], v151 offset:18432
	ds_read_b64_tr_b16 v[238:239], v151 offset:20736
	ds_read_b64_tr_b16 v[240:241], v151 offset:18464
	ds_read_b64_tr_b16 v[242:243], v151 offset:20768
	ds_read_b64_tr_b16 v[244:245], v151 offset:18496
	ds_read_b64_tr_b16 v[246:247], v151 offset:20800
	ds_read_b64_tr_b16 v[248:249], v151 offset:18528
	ds_read_b64_tr_b16 v[250:251], v151 offset:20832
	s_waitcnt lgkmcnt(0)
	v_mfma_f32_16x16x32_bf16 v[204:207], v[236:239], v[128:131], v[204:207]
	v_mfma_f32_16x16x32_bf16 v[208:211], v[240:243], v[128:131], v[208:211]
	v_mfma_f32_16x16x32_bf16 v[212:215], v[244:247], v[128:131], v[212:215]
	v_mfma_f32_16x16x32_bf16 v[216:219], v[248:251], v[128:131], v[216:219]
	v_mfma_f32_16x16x32_bf16 v[220:223], v[236:239], v[200:203], v[220:223]
	v_mfma_f32_16x16x32_bf16 v[224:227], v[240:243], v[200:203], v[224:227]
	v_mfma_f32_16x16x32_bf16 v[228:231], v[244:247], v[200:203], v[228:231]
	v_mfma_f32_16x16x32_bf16 v[232:235], v[248:251], v[200:203], v[232:235]
	s_barrier
	ds_write_b128 v173, v[204:207] offset:0
	ds_write_b128 v173, v[208:211] offset:64
	ds_write_b128 v173, v[212:215] offset:128
	ds_write_b128 v173, v[216:219] offset:192
	ds_write_b32 v174, v132 offset:0
	ds_write_b128 v173, v[220:223] offset:4624
	ds_write_b128 v173, v[224:227] offset:4688
	ds_write_b128 v173, v[228:231] offset:4752
	ds_write_b128 v173, v[232:235] offset:4816
	ds_write_b32 v174, v133 offset:64
	s_waitcnt lgkmcnt(0)
	s_barrier
	s_mov_b32 s40, s42
	s_mov_b32 s41, s43
	v_mov_b32_e32 v173, v176
	v_mov_b32_e32 v174, v177
	v_mov_b32_e32 v175, v178
	v_mov_b32_e32 v179, v183
	v_mov_b32_e32 v182, v252
	s_lshr_b32 s44, s33, 2
	s_lshr_b32 s42, s15, 4
	s_add_i32 s43, s0, 0
	s_waitcnt vmcnt(12)
	v_mov_b32_e32 v132, 0
	v_mov_b32_e32 v133, 0
	v_mfma_f32_16x16x32_bf16 v[236:239], v[0:3], v[48:51], 0
	v_mfma_f32_16x16x32_bf16 v[236:239], v[4:7], v[52:55], v[236:239]
	v_mfma_f32_16x16x32_bf16 v[240:243], v[8:11], v[48:51], 0
	v_mfma_f32_16x16x32_bf16 v[240:243], v[12:15], v[52:55], v[240:243]
	v_mfma_f32_16x16x32_bf16 v[248:251], v[8:11], v[56:59], 0
	v_mfma_f32_16x16x32_bf16 v[248:251], v[12:15], v[60:63], v[248:251]
	s_nop 7
	v_min_f32_e32 v152, 0x42a00000, v236
	v_min_f32_e32 v153, 0x42a00000, v237
	v_min_f32_e32 v154, 0x42a00000, v238
	v_min_f32_e32 v155, 0x42a00000, v239
	v_mfma_f32_16x16x32_bf16 v[236:239], v[16:19], v[48:51], 0
	v_mfma_f32_16x16x32_bf16 v[236:239], v[20:23], v[52:55], v[236:239]
	v_mfma_f32_16x16x32_bf16 v[244:247], v[16:19], v[56:59], 0
	v_mfma_f32_16x16x32_bf16 v[244:247], v[20:23], v[60:63], v[244:247]
	v_add_u32_e32 v136, 24, v182
	v_med3_i32 v136, v136, 0, s38
	v_lshl_add_u32 v136, v136, 9, v179
	global_load_dwordx4 v[0:3], v136, s[24:25]
	global_load_dwordx4 v[4:7], v136, s[24:25] offset:64
	v_mul_f32_e32 v152, 0x3fb8aa3b, v152
	v_mul_f32_e32 v153, 0x3fb8aa3b, v153
	v_mul_f32_e32 v154, 0x3fb8aa3b, v154
	v_mul_f32_e32 v155, 0x3fb8aa3b, v155
	v_exp_f32_e32 v152, v152
	v_exp_f32_e32 v153, v153
	v_exp_f32_e32 v154, v154
	v_exp_f32_e32 v155, v155
	v_add_u32_e32 v138, 0, v175
	v_add_u32_e32 v139, 1, v175
	v_add_u32_e32 v140, 2, v175
	v_add_u32_e32 v141, 3, v175
	v_cmp_gt_u32_e64 s[70:71], s44, v138
	v_cmp_gt_u32_e64 s[72:73], s44, v139
	v_cmp_gt_u32_e64 s[74:75], s44, v140
	v_cmp_gt_u32_e64 s[76:77], s44, v141
	v_cndmask_b32_e64 v152, 0, v152, s[54:55]
	v_cndmask_b32_e64 v153, 0, v153, s[56:57]
	v_cndmask_b32_e64 v154, 0, v154, s[58:59]
	v_cndmask_b32_e64 v155, 0, v155, s[60:61]
	v_cndmask_b32_e64 v152, 0, v152, s[70:71]
	v_cndmask_b32_e64 v153, 0, v153, s[72:73]
	v_cndmask_b32_e64 v154, 0, v154, s[74:75]
	v_cndmask_b32_e64 v155, 0, v155, s[76:77]
	v_add_f32_e32 v132, v132, v152
	v_add_f32_e32 v132, v132, v153
	v_add_f32_e32 v132, v132, v154
	v_add_f32_e32 v132, v132, v155
	v_cvt_pk_bf16_f32 v112, v152, v153
	v_cvt_pk_bf16_f32 v113, v154, v155
	v_min_f32_e32 v152, 0x42a00000, v240
	v_min_f32_e32 v153, 0x42a00000, v241
	v_min_f32_e32 v154, 0x42a00000, v242
	v_min_f32_e32 v155, 0x42a00000, v243
	v_min_f32_e32 v156, 0x42a00000, v248
	v_min_f32_e32 v157, 0x42a00000, v249
	v_min_f32_e32 v158, 0x42a00000, v250
	v_min_f32_e32 v159, 0x42a00000, v251
	v_mfma_f32_16x16x32_bf16 v[240:243], v[24:27], v[48:51], 0
	v_mfma_f32_16x16x32_bf16 v[240:243], v[28:31], v[52:55], v[240:243]
	v_mfma_f32_16x16x32_bf16 v[248:251], v[24:27], v[56:59], 0
	v_mfma_f32_16x16x32_bf16 v[248:251], v[28:31], v[60:63], v[248:251]
	v_add_u32_e32 v135, 28, v182
	v_med3_i32 v135, v135, 0, s38
	v_lshl_add_u32 v135, v135, 9, v179
	global_load_dwordx4 v[8:11], v135, s[24:25]
	global_load_dwordx4 v[12:15], v135, s[24:25] offset:64
	v_mul_f32_e32 v152, 0x3fb8aa3b, v152
	v_mul_f32_e32 v153, 0x3fb8aa3b, v153
	v_mul_f32_e32 v154, 0x3fb8aa3b, v154
	v_mul_f32_e32 v155, 0x3fb8aa3b, v155
	v_exp_f32_e32 v152, v152
	v_exp_f32_e32 v153, v153
	v_exp_f32_e32 v154, v154
	v_exp_f32_e32 v155, v155
	v_add_u32_e32 v138, 16, v175
	v_add_u32_e32 v139, 17, v175
	v_add_u32_e32 v140, 18, v175
	v_add_u32_e32 v141, 19, v175
	v_cmp_gt_u32_e64 s[70:71], s44, v138
	v_cmp_gt_u32_e64 s[72:73], s44, v139
	v_cmp_gt_u32_e64 s[74:75], s44, v140
	v_cmp_gt_u32_e64 s[76:77], s44, v141
	v_cndmask_b32_e64 v152, 0, v152, s[70:71]
	v_cndmask_b32_e64 v153, 0, v153, s[72:73]
	v_cndmask_b32_e64 v154, 0, v154, s[74:75]
	v_cndmask_b32_e64 v155, 0, v155, s[76:77]
	v_add_f32_e32 v132, v132, v152
	v_add_f32_e32 v132, v132, v153
	v_add_f32_e32 v132, v132, v154
	v_add_f32_e32 v132, v132, v155
	v_cvt_pk_bf16_f32 v114, v152, v153
	v_cvt_pk_bf16_f32 v115, v154, v155
	v_mul_f32_e32 v156, 0x3fb8aa3b, v156
	v_mul_f32_e32 v157, 0x3fb8aa3b, v157
	v_mul_f32_e32 v158, 0x3fb8aa3b, v158
	v_mul_f32_e32 v159, 0x3fb8aa3b, v159
	v_exp_f32_e32 v156, v156
	v_exp_f32_e32 v157, v157
	v_exp_f32_e32 v158, v158
	v_exp_f32_e32 v159, v159
	v_add_u32_e32 v138, 16, v175
	v_add_u32_e32 v139, 17, v175
	v_add_u32_e32 v140, 18, v175
	v_add_u32_e32 v141, 19, v175
	v_cmp_gt_u32_e64 s[70:71], s44, v138
	v_cmp_gt_u32_e64 s[72:73], s44, v139
	v_cmp_gt_u32_e64 s[74:75], s44, v140
	v_cmp_gt_u32_e64 s[76:77], s44, v141
	v_cndmask_b32_e64 v156, 0, v156, s[54:55]
	v_cndmask_b32_e64 v157, 0, v157, s[56:57]
	v_cndmask_b32_e64 v158, 0, v158, s[58:59]
	v_cndmask_b32_e64 v159, 0, v159, s[60:61]
	v_cndmask_b32_e64 v156, 0, v156, s[70:71]
	v_cndmask_b32_e64 v157, 0, v157, s[72:73]
	v_cndmask_b32_e64 v158, 0, v158, s[74:75]
	v_cndmask_b32_e64 v159, 0, v159, s[76:77]
	v_add_f32_e32 v133, v133, v156
	v_add_f32_e32 v133, v133, v157
	v_add_f32_e32 v133, v133, v158
	v_add_f32_e32 v133, v133, v159
	v_cvt_pk_bf16_f32 v186, v156, v157
	v_cvt_pk_bf16_f32 v187, v158, v159
	v_min_f32_e32 v152, 0x42a00000, v236
	v_min_f32_e32 v153, 0x42a00000, v237
	v_min_f32_e32 v154, 0x42a00000, v238
	v_min_f32_e32 v155, 0x42a00000, v239
	v_min_f32_e32 v156, 0x42a00000, v244
	v_min_f32_e32 v157, 0x42a00000, v245
	v_min_f32_e32 v158, 0x42a00000, v246
	v_min_f32_e32 v159, 0x42a00000, v247
	v_mfma_f32_16x16x32_bf16 v[236:239], v[32:35], v[48:51], 0
	v_mfma_f32_16x16x32_bf16 v[236:239], v[36:39], v[52:55], v[236:239]
	v_mfma_f32_16x16x32_bf16 v[244:247], v[32:35], v[56:59], 0
	v_mfma_f32_16x16x32_bf16 v[244:247], v[36:39], v[60:63], v[244:247]
	v_add_u32_e32 v136, 32, v182
	v_med3_i32 v136, v136, 0, s38
	v_lshl_add_u32 v136, v136, 9, v179
	global_load_dwordx4 v[16:19], v136, s[24:25]
	global_load_dwordx4 v[20:23], v136, s[24:25] offset:64
	v_mul_f32_e32 v152, 0x3fb8aa3b, v152
	v_mul_f32_e32 v153, 0x3fb8aa3b, v153
	v_mul_f32_e32 v154, 0x3fb8aa3b, v154
	v_mul_f32_e32 v155, 0x3fb8aa3b, v155
	v_exp_f32_e32 v152, v152
	v_exp_f32_e32 v153, v153
	v_exp_f32_e32 v154, v154
	v_exp_f32_e32 v155, v155
	v_add_u32_e32 v138, 32, v175
	v_add_u32_e32 v139, 33, v175
	v_add_u32_e32 v140, 34, v175
	v_add_u32_e32 v141, 35, v175
	v_cmp_gt_u32_e64 s[70:71], s44, v138
	v_cmp_gt_u32_e64 s[72:73], s44, v139
	v_cmp_gt_u32_e64 s[74:75], s44, v140
	v_cmp_gt_u32_e64 s[76:77], s44, v141
	v_cndmask_b32_e64 v152, 0, v152, s[70:71]
	v_cndmask_b32_e64 v153, 0, v153, s[72:73]
	v_cndmask_b32_e64 v154, 0, v154, s[74:75]
	v_cndmask_b32_e64 v155, 0, v155, s[76:77]
	v_add_f32_e32 v132, v132, v152
	v_add_f32_e32 v132, v132, v153
	v_add_f32_e32 v132, v132, v154
	v_add_f32_e32 v132, v132, v155
	v_cvt_pk_bf16_f32 v116, v152, v153
	v_cvt_pk_bf16_f32 v117, v154, v155
	v_mul_f32_e32 v156, 0x3fb8aa3b, v156
	v_mul_f32_e32 v157, 0x3fb8aa3b, v157
	v_mul_f32_e32 v158, 0x3fb8aa3b, v158
	v_mul_f32_e32 v159, 0x3fb8aa3b, v159
	v_exp_f32_e32 v156, v156
	v_exp_f32_e32 v157, v157
	v_exp_f32_e32 v158, v158
	v_exp_f32_e32 v159, v159
	v_add_u32_e32 v138, 32, v175
	v_add_u32_e32 v139, 33, v175
	v_add_u32_e32 v140, 34, v175
	v_add_u32_e32 v141, 35, v175
	v_cmp_gt_u32_e64 s[70:71], s44, v138
	v_cmp_gt_u32_e64 s[72:73], s44, v139
	v_cmp_gt_u32_e64 s[74:75], s44, v140
	v_cmp_gt_u32_e64 s[76:77], s44, v141
	v_cndmask_b32_e64 v156, 0, v156, s[70:71]
	v_cndmask_b32_e64 v157, 0, v157, s[72:73]
	v_cndmask_b32_e64 v158, 0, v158, s[74:75]
	v_cndmask_b32_e64 v159, 0, v159, s[76:77]
	v_add_f32_e32 v133, v133, v156
	v_add_f32_e32 v133, v133, v157
	v_add_f32_e32 v133, v133, v158
	v_add_f32_e32 v133, v133, v159
	v_cvt_pk_bf16_f32 v188, v156, v157
	v_cvt_pk_bf16_f32 v189, v158, v159
	v_min_f32_e32 v152, 0x42a00000, v240
	v_min_f32_e32 v153, 0x42a00000, v241
	v_min_f32_e32 v154, 0x42a00000, v242
	v_min_f32_e32 v155, 0x42a00000, v243
	v_min_f32_e32 v156, 0x42a00000, v248
	v_min_f32_e32 v157, 0x42a00000, v249
	v_min_f32_e32 v158, 0x42a00000, v250
	v_min_f32_e32 v159, 0x42a00000, v251
	v_mfma_f32_16x16x32_bf16 v[240:243], v[40:43], v[48:51], 0
	v_mfma_f32_16x16x32_bf16 v[240:243], v[44:47], v[52:55], v[240:243]
	v_mfma_f32_16x16x32_bf16 v[248:251], v[40:43], v[56:59], 0
	v_mfma_f32_16x16x32_bf16 v[248:251], v[44:47], v[60:63], v[248:251]
	v_add_u32_e32 v135, 36, v182
	v_med3_i32 v135, v135, 0, s38
	v_lshl_add_u32 v135, v135, 9, v179
	global_load_dwordx4 v[24:27], v135, s[24:25]
	global_load_dwordx4 v[28:31], v135, s[24:25] offset:64
	v_mul_f32_e32 v152, 0x3fb8aa3b, v152
	v_mul_f32_e32 v153, 0x3fb8aa3b, v153
	v_mul_f32_e32 v154, 0x3fb8aa3b, v154
	v_mul_f32_e32 v155, 0x3fb8aa3b, v155
	v_exp_f32_e32 v152, v152
	v_exp_f32_e32 v153, v153
	v_exp_f32_e32 v154, v154
	v_exp_f32_e32 v155, v155
	v_add_u32_e32 v138, 48, v175
	v_add_u32_e32 v139, 49, v175
	v_add_u32_e32 v140, 50, v175
	v_add_u32_e32 v141, 51, v175
	v_cmp_gt_u32_e64 s[70:71], s44, v138
	v_cmp_gt_u32_e64 s[72:73], s44, v139
	v_cmp_gt_u32_e64 s[74:75], s44, v140
	v_cmp_gt_u32_e64 s[76:77], s44, v141
	v_cndmask_b32_e64 v152, 0, v152, s[70:71]
	v_cndmask_b32_e64 v153, 0, v153, s[72:73]
	v_cndmask_b32_e64 v154, 0, v154, s[74:75]
	v_cndmask_b32_e64 v155, 0, v155, s[76:77]
	v_add_f32_e32 v132, v132, v152
	v_add_f32_e32 v132, v132, v153
	v_add_f32_e32 v132, v132, v154
	v_add_f32_e32 v132, v132, v155
	v_cvt_pk_bf16_f32 v118, v152, v153
	v_cvt_pk_bf16_f32 v119, v154, v155
	v_mul_f32_e32 v156, 0x3fb8aa3b, v156
	v_mul_f32_e32 v157, 0x3fb8aa3b, v157
	v_mul_f32_e32 v158, 0x3fb8aa3b, v158
	v_mul_f32_e32 v159, 0x3fb8aa3b, v159
	v_exp_f32_e32 v156, v156
	v_exp_f32_e32 v157, v157
	v_exp_f32_e32 v158, v158
	v_exp_f32_e32 v159, v159
	v_add_u32_e32 v138, 48, v175
	v_add_u32_e32 v139, 49, v175
	v_add_u32_e32 v140, 50, v175
	v_add_u32_e32 v141, 51, v175
	v_cmp_gt_u32_e64 s[70:71], s44, v138
	v_cmp_gt_u32_e64 s[72:73], s44, v139
	v_cmp_gt_u32_e64 s[74:75], s44, v140
	v_cmp_gt_u32_e64 s[76:77], s44, v141
	v_cndmask_b32_e64 v156, 0, v156, s[70:71]
	v_cndmask_b32_e64 v157, 0, v157, s[72:73]
	v_cndmask_b32_e64 v158, 0, v158, s[74:75]
	v_cndmask_b32_e64 v159, 0, v159, s[76:77]
	v_add_f32_e32 v133, v133, v156
	v_add_f32_e32 v133, v133, v157
	v_add_f32_e32 v133, v133, v158
	v_add_f32_e32 v133, v133, v159
	v_cvt_pk_bf16_f32 v190, v156, v157
	v_cvt_pk_bf16_f32 v191, v158, v159
	v_min_f32_e32 v152, 0x42a00000, v236
	v_min_f32_e32 v153, 0x42a00000, v237
	v_min_f32_e32 v154, 0x42a00000, v238
	v_min_f32_e32 v155, 0x42a00000, v239
	v_min_f32_e32 v156, 0x42a00000, v244
	v_min_f32_e32 v157, 0x42a00000, v245
	v_min_f32_e32 v158, 0x42a00000, v246
	v_min_f32_e32 v159, 0x42a00000, v247
	s_waitcnt vmcnt(6)
	v_mfma_f32_16x16x32_bf16 v[236:239], v[0:3], v[48:51], 0
	v_mfma_f32_16x16x32_bf16 v[236:239], v[4:7], v[52:55], v[236:239]
	v_mfma_f32_16x16x32_bf16 v[244:247], v[0:3], v[56:59], 0
	v_mfma_f32_16x16x32_bf16 v[244:247], v[4:7], v[60:63], v[244:247]
	v_mul_f32_e32 v152, 0x3fb8aa3b, v152
	v_mul_f32_e32 v153, 0x3fb8aa3b, v153
	v_mul_f32_e32 v154, 0x3fb8aa3b, v154
	v_mul_f32_e32 v155, 0x3fb8aa3b, v155
	v_exp_f32_e32 v152, v152
	v_exp_f32_e32 v153, v153
	v_exp_f32_e32 v154, v154
	v_exp_f32_e32 v155, v155
	v_add_u32_e32 v138, 64, v175
	v_add_u32_e32 v139, 0x41, v175
	v_add_u32_e32 v140, 0x42, v175
	v_add_u32_e32 v141, 0x43, v175
	v_cmp_gt_u32_e64 s[70:71], s44, v138
	v_cmp_gt_u32_e64 s[72:73], s44, v139
	v_cmp_gt_u32_e64 s[74:75], s44, v140
	v_cmp_gt_u32_e64 s[76:77], s44, v141
	v_cndmask_b32_e64 v152, 0, v152, s[70:71]
	v_cndmask_b32_e64 v153, 0, v153, s[72:73]
	v_cndmask_b32_e64 v154, 0, v154, s[74:75]
	v_cndmask_b32_e64 v155, 0, v155, s[76:77]
	v_add_f32_e32 v132, v132, v152
	v_add_f32_e32 v132, v132, v153
	v_add_f32_e32 v132, v132, v154
	v_add_f32_e32 v132, v132, v155
	v_cvt_pk_bf16_f32 v120, v152, v153
	v_cvt_pk_bf16_f32 v121, v154, v155
	v_mul_f32_e32 v156, 0x3fb8aa3b, v156
	v_mul_f32_e32 v157, 0x3fb8aa3b, v157
	v_mul_f32_e32 v158, 0x3fb8aa3b, v158
	v_mul_f32_e32 v159, 0x3fb8aa3b, v159
	v_exp_f32_e32 v156, v156
	v_exp_f32_e32 v157, v157
	v_exp_f32_e32 v158, v158
	v_exp_f32_e32 v159, v159
	v_add_u32_e32 v138, 64, v175
	v_add_u32_e32 v139, 0x41, v175
	v_add_u32_e32 v140, 0x42, v175
	v_add_u32_e32 v141, 0x43, v175
	v_cmp_gt_u32_e64 s[70:71], s44, v138
	v_cmp_gt_u32_e64 s[72:73], s44, v139
	v_cmp_gt_u32_e64 s[74:75], s44, v140
	v_cmp_gt_u32_e64 s[76:77], s44, v141
	v_cndmask_b32_e64 v156, 0, v156, s[70:71]
	v_cndmask_b32_e64 v157, 0, v157, s[72:73]
	v_cndmask_b32_e64 v158, 0, v158, s[74:75]
	v_cndmask_b32_e64 v159, 0, v159, s[76:77]
	v_add_f32_e32 v133, v133, v156
	v_add_f32_e32 v133, v133, v157
	v_add_f32_e32 v133, v133, v158
	v_add_f32_e32 v133, v133, v159
	v_cvt_pk_bf16_f32 v192, v156, v157
	v_cvt_pk_bf16_f32 v193, v158, v159
	v_min_f32_e32 v152, 0x42a00000, v240
	v_min_f32_e32 v153, 0x42a00000, v241
	v_min_f32_e32 v154, 0x42a00000, v242
	v_min_f32_e32 v155, 0x42a00000, v243
	v_min_f32_e32 v156, 0x42a00000, v248
	v_min_f32_e32 v157, 0x42a00000, v249
	v_min_f32_e32 v158, 0x42a00000, v250
	v_min_f32_e32 v159, 0x42a00000, v251
	s_waitcnt vmcnt(4)
	v_mfma_f32_16x16x32_bf16 v[240:243], v[8:11], v[48:51], 0
	v_mfma_f32_16x16x32_bf16 v[240:243], v[12:15], v[52:55], v[240:243]
	v_mfma_f32_16x16x32_bf16 v[248:251], v[8:11], v[56:59], 0
	v_mfma_f32_16x16x32_bf16 v[248:251], v[12:15], v[60:63], v[248:251]
	v_mul_f32_e32 v152, 0x3fb8aa3b, v152
	v_mul_f32_e32 v153, 0x3fb8aa3b, v153
	v_mul_f32_e32 v154, 0x3fb8aa3b, v154
	v_mul_f32_e32 v155, 0x3fb8aa3b, v155
	v_exp_f32_e32 v152, v152
	v_exp_f32_e32 v153, v153
	v_exp_f32_e32 v154, v154
	v_exp_f32_e32 v155, v155
	v_add_u32_e32 v138, 0x50, v175
	v_add_u32_e32 v139, 0x51, v175
	v_add_u32_e32 v140, 0x52, v175
	v_add_u32_e32 v141, 0x53, v175
	v_cmp_gt_u32_e64 s[70:71], s44, v138
	v_cmp_gt_u32_e64 s[72:73], s44, v139
	v_cmp_gt_u32_e64 s[74:75], s44, v140
	v_cmp_gt_u32_e64 s[76:77], s44, v141
	v_cndmask_b32_e64 v152, 0, v152, s[70:71]
	v_cndmask_b32_e64 v153, 0, v153, s[72:73]
	v_cndmask_b32_e64 v154, 0, v154, s[74:75]
	v_cndmask_b32_e64 v155, 0, v155, s[76:77]
	v_add_f32_e32 v132, v132, v152
	v_add_f32_e32 v132, v132, v153
	v_add_f32_e32 v132, v132, v154
	v_add_f32_e32 v132, v132, v155
	v_cvt_pk_bf16_f32 v122, v152, v153
	v_cvt_pk_bf16_f32 v123, v154, v155
	v_mul_f32_e32 v156, 0x3fb8aa3b, v156
	v_mul_f32_e32 v157, 0x3fb8aa3b, v157
	v_mul_f32_e32 v158, 0x3fb8aa3b, v158
	v_mul_f32_e32 v159, 0x3fb8aa3b, v159
	v_exp_f32_e32 v156, v156
	v_exp_f32_e32 v157, v157
	v_exp_f32_e32 v158, v158
	v_exp_f32_e32 v159, v159
	v_add_u32_e32 v138, 0x50, v175
	v_add_u32_e32 v139, 0x51, v175
	v_add_u32_e32 v140, 0x52, v175
	v_add_u32_e32 v141, 0x53, v175
	v_cmp_gt_u32_e64 s[70:71], s44, v138
	v_cmp_gt_u32_e64 s[72:73], s44, v139
	v_cmp_gt_u32_e64 s[74:75], s44, v140
	v_cmp_gt_u32_e64 s[76:77], s44, v141
	v_cndmask_b32_e64 v156, 0, v156, s[70:71]
	v_cndmask_b32_e64 v157, 0, v157, s[72:73]
	v_cndmask_b32_e64 v158, 0, v158, s[74:75]
	v_cndmask_b32_e64 v159, 0, v159, s[76:77]
	v_add_f32_e32 v133, v133, v156
	v_add_f32_e32 v133, v133, v157
	v_add_f32_e32 v133, v133, v158
	v_add_f32_e32 v133, v133, v159
	v_cvt_pk_bf16_f32 v194, v156, v157
	v_cvt_pk_bf16_f32 v195, v158, v159
	v_min_f32_e32 v152, 0x42a00000, v236
	v_min_f32_e32 v153, 0x42a00000, v237
	v_min_f32_e32 v154, 0x42a00000, v238
	v_min_f32_e32 v155, 0x42a00000, v239
	v_min_f32_e32 v156, 0x42a00000, v244
	v_min_f32_e32 v157, 0x42a00000, v245
	v_min_f32_e32 v158, 0x42a00000, v246
	v_min_f32_e32 v159, 0x42a00000, v247
	s_waitcnt vmcnt(2)
	v_mfma_f32_16x16x32_bf16 v[236:239], v[16:19], v[48:51], 0
	v_mfma_f32_16x16x32_bf16 v[236:239], v[20:23], v[52:55], v[236:239]
	v_mfma_f32_16x16x32_bf16 v[244:247], v[16:19], v[56:59], 0
	v_mfma_f32_16x16x32_bf16 v[244:247], v[20:23], v[60:63], v[244:247]
	v_mul_f32_e32 v152, 0x3fb8aa3b, v152
	v_mul_f32_e32 v153, 0x3fb8aa3b, v153
	v_mul_f32_e32 v154, 0x3fb8aa3b, v154
	v_mul_f32_e32 v155, 0x3fb8aa3b, v155
	v_exp_f32_e32 v152, v152
	v_exp_f32_e32 v153, v153
	v_exp_f32_e32 v154, v154
	v_exp_f32_e32 v155, v155
	v_add_u32_e32 v138, 0x60, v175
	v_add_u32_e32 v139, 0x61, v175
	v_add_u32_e32 v140, 0x62, v175
	v_add_u32_e32 v141, 0x63, v175
	v_cmp_gt_u32_e64 s[70:71], s44, v138
	v_cmp_gt_u32_e64 s[72:73], s44, v139
	v_cmp_gt_u32_e64 s[74:75], s44, v140
	v_cmp_gt_u32_e64 s[76:77], s44, v141
	v_cndmask_b32_e64 v152, 0, v152, s[70:71]
	v_cndmask_b32_e64 v153, 0, v153, s[72:73]
	v_cndmask_b32_e64 v154, 0, v154, s[74:75]
	v_cndmask_b32_e64 v155, 0, v155, s[76:77]
	v_add_f32_e32 v132, v132, v152
	v_add_f32_e32 v132, v132, v153
	v_add_f32_e32 v132, v132, v154
	v_add_f32_e32 v132, v132, v155
	v_cvt_pk_bf16_f32 v124, v152, v153
	v_cvt_pk_bf16_f32 v125, v154, v155
	v_mul_f32_e32 v156, 0x3fb8aa3b, v156
	v_mul_f32_e32 v157, 0x3fb8aa3b, v157
	v_mul_f32_e32 v158, 0x3fb8aa3b, v158
	v_mul_f32_e32 v159, 0x3fb8aa3b, v159
	v_exp_f32_e32 v156, v156
	v_exp_f32_e32 v157, v157
	v_exp_f32_e32 v158, v158
	v_exp_f32_e32 v159, v159
	v_add_u32_e32 v138, 0x60, v175
	v_add_u32_e32 v139, 0x61, v175
	v_add_u32_e32 v140, 0x62, v175
	v_add_u32_e32 v141, 0x63, v175
	v_cmp_gt_u32_e64 s[70:71], s44, v138
	v_cmp_gt_u32_e64 s[72:73], s44, v139
	v_cmp_gt_u32_e64 s[74:75], s44, v140
	v_cmp_gt_u32_e64 s[76:77], s44, v141
	v_cndmask_b32_e64 v156, 0, v156, s[70:71]
	v_cndmask_b32_e64 v157, 0, v157, s[72:73]
	v_cndmask_b32_e64 v158, 0, v158, s[74:75]
	v_cndmask_b32_e64 v159, 0, v159, s[76:77]
	v_add_f32_e32 v133, v133, v156
	v_add_f32_e32 v133, v133, v157
	v_add_f32_e32 v133, v133, v158
	v_add_f32_e32 v133, v133, v159
	v_cvt_pk_bf16_f32 v196, v156, v157
	v_cvt_pk_bf16_f32 v197, v158, v159
	v_min_f32_e32 v152, 0x42a00000, v240
	v_min_f32_e32 v153, 0x42a00000, v241
	v_min_f32_e32 v154, 0x42a00000, v242
	v_min_f32_e32 v155, 0x42a00000, v243
	v_min_f32_e32 v156, 0x42a00000, v248
	v_min_f32_e32 v157, 0x42a00000, v249
	v_min_f32_e32 v158, 0x42a00000, v250
	v_min_f32_e32 v159, 0x42a00000, v251
	s_waitcnt vmcnt(0)
	v_mfma_f32_16x16x32_bf16 v[248:251], v[24:27], v[56:59], 0
	v_mfma_f32_16x16x32_bf16 v[248:251], v[28:31], v[60:63], v[248:251]
	v_mul_f32_e32 v152, 0x3fb8aa3b, v152
	v_mul_f32_e32 v153, 0x3fb8aa3b, v153
	v_mul_f32_e32 v154, 0x3fb8aa3b, v154
	v_mul_f32_e32 v155, 0x3fb8aa3b, v155
	v_exp_f32_e32 v152, v152
	v_exp_f32_e32 v153, v153
	v_exp_f32_e32 v154, v154
	v_exp_f32_e32 v155, v155
	v_add_u32_e32 v138, 0x70, v175
	v_add_u32_e32 v139, 0x71, v175
	v_add_u32_e32 v140, 0x72, v175
	v_add_u32_e32 v141, 0x73, v175
	v_cmp_gt_u32_e64 s[70:71], s44, v138
	v_cmp_gt_u32_e64 s[72:73], s44, v139
	v_cmp_gt_u32_e64 s[74:75], s44, v140
	v_cmp_gt_u32_e64 s[76:77], s44, v141
	v_cndmask_b32_e64 v152, 0, v152, s[70:71]
	v_cndmask_b32_e64 v153, 0, v153, s[72:73]
	v_cndmask_b32_e64 v154, 0, v154, s[74:75]
	v_cndmask_b32_e64 v155, 0, v155, s[76:77]
	v_add_f32_e32 v132, v132, v152
	v_add_f32_e32 v132, v132, v153
	v_add_f32_e32 v132, v132, v154
	v_add_f32_e32 v132, v132, v155
	v_cvt_pk_bf16_f32 v126, v152, v153
	v_cvt_pk_bf16_f32 v127, v154, v155
	v_mul_f32_e32 v156, 0x3fb8aa3b, v156
	v_mul_f32_e32 v157, 0x3fb8aa3b, v157
	v_mul_f32_e32 v158, 0x3fb8aa3b, v158
	v_mul_f32_e32 v159, 0x3fb8aa3b, v159
	v_exp_f32_e32 v156, v156
	v_exp_f32_e32 v157, v157
	v_exp_f32_e32 v158, v158
	v_exp_f32_e32 v159, v159
	v_add_u32_e32 v138, 0x70, v175
	v_add_u32_e32 v139, 0x71, v175
	v_add_u32_e32 v140, 0x72, v175
	v_add_u32_e32 v141, 0x73, v175
	v_cmp_gt_u32_e64 s[70:71], s44, v138
	v_cmp_gt_u32_e64 s[72:73], s44, v139
	v_cmp_gt_u32_e64 s[74:75], s44, v140
	v_cmp_gt_u32_e64 s[76:77], s44, v141
	v_cndmask_b32_e64 v156, 0, v156, s[70:71]
	v_cndmask_b32_e64 v157, 0, v157, s[72:73]
	v_cndmask_b32_e64 v158, 0, v158, s[74:75]
	v_cndmask_b32_e64 v159, 0, v159, s[76:77]
	v_add_f32_e32 v133, v133, v156
	v_add_f32_e32 v133, v133, v157
	v_add_f32_e32 v133, v133, v158
	v_add_f32_e32 v133, v133, v159
	v_cvt_pk_bf16_f32 v198, v156, v157
	v_cvt_pk_bf16_f32 v199, v158, v159
	v_min_f32_e32 v152, 0x42a00000, v236
	v_min_f32_e32 v153, 0x42a00000, v237
	v_min_f32_e32 v154, 0x42a00000, v238
	v_min_f32_e32 v155, 0x42a00000, v239
	v_min_f32_e32 v156, 0x42a00000, v244
	v_min_f32_e32 v157, 0x42a00000, v245
	v_min_f32_e32 v158, 0x42a00000, v246
	v_min_f32_e32 v159, 0x42a00000, v247
	v_mul_f32_e32 v152, 0x3fb8aa3b, v152
	v_mul_f32_e32 v153, 0x3fb8aa3b, v153
	v_mul_f32_e32 v154, 0x3fb8aa3b, v154
	v_mul_f32_e32 v155, 0x3fb8aa3b, v155
	v_exp_f32_e32 v152, v152
	v_exp_f32_e32 v153, v153
	v_exp_f32_e32 v154, v154
	v_exp_f32_e32 v155, v155
	v_add_u32_e32 v138, 0x80, v175
	v_add_u32_e32 v139, 0x81, v175
	v_add_u32_e32 v140, 0x82, v175
	v_add_u32_e32 v141, 0x83, v175
	v_cmp_gt_u32_e64 s[70:71], s44, v138
	v_cmp_gt_u32_e64 s[72:73], s44, v139
	v_cmp_gt_u32_e64 s[74:75], s44, v140
	v_cmp_gt_u32_e64 s[76:77], s44, v141
	v_cndmask_b32_e64 v152, 0, v152, s[62:63]
	v_cndmask_b32_e64 v153, 0, v153, s[64:65]
	v_cndmask_b32_e64 v154, 0, v154, s[66:67]
	v_cndmask_b32_e64 v155, 0, v155, s[68:69]
	v_cndmask_b32_e64 v152, 0, v152, s[70:71]
	v_cndmask_b32_e64 v153, 0, v153, s[72:73]
	v_cndmask_b32_e64 v154, 0, v154, s[74:75]
	v_cndmask_b32_e64 v155, 0, v155, s[76:77]
	v_add_f32_e32 v132, v132, v152
	v_add_f32_e32 v132, v132, v153
	v_add_f32_e32 v132, v132, v154
	v_add_f32_e32 v132, v132, v155
	v_cvt_pk_bf16_f32 v128, v152, v153
	v_cvt_pk_bf16_f32 v129, v154, v155
	v_mul_f32_e32 v156, 0x3fb8aa3b, v156
	v_mul_f32_e32 v157, 0x3fb8aa3b, v157
	v_mul_f32_e32 v158, 0x3fb8aa3b, v158
	v_mul_f32_e32 v159, 0x3fb8aa3b, v159
	v_exp_f32_e32 v156, v156
	v_exp_f32_e32 v157, v157
	v_exp_f32_e32 v158, v158
	v_exp_f32_e32 v159, v159
	v_add_u32_e32 v138, 0x80, v175
	v_add_u32_e32 v139, 0x81, v175
	v_add_u32_e32 v140, 0x82, v175
	v_add_u32_e32 v141, 0x83, v175
	v_cmp_gt_u32_e64 s[70:71], s44, v138
	v_cmp_gt_u32_e64 s[72:73], s44, v139
	v_cmp_gt_u32_e64 s[74:75], s44, v140
	v_cmp_gt_u32_e64 s[76:77], s44, v141
	v_cndmask_b32_e64 v156, 0, v156, s[70:71]
	v_cndmask_b32_e64 v157, 0, v157, s[72:73]
	v_cndmask_b32_e64 v158, 0, v158, s[74:75]
	v_cndmask_b32_e64 v159, 0, v159, s[76:77]
	v_add_f32_e32 v133, v133, v156
	v_add_f32_e32 v133, v133, v157
	v_add_f32_e32 v133, v133, v158
	v_add_f32_e32 v133, v133, v159
	v_cvt_pk_bf16_f32 v200, v156, v157
	v_cvt_pk_bf16_f32 v201, v158, v159
	v_min_f32_e32 v156, 0x42a00000, v248
	v_min_f32_e32 v157, 0x42a00000, v249
	v_min_f32_e32 v158, 0x42a00000, v250
	v_min_f32_e32 v159, 0x42a00000, v251
	v_mul_f32_e32 v156, 0x3fb8aa3b, v156
	v_mul_f32_e32 v157, 0x3fb8aa3b, v157
	v_mul_f32_e32 v158, 0x3fb8aa3b, v158
	v_mul_f32_e32 v159, 0x3fb8aa3b, v159
	v_exp_f32_e32 v156, v156
	v_exp_f32_e32 v157, v157
	v_exp_f32_e32 v158, v158
	v_exp_f32_e32 v159, v159
	v_add_u32_e32 v138, 0x90, v175
	v_add_u32_e32 v139, 0x91, v175
	v_add_u32_e32 v140, 0x92, v175
	v_add_u32_e32 v141, 0x93, v175
	v_cmp_gt_u32_e64 s[70:71], s44, v138
	v_cmp_gt_u32_e64 s[72:73], s44, v139
	v_cmp_gt_u32_e64 s[74:75], s44, v140
	v_cmp_gt_u32_e64 s[76:77], s44, v141
	v_cndmask_b32_e64 v156, 0, v156, s[62:63]
	v_cndmask_b32_e64 v157, 0, v157, s[64:65]
	v_cndmask_b32_e64 v158, 0, v158, s[66:67]
	v_cndmask_b32_e64 v159, 0, v159, s[68:69]
	v_cndmask_b32_e64 v156, 0, v156, s[70:71]
	v_cndmask_b32_e64 v157, 0, v157, s[72:73]
	v_cndmask_b32_e64 v158, 0, v158, s[74:75]
	v_cndmask_b32_e64 v159, 0, v159, s[76:77]
	v_add_f32_e32 v133, v133, v156
	v_add_f32_e32 v133, v133, v157
	v_add_f32_e32 v133, v133, v158
	v_add_f32_e32 v133, v133, v159
	v_cvt_pk_bf16_f32 v202, v156, v157
	v_cvt_pk_bf16_f32 v203, v158, v159
	v_add_u32_e32 v134, s42, v160
	v_lshlrev_b32_e32 v134, 4, v134
	v_add_u32_e32 v134, s43, v134
	v_subrev_u32_e32 v135, s15, v134
	v_lshrrev_b32_e32 v136, 4, v135
	v_add_u32_e32 v136, v136, v135
	v_mad_u32_u24 v176, v136, s79, v161
	v_lshl_add_u32 v177, v135, 2, s80
	s_sub_i32 s2, s42, 64
	v_add_u32_e32 v178, s2, v169
	v_and_b32_e32 v135, 3, v134
	v_lshlrev_b32_e32 v135, s13, v135
	v_lshrrev_b32_e32 v136, 2, v134
	v_add_u32_e32 v135, v135, v136
	v_lshl_add_u32 v135, v135, 7, v161
	global_load_dwordx4 v[48:51], v135, s[18:19]
	global_load_dwordx4 v[52:55], v135, s[18:19] offset:64
	v_subrev_u32_e32 v134, 0x400, v134
	v_and_b32_e32 v137, 3, v134
	v_lshlrev_b32_e32 v137, s13, v137
	v_bfe_u32 v135, v134, 2, 2
	v_add_u32_e32 v137, v137, v135
	v_lshl_add_u32 v183, v137, 7, v161
	v_ashrrev_i32_e32 v252, 4, v134
	v_med3_i32 v136, v252, 0, s14
	v_lshl_add_u32 v136, v136, 9, v183
	global_load_dwordx4 v[0:3], v136, s[20:21]
	global_load_dwordx4 v[4:7], v136, s[20:21] offset:64
	v_add_u32_e32 v135, 16, v252
	v_med3_i32 v135, v135, 0, s14
	v_lshl_add_u32 v135, v135, 9, v183
	global_load_dwordx4 v[8:11], v135, s[20:21]
	global_load_dwordx4 v[12:15], v135, s[20:21] offset:64
	v_add_u32_e32 v136, 32, v252
	v_med3_i32 v136, v136, 0, s14
	v_lshl_add_u32 v136, v136, 9, v183
	global_load_dwordx4 v[16:19], v136, s[20:21]
	global_load_dwordx4 v[20:23], v136, s[20:21] offset:64
	v_add_u32_e32 v135, 48, v252
	v_med3_i32 v135, v135, 0, s14
	v_lshl_add_u32 v135, v135, 9, v183
	global_load_dwordx4 v[24:27], v135, s[20:21]
	global_load_dwordx4 v[28:31], v135, s[20:21] offset:64
	v_add_u32_e32 v136, 64, v252
	v_med3_i32 v136, v136, 0, s14
	v_lshl_add_u32 v136, v136, 9, v183
	global_load_dwordx4 v[32:35], v136, s[20:21]
	global_load_dwordx4 v[36:39], v136, s[20:21] offset:64
	v_add_u32_e32 v135, 0x50, v252
	v_med3_i32 v135, v135, 0, s14
	v_lshl_add_u32 v135, v135, 9, v183
	global_load_dwordx4 v[40:43], v135, s[20:21]
	global_load_dwordx4 v[44:47], v135, s[20:21] offset:64
	ds_bpermute_b32 v142, v167, v132
	s_waitcnt lgkmcnt(0)
	v_add_f32_e32 v132, v132, v142
	ds_bpermute_b32 v142, v168, v132
	s_waitcnt lgkmcnt(0)
	v_add_f32_e32 v132, v132, v142
	ds_bpermute_b32 v142, v167, v133
	s_waitcnt lgkmcnt(0)
	v_add_f32_e32 v133, v133, v142
	ds_bpermute_b32 v142, v168, v133
	s_waitcnt lgkmcnt(0)
	v_add_f32_e32 v133, v133, v142
	s_waitcnt vmcnt(14)
	ds_write_b128 v165, v[64:67]
	ds_write_b128 v165, v[68:71] offset:1152
	ds_write_b128 v165, v[72:75] offset:2304
	ds_write_b128 v165, v[76:79] offset:3456
	s_waitcnt lgkmcnt(0)
	ds_read_b64_tr_b16 v[236:237], v166
	ds_read_b64_tr_b16 v[238:239], v166 offset:2304
	ds_read_b64_tr_b16 v[240:241], v166 offset:32
	ds_read_b64_tr_b16 v[242:243], v166 offset:2336
	ds_read_b64_tr_b16 v[244:245], v166 offset:64
	ds_read_b64_tr_b16 v[246:247], v166 offset:2368
	ds_read_b64_tr_b16 v[248:249], v166 offset:96
	ds_read_b64_tr_b16 v[250:251], v166 offset:2400
	s_waitcnt lgkmcnt(0)
	s_add_i32 s2, s40, 32
	v_add_u32_e32 v138, s2, v164
	v_lshlrev_b32_e32 v138, 2, v138
	v_add_u32_e32 v138, s41, v138
	v_and_b32_e32 v139, 3, v138
	v_lshlrev_b32_e32 v139, s39, v139
	v_bfe_u32 v140, v138, 2, 2
	v_add_u32_e32 v139, v139, v140
	v_lshl_add_u32 v139, v139, 7, v162
	v_ashrrev_i32_e32 v138, 4, v138
	v_med3_i32 v138, v138, 0, s38
	v_lshl_add_u32 v138, v138, 9, v139
	global_load_dwordx4 v[64:67], v138, s[26:27]
	s_add_i32 s2, s40, 40
	v_add_u32_e32 v138, s2, v164
	v_lshlrev_b32_e32 v138, 2, v138
	v_add_u32_e32 v138, s41, v138
	v_and_b32_e32 v139, 3, v138
	v_lshlrev_b32_e32 v139, s39, v139
	v_bfe_u32 v140, v138, 2, 2
	v_add_u32_e32 v139, v139, v140
	v_lshl_add_u32 v139, v139, 7, v162
	v_ashrrev_i32_e32 v138, 4, v138
	v_med3_i32 v138, v138, 0, s38
	v_lshl_add_u32 v138, v138, 9, v139
	global_load_dwordx4 v[68:71], v138, s[26:27]
	s_add_i32 s2, s40, 48
	v_add_u32_e32 v138, s2, v164
	v_lshlrev_b32_e32 v138, 2, v138
	v_add_u32_e32 v138, s41, v138
	v_and_b32_e32 v139, 3, v138
	v_lshlrev_b32_e32 v139, s39, v139
	v_bfe_u32 v140, v138, 2, 2
	v_add_u32_e32 v139, v139, v140
	v_lshl_add_u32 v139, v139, 7, v162
	v_ashrrev_i32_e32 v138, 4, v138
	v_med3_i32 v138, v138, 0, s38
	v_lshl_add_u32 v138, v138, 9, v139
	global_load_dwordx4 v[72:75], v138, s[26:27]
	s_add_i32 s2, s40, 56
	v_add_u32_e32 v138, s2, v164
	v_lshlrev_b32_e32 v138, 2, v138
	v_add_u32_e32 v138, s41, v138
	v_and_b32_e32 v139, 3, v138
	v_lshlrev_b32_e32 v139, s39, v139
	v_bfe_u32 v140, v138, 2, 2
	v_add_u32_e32 v139, v139, v140
	v_lshl_add_u32 v139, v139, 7, v162
	v_ashrrev_i32_e32 v138, 4, v138
	v_med3_i32 v138, v138, 0, s38
	v_lshl_add_u32 v138, v138, 9, v139
	global_load_dwordx4 v[76:79], v138, s[26:27]
	ds_write_b128 v165, v[80:83]
	ds_write_b128 v165, v[84:87] offset:1152
	ds_write_b128 v165, v[88:91] offset:2304
	ds_write_b128 v165, v[92:95] offset:3456
	v_mfma_f32_16x16x32_bf16 v[204:207], v[236:239], v[112:115], 0
	v_mfma_f32_16x16x32_bf16 v[208:211], v[240:243], v[112:115], 0
	v_mfma_f32_16x16x32_bf16 v[212:215], v[244:247], v[112:115], 0
	v_mfma_f32_16x16x32_bf16 v[216:219], v[248:251], v[112:115], 0
	v_mfma_f32_16x16x32_bf16 v[220:223], v[236:239], v[184:187], 0
	v_mfma_f32_16x16x32_bf16 v[224:227], v[240:243], v[184:187], 0
	v_mfma_f32_16x16x32_bf16 v[228:231], v[244:247], v[184:187], 0
	v_mfma_f32_16x16x32_bf16 v[232:235], v[248:251], v[184:187], 0
	s_waitcnt lgkmcnt(0)
	ds_read_b64_tr_b16 v[236:237], v166
	ds_read_b64_tr_b16 v[238:239], v166 offset:2304
	ds_read_b64_tr_b16 v[240:241], v166 offset:32
	ds_read_b64_tr_b16 v[242:243], v166 offset:2336
	ds_read_b64_tr_b16 v[244:245], v166 offset:64
	ds_read_b64_tr_b16 v[246:247], v166 offset:2368
	ds_read_b64_tr_b16 v[248:249], v166 offset:96
	ds_read_b64_tr_b16 v[250:251], v166 offset:2400
	s_waitcnt lgkmcnt(0)
	s_add_i32 s2, s40, 64
	v_add_u32_e32 v138, s2, v164
	v_lshlrev_b32_e32 v138, 2, v138
	v_add_u32_e32 v138, s41, v138
	v_and_b32_e32 v139, 3, v138
	v_lshlrev_b32_e32 v139, s39, v139
	v_bfe_u32 v140, v138, 2, 2
	v_add_u32_e32 v139, v139, v140
	v_lshl_add_u32 v139, v139, 7, v162
	v_ashrrev_i32_e32 v138, 4, v138
	v_med3_i32 v138, v138, 0, s38
	v_lshl_add_u32 v138, v138, 9, v139
	global_load_dwordx4 v[80:83], v138, s[26:27]
	s_add_i32 s2, s40, 72
	v_add_u32_e32 v138, s2, v164
	v_lshlrev_b32_e32 v138, 2, v138
	v_add_u32_e32 v138, s41, v138
	v_and_b32_e32 v139, 3, v138
	v_lshlrev_b32_e32 v139, s39, v139
	v_bfe_u32 v140, v138, 2, 2
	v_add_u32_e32 v139, v139, v140
	v_lshl_add_u32 v139, v139, 7, v162
	v_ashrrev_i32_e32 v138, 4, v138
	v_med3_i32 v138, v138, 0, s38
	v_lshl_add_u32 v138, v138, 9, v139
	global_load_dwordx4 v[84:87], v138, s[26:27]
	s_add_i32 s2, s40, 80
	v_add_u32_e32 v138, s2, v164
	v_lshlrev_b32_e32 v138, 2, v138
	v_add_u32_e32 v138, s41, v138
	v_and_b32_e32 v139, 3, v138
	v_lshlrev_b32_e32 v139, s39, v139
	v_bfe_u32 v140, v138, 2, 2
	v_add_u32_e32 v139, v139, v140
	v_lshl_add_u32 v139, v139, 7, v162
	v_ashrrev_i32_e32 v138, 4, v138
	v_med3_i32 v138, v138, 0, s38
	v_lshl_add_u32 v138, v138, 9, v139
	global_load_dwordx4 v[88:91], v138, s[26:27]
	s_add_i32 s2, s40, 88
	v_add_u32_e32 v138, s2, v164
	v_lshlrev_b32_e32 v138, 2, v138
	v_add_u32_e32 v138, s41, v138
	v_and_b32_e32 v139, 3, v138
	v_lshlrev_b32_e32 v139, s39, v139
	v_bfe_u32 v140, v138, 2, 2
	v_add_u32_e32 v139, v139, v140
	v_lshl_add_u32 v139, v139, 7, v162
	v_ashrrev_i32_e32 v138, 4, v138
	v_med3_i32 v138, v138, 0, s38
	v_lshl_add_u32 v138, v138, 9, v139
	global_load_dwordx4 v[92:95], v138, s[26:27]
	ds_write_b128 v165, v[96:99]
	ds_write_b128 v165, v[100:103] offset:1152
	ds_write_b128 v165, v[104:107] offset:2304
	ds_write_b128 v165, v[108:111] offset:3456
	v_mfma_f32_16x16x32_bf16 v[204:207], v[236:239], v[116:119], v[204:207]
	v_mfma_f32_16x16x32_bf16 v[208:211], v[240:243], v[116:119], v[208:211]
	v_mfma_f32_16x16x32_bf16 v[212:215], v[244:247], v[116:119], v[212:215]
	v_mfma_f32_16x16x32_bf16 v[216:219], v[248:251], v[116:119], v[216:219]
	v_mfma_f32_16x16x32_bf16 v[220:223], v[236:239], v[188:191], v[220:223]
	v_mfma_f32_16x16x32_bf16 v[224:227], v[240:243], v[188:191], v[224:227]
	v_mfma_f32_16x16x32_bf16 v[228:231], v[244:247], v[188:191], v[228:231]
	v_mfma_f32_16x16x32_bf16 v[232:235], v[248:251], v[188:191], v[232:235]
	s_waitcnt lgkmcnt(0)
	ds_read_b64_tr_b16 v[236:237], v166
	ds_read_b64_tr_b16 v[238:239], v166 offset:2304
	ds_read_b64_tr_b16 v[240:241], v166 offset:32
	ds_read_b64_tr_b16 v[242:243], v166 offset:2336
	ds_read_b64_tr_b16 v[244:245], v166 offset:64
	ds_read_b64_tr_b16 v[246:247], v166 offset:2368
	ds_read_b64_tr_b16 v[248:249], v166 offset:96
	ds_read_b64_tr_b16 v[250:251], v166 offset:2400
	s_waitcnt lgkmcnt(0)
	s_waitcnt vmcnt(4)
	ds_write_b128 v165, v[64:67]
	ds_write_b128 v165, v[68:71] offset:1152
	ds_write_b128 v165, v[72:75] offset:2304
	ds_write_b128 v165, v[76:79] offset:3456
	v_mfma_f32_16x16x32_bf16 v[204:207], v[236:239], v[120:123], v[204:207]
	v_mfma_f32_16x16x32_bf16 v[208:211], v[240:243], v[120:123], v[208:211]
	v_mfma_f32_16x16x32_bf16 v[212:215], v[244:247], v[120:123], v[212:215]
	v_mfma_f32_16x16x32_bf16 v[216:219], v[248:251], v[120:123], v[216:219]
	v_mfma_f32_16x16x32_bf16 v[220:223], v[236:239], v[192:195], v[220:223]
	v_mfma_f32_16x16x32_bf16 v[224:227], v[240:243], v[192:195], v[224:227]
	v_mfma_f32_16x16x32_bf16 v[228:231], v[244:247], v[192:195], v[228:231]
	v_mfma_f32_16x16x32_bf16 v[232:235], v[248:251], v[192:195], v[232:235]
	s_waitcnt lgkmcnt(0)
	ds_read_b64_tr_b16 v[236:237], v166
	ds_read_b64_tr_b16 v[238:239], v166 offset:2304
	ds_read_b64_tr_b16 v[240:241], v166 offset:32
	ds_read_b64_tr_b16 v[242:243], v166 offset:2336
	ds_read_b64_tr_b16 v[244:245], v166 offset:64
	ds_read_b64_tr_b16 v[246:247], v166 offset:2368
	ds_read_b64_tr_b16 v[248:249], v166 offset:96
	ds_read_b64_tr_b16 v[250:251], v166 offset:2400
	s_waitcnt lgkmcnt(0)
	s_waitcnt vmcnt(0)
	ds_write_b128 v165, v[80:83]
	ds_write_b128 v165, v[84:87] offset:1152
	ds_write_b128 v165, v[88:91] offset:2304
	ds_write_b128 v165, v[92:95] offset:3456
	v_mfma_f32_16x16x32_bf16 v[204:207], v[236:239], v[124:127], v[204:207]
	v_mfma_f32_16x16x32_bf16 v[208:211], v[240:243], v[124:127], v[208:211]
	v_mfma_f32_16x16x32_bf16 v[212:215], v[244:247], v[124:127], v[212:215]
	v_mfma_f32_16x16x32_bf16 v[216:219], v[248:251], v[124:127], v[216:219]
	v_mfma_f32_16x16x32_bf16 v[220:223], v[236:239], v[196:199], v[220:223]
	v_mfma_f32_16x16x32_bf16 v[224:227], v[240:243], v[196:199], v[224:227]
	v_mfma_f32_16x16x32_bf16 v[228:231], v[244:247], v[196:199], v[228:231]
	v_mfma_f32_16x16x32_bf16 v[232:235], v[248:251], v[196:199], v[232:235]
	s_waitcnt lgkmcnt(0)
	ds_read_b64_tr_b16 v[236:237], v166
	ds_read_b64_tr_b16 v[238:239], v166 offset:2304
	ds_read_b64_tr_b16 v[240:241], v166 offset:32
	ds_read_b64_tr_b16 v[242:243], v166 offset:2336
	ds_read_b64_tr_b16 v[244:245], v166 offset:64
	ds_read_b64_tr_b16 v[246:247], v166 offset:2368
	ds_read_b64_tr_b16 v[248:249], v166 offset:96
	ds_read_b64_tr_b16 v[250:251], v166 offset:2400
	s_waitcnt lgkmcnt(0)
	v_mfma_f32_16x16x32_bf16 v[204:207], v[236:239], v[128:131], v[204:207]
	v_mfma_f32_16x16x32_bf16 v[208:211], v[240:243], v[128:131], v[208:211]
	v_mfma_f32_16x16x32_bf16 v[212:215], v[244:247], v[128:131], v[212:215]
	v_mfma_f32_16x16x32_bf16 v[216:219], v[248:251], v[128:131], v[216:219]
	v_mfma_f32_16x16x32_bf16 v[220:223], v[236:239], v[200:203], v[220:223]
	v_mfma_f32_16x16x32_bf16 v[224:227], v[240:243], v[200:203], v[224:227]
	v_mfma_f32_16x16x32_bf16 v[228:231], v[244:247], v[200:203], v[228:231]
	v_mfma_f32_16x16x32_bf16 v[232:235], v[248:251], v[200:203], v[232:235]
	s_add_i32 s2, s42, -64
	v_add_u32_e32 v138, s2, v164
	v_lshlrev_b32_e32 v138, 4, v138
	v_add_u32_e32 v138, s43, v138
	v_and_b32_e32 v139, 3, v138
	v_lshlrev_b32_e32 v139, s13, v139
	v_bfe_u32 v140, v138, 2, 2
	v_add_u32_e32 v139, v139, v140
	v_lshl_add_u32 v139, v139, 7, v162
	v_ashrrev_i32_e32 v138, 4, v138
	v_med3_i32 v138, v138, 0, s14
	v_lshl_add_u32 v138, v138, 9, v139
	global_load_dwordx4 v[64:67], v138, s[22:23]
	s_add_i32 s2, s42, -56
	v_add_u32_e32 v138, s2, v164
	v_lshlrev_b32_e32 v138, 4, v138
	v_add_u32_e32 v138, s43, v138
	v_and_b32_e32 v139, 3, v138
	v_lshlrev_b32_e32 v139, s13, v139
	v_bfe_u32 v140, v138, 2, 2
	v_add_u32_e32 v139, v139, v140
	v_lshl_add_u32 v139, v139, 7, v162
	v_ashrrev_i32_e32 v138, 4, v138
	v_med3_i32 v138, v138, 0, s14
	v_lshl_add_u32 v138, v138, 9, v139
	global_load_dwordx4 v[68:71], v138, s[22:23]
	s_add_i32 s2, s42, -48
	v_add_u32_e32 v138, s2, v164
	v_lshlrev_b32_e32 v138, 4, v138
	v_add_u32_e32 v138, s43, v138
	v_and_b32_e32 v139, 3, v138
	v_lshlrev_b32_e32 v139, s13, v139
	v_bfe_u32 v140, v138, 2, 2
	v_add_u32_e32 v139, v139, v140
	v_lshl_add_u32 v139, v139, 7, v162
	v_ashrrev_i32_e32 v138, 4, v138
	v_med3_i32 v138, v138, 0, s14
	v_lshl_add_u32 v138, v138, 9, v139
	global_load_dwordx4 v[72:75], v138, s[22:23]
	s_add_i32 s2, s42, -40
	v_add_u32_e32 v138, s2, v164
	v_lshlrev_b32_e32 v138, 4, v138
	v_add_u32_e32 v138, s43, v138
	v_and_b32_e32 v139, 3, v138
	v_lshlrev_b32_e32 v139, s13, v139
	v_bfe_u32 v140, v138, 2, 2
	v_add_u32_e32 v139, v139, v140
	v_lshl_add_u32 v139, v139, 7, v162
	v_ashrrev_i32_e32 v138, 4, v138
	v_med3_i32 v138, v138, 0, s14
	v_lshl_add_u32 v138, v138, 9, v139
	global_load_dwordx4 v[76:79], v138, s[22:23]
	s_add_i32 s2, s42, -32
	v_add_u32_e32 v138, s2, v164
	v_lshlrev_b32_e32 v138, 4, v138
	v_add_u32_e32 v138, s43, v138
	v_and_b32_e32 v139, 3, v138
	v_lshlrev_b32_e32 v139, s13, v139
	v_bfe_u32 v140, v138, 2, 2
	v_add_u32_e32 v139, v139, v140
	v_lshl_add_u32 v139, v139, 7, v162
	v_ashrrev_i32_e32 v138, 4, v138
	v_med3_i32 v138, v138, 0, s14
	v_lshl_add_u32 v138, v138, 9, v139
	global_load_dwordx4 v[80:83], v138, s[22:23]
	s_add_i32 s2, s42, -24
	v_add_u32_e32 v138, s2, v164
	v_lshlrev_b32_e32 v138, 4, v138
	v_add_u32_e32 v138, s43, v138
	v_and_b32_e32 v139, 3, v138
	v_lshlrev_b32_e32 v139, s13, v139
	v_bfe_u32 v140, v138, 2, 2
	v_add_u32_e32 v139, v139, v140
	v_lshl_add_u32 v139, v139, 7, v162
	v_ashrrev_i32_e32 v138, 4, v138
	v_med3_i32 v138, v138, 0, s14
	v_lshl_add_u32 v138, v138, 9, v139
	global_load_dwordx4 v[84:87], v138, s[22:23]
	s_add_i32 s2, s42, -16
	v_add_u32_e32 v138, s2, v164
	v_lshlrev_b32_e32 v138, 4, v138
	v_add_u32_e32 v138, s43, v138
	v_and_b32_e32 v139, 3, v138
	v_lshlrev_b32_e32 v139, s13, v139
	v_bfe_u32 v140, v138, 2, 2
	v_add_u32_e32 v139, v139, v140
	v_lshl_add_u32 v139, v139, 7, v162
	v_ashrrev_i32_e32 v138, 4, v138
	v_med3_i32 v138, v138, 0, s14
	v_lshl_add_u32 v138, v138, 9, v139
	global_load_dwordx4 v[88:91], v138, s[22:23]
	s_add_i32 s2, s42, -8
	v_add_u32_e32 v138, s2, v164
	v_lshlrev_b32_e32 v138, 4, v138
	v_add_u32_e32 v138, s43, v138
	v_and_b32_e32 v139, 3, v138
	v_lshlrev_b32_e32 v139, s13, v139
	v_bfe_u32 v140, v138, 2, 2
	v_add_u32_e32 v139, v139, v140
	v_lshl_add_u32 v139, v139, 7, v162
	v_ashrrev_i32_e32 v138, 4, v138
	v_med3_i32 v138, v138, 0, s14
	v_lshl_add_u32 v138, v138, 9, v139
	global_load_dwordx4 v[92:95], v138, s[22:23]
	s_add_i32 s2, s42, 0
	v_add_u32_e32 v138, s2, v164
	v_lshlrev_b32_e32 v138, 4, v138
	v_add_u32_e32 v138, s43, v138
	v_and_b32_e32 v139, 3, v138
	v_lshlrev_b32_e32 v139, s13, v139
	v_bfe_u32 v140, v138, 2, 2
	v_add_u32_e32 v139, v139, v140
	v_lshl_add_u32 v139, v139, 7, v162
	v_ashrrev_i32_e32 v138, 4, v138
	v_med3_i32 v138, v138, 0, s14
	v_lshl_add_u32 v138, v138, 9, v139
	global_load_dwordx4 v[96:99], v138, s[22:23]
	s_add_i32 s2, s42, 8
	v_add_u32_e32 v138, s2, v164
	v_lshlrev_b32_e32 v138, 4, v138
	v_add_u32_e32 v138, s43, v138
	v_and_b32_e32 v139, 3, v138
	v_lshlrev_b32_e32 v139, s13, v139
	v_bfe_u32 v140, v138, 2, 2
	v_add_u32_e32 v139, v139, v140
	v_lshl_add_u32 v139, v139, 7, v162
	v_ashrrev_i32_e32 v138, 4, v138
	v_med3_i32 v138, v138, 0, s14
	v_lshl_add_u32 v138, v138, 9, v139
	global_load_dwordx4 v[100:103], v138, s[22:23]
	s_add_i32 s2, s42, 16
	v_add_u32_e32 v138, s2, v164
	v_lshlrev_b32_e32 v138, 4, v138
	v_add_u32_e32 v138, s43, v138
	v_and_b32_e32 v139, 3, v138
	v_lshlrev_b32_e32 v139, s13, v139
	v_bfe_u32 v140, v138, 2, 2
	v_add_u32_e32 v139, v139, v140
	v_lshl_add_u32 v139, v139, 7, v162
	v_ashrrev_i32_e32 v138, 4, v138
	v_med3_i32 v138, v138, 0, s14
	v_lshl_add_u32 v138, v138, 9, v139
	global_load_dwordx4 v[104:107], v138, s[22:23]
	s_add_i32 s2, s42, 24
	v_add_u32_e32 v138, s2, v164
	v_lshlrev_b32_e32 v138, 4, v138
	v_add_u32_e32 v138, s43, v138
	v_and_b32_e32 v139, 3, v138
	v_lshlrev_b32_e32 v139, s13, v139
	v_bfe_u32 v140, v138, 2, 2
	v_add_u32_e32 v139, v139, v140
	v_lshl_add_u32 v139, v139, 7, v162
	v_ashrrev_i32_e32 v138, 4, v138
	v_med3_i32 v138, v138, 0, s14
	v_lshl_add_u32 v138, v138, 9, v139
	global_load_dwordx4 v[108:111], v138, s[22:23]
	ds_read_b128 v[236:239], v173 offset:0
	ds_read_b128 v[240:243], v173 offset:64
	ds_read_b128 v[244:247], v173 offset:128
	ds_read_b128 v[248:251], v173 offset:192
	ds_read_b32 v142, v174 offset:0
	s_waitcnt lgkmcnt(0)
	v_add_f32_e32 v204, v236, v204
	v_add_f32_e32 v205, v237, v205
	v_add_f32_e32 v206, v238, v206
	v_add_f32_e32 v207, v239, v207
	v_add_f32_e32 v208, v240, v208
	v_add_f32_e32 v209, v241, v209
	v_add_f32_e32 v210, v242, v210
	v_add_f32_e32 v211, v243, v211
	v_add_f32_e32 v212, v244, v212
	v_add_f32_e32 v213, v245, v213
	v_add_f32_e32 v214, v246, v214
	v_add_f32_e32 v215, v247, v215
	v_add_f32_e32 v216, v248, v216
	v_add_f32_e32 v217, v249, v217
	v_add_f32_e32 v218, v250, v218
	v_add_f32_e32 v219, v251, v219
	v_add_f32_e32 v132, v142, v132
	ds_write_b128 v173, v[204:207] offset:0
	ds_write_b128 v173, v[208:211] offset:64
	ds_write_b128 v173, v[212:215] offset:128
	ds_write_b128 v173, v[216:219] offset:192
	ds_write_b32 v174, v132 offset:0
	ds_read_b128 v[236:239], v173 offset:18496
	ds_read_b128 v[240:243], v173 offset:18560
	ds_read_b128 v[244:247], v173 offset:18624
	ds_read_b128 v[248:251], v173 offset:18688
	ds_read_b32 v142, v174 offset:256
	s_waitcnt lgkmcnt(0)
	v_add_f32_e32 v220, v236, v220
	v_add_f32_e32 v221, v237, v221
	v_add_f32_e32 v222, v238, v222
	v_add_f32_e32 v223, v239, v223
	v_add_f32_e32 v224, v240, v224
	v_add_f32_e32 v225, v241, v225
	v_add_f32_e32 v226, v242, v226
	v_add_f32_e32 v227, v243, v227
	v_add_f32_e32 v228, v244, v228
	v_add_f32_e32 v229, v245, v229
	v_add_f32_e32 v230, v246, v230
	v_add_f32_e32 v231, v247, v231
	v_add_f32_e32 v232, v248, v232
	v_add_f32_e32 v233, v249, v233
	v_add_f32_e32 v234, v250, v234
	v_add_f32_e32 v235, v251, v235
	v_add_f32_e32 v133, v142, v133
	ds_write_b128 v173, v[220:223] offset:18496
	ds_write_b128 v173, v[224:227] offset:18560
	ds_write_b128 v173, v[228:231] offset:18624
	ds_write_b128 v173, v[232:235] offset:18688
	ds_write_b32 v174, v133 offset:256
	s_waitcnt lgkmcnt(0)
	s_barrier
	s_mov_b32 s40, s42
	s_mov_b32 s41, s43
	v_mov_b32_e32 v173, v176
	v_mov_b32_e32 v174, v177
	v_mov_b32_e32 v175, v178
	v_mov_b32_e32 v179, v183
	v_mov_b32_e32 v182, v252
	s_lshr_b32 s44, s33, 4
	s_lshr_b32 s42, s15, 4
	s_add_i32 s43, s0, 8
	s_waitcnt vmcnt(12)
	v_mov_b32_e32 v132, 0
	v_mfma_f32_16x16x32_bf16 v[236:239], v[0:3], v[48:51], 0
	v_mfma_f32_16x16x32_bf16 v[236:239], v[4:7], v[52:55], v[236:239]
	v_mfma_f32_16x16x32_bf16 v[240:243], v[8:11], v[48:51], 0
	v_mfma_f32_16x16x32_bf16 v[240:243], v[12:15], v[52:55], v[240:243]
	s_nop 7
	v_min_f32_e32 v152, 0x42a00000, v236
	v_min_f32_e32 v153, 0x42a00000, v237
	v_min_f32_e32 v154, 0x42a00000, v238
	v_min_f32_e32 v155, 0x42a00000, v239
	v_mfma_f32_16x16x32_bf16 v[236:239], v[16:19], v[48:51], 0
	v_mfma_f32_16x16x32_bf16 v[236:239], v[20:23], v[52:55], v[236:239]
	v_add_u32_e32 v136, 0x60, v182
	v_med3_i32 v136, v136, 0, s38
	v_lshl_add_u32 v136, v136, 9, v179
	global_load_dwordx4 v[0:3], v136, s[24:25]
	global_load_dwordx4 v[4:7], v136, s[24:25] offset:64
	v_mul_f32_e32 v152, 0x3fb8aa3b, v152
	v_mul_f32_e32 v153, 0x3fb8aa3b, v153
	v_mul_f32_e32 v154, 0x3fb8aa3b, v154
	v_mul_f32_e32 v155, 0x3fb8aa3b, v155
	v_exp_f32_e32 v152, v152
	v_exp_f32_e32 v153, v153
	v_exp_f32_e32 v154, v154
	v_exp_f32_e32 v155, v155
	v_add_u32_e32 v138, 0, v175
	v_add_u32_e32 v139, 1, v175
	v_add_u32_e32 v140, 2, v175
	v_add_u32_e32 v141, 3, v175
	v_cmp_gt_u32_e64 s[70:71], s44, v138
	v_cmp_gt_u32_e64 s[72:73], s44, v139
	v_cmp_gt_u32_e64 s[74:75], s44, v140
	v_cmp_gt_u32_e64 s[76:77], s44, v141
	v_cndmask_b32_e64 v152, 0, v152, s[54:55]
	v_cndmask_b32_e64 v153, 0, v153, s[56:57]
	v_cndmask_b32_e64 v154, 0, v154, s[58:59]
	v_cndmask_b32_e64 v155, 0, v155, s[60:61]
	v_cndmask_b32_e64 v152, 0, v152, s[70:71]
	v_cndmask_b32_e64 v153, 0, v153, s[72:73]
	v_cndmask_b32_e64 v154, 0, v154, s[74:75]
	v_cndmask_b32_e64 v155, 0, v155, s[76:77]
	v_add_f32_e32 v132, v132, v152
	v_add_f32_e32 v132, v132, v153
	v_add_f32_e32 v132, v132, v154
	v_add_f32_e32 v132, v132, v155
	v_cvt_pk_bf16_f32 v112, v152, v153
	v_cvt_pk_bf16_f32 v113, v154, v155
	v_min_f32_e32 v152, 0x42a00000, v240
	v_min_f32_e32 v153, 0x42a00000, v241
	v_min_f32_e32 v154, 0x42a00000, v242
	v_min_f32_e32 v155, 0x42a00000, v243
	v_mfma_f32_16x16x32_bf16 v[240:243], v[24:27], v[48:51], 0
	v_mfma_f32_16x16x32_bf16 v[240:243], v[28:31], v[52:55], v[240:243]
	v_add_u32_e32 v135, 0x70, v182
	v_med3_i32 v135, v135, 0, s38
	v_lshl_add_u32 v135, v135, 9, v179
	global_load_dwordx4 v[8:11], v135, s[24:25]
	global_load_dwordx4 v[12:15], v135, s[24:25] offset:64
	v_mul_f32_e32 v152, 0x3fb8aa3b, v152
	v_mul_f32_e32 v153, 0x3fb8aa3b, v153
	v_mul_f32_e32 v154, 0x3fb8aa3b, v154
	v_mul_f32_e32 v155, 0x3fb8aa3b, v155
	v_exp_f32_e32 v152, v152
	v_exp_f32_e32 v153, v153
	v_exp_f32_e32 v154, v154
	v_exp_f32_e32 v155, v155
	v_add_u32_e32 v138, 16, v175
	v_add_u32_e32 v139, 17, v175
	v_add_u32_e32 v140, 18, v175
	v_add_u32_e32 v141, 19, v175
	v_cmp_gt_u32_e64 s[70:71], s44, v138
	v_cmp_gt_u32_e64 s[72:73], s44, v139
	v_cmp_gt_u32_e64 s[74:75], s44, v140
	v_cmp_gt_u32_e64 s[76:77], s44, v141
	v_cndmask_b32_e64 v152, 0, v152, s[70:71]
	v_cndmask_b32_e64 v153, 0, v153, s[72:73]
	v_cndmask_b32_e64 v154, 0, v154, s[74:75]
	v_cndmask_b32_e64 v155, 0, v155, s[76:77]
	v_add_f32_e32 v132, v132, v152
	v_add_f32_e32 v132, v132, v153
	v_add_f32_e32 v132, v132, v154
	v_add_f32_e32 v132, v132, v155
	v_cvt_pk_bf16_f32 v114, v152, v153
	v_cvt_pk_bf16_f32 v115, v154, v155
	v_min_f32_e32 v152, 0x42a00000, v236
	v_min_f32_e32 v153, 0x42a00000, v237
	v_min_f32_e32 v154, 0x42a00000, v238
	v_min_f32_e32 v155, 0x42a00000, v239
	v_mfma_f32_16x16x32_bf16 v[236:239], v[32:35], v[48:51], 0
	v_mfma_f32_16x16x32_bf16 v[236:239], v[36:39], v[52:55], v[236:239]
	v_add_u32_e32 v136, 0x80, v182
	v_med3_i32 v136, v136, 0, s38
	v_lshl_add_u32 v136, v136, 9, v179
	global_load_dwordx4 v[16:19], v136, s[24:25]
	global_load_dwordx4 v[20:23], v136, s[24:25] offset:64
	v_mul_f32_e32 v152, 0x3fb8aa3b, v152
	v_mul_f32_e32 v153, 0x3fb8aa3b, v153
	v_mul_f32_e32 v154, 0x3fb8aa3b, v154
	v_mul_f32_e32 v155, 0x3fb8aa3b, v155
	v_exp_f32_e32 v152, v152
	v_exp_f32_e32 v153, v153
	v_exp_f32_e32 v154, v154
	v_exp_f32_e32 v155, v155
	v_add_u32_e32 v138, 32, v175
	v_add_u32_e32 v139, 33, v175
	v_add_u32_e32 v140, 34, v175
	v_add_u32_e32 v141, 35, v175
	v_cmp_gt_u32_e64 s[70:71], s44, v138
	v_cmp_gt_u32_e64 s[72:73], s44, v139
	v_cmp_gt_u32_e64 s[74:75], s44, v140
	v_cmp_gt_u32_e64 s[76:77], s44, v141
	v_cndmask_b32_e64 v152, 0, v152, s[70:71]
	v_cndmask_b32_e64 v153, 0, v153, s[72:73]
	v_cndmask_b32_e64 v154, 0, v154, s[74:75]
	v_cndmask_b32_e64 v155, 0, v155, s[76:77]
	v_add_f32_e32 v132, v132, v152
	v_add_f32_e32 v132, v132, v153
	v_add_f32_e32 v132, v132, v154
	v_add_f32_e32 v132, v132, v155
	v_cvt_pk_bf16_f32 v116, v152, v153
	v_cvt_pk_bf16_f32 v117, v154, v155
	v_min_f32_e32 v152, 0x42a00000, v240
	v_min_f32_e32 v153, 0x42a00000, v241
	v_min_f32_e32 v154, 0x42a00000, v242
	v_min_f32_e32 v155, 0x42a00000, v243
	v_mfma_f32_16x16x32_bf16 v[240:243], v[40:43], v[48:51], 0
	v_mfma_f32_16x16x32_bf16 v[240:243], v[44:47], v[52:55], v[240:243]
	v_mul_f32_e32 v152, 0x3fb8aa3b, v152
	v_mul_f32_e32 v153, 0x3fb8aa3b, v153
	v_mul_f32_e32 v154, 0x3fb8aa3b, v154
	v_mul_f32_e32 v155, 0x3fb8aa3b, v155
	v_exp_f32_e32 v152, v152
	v_exp_f32_e32 v153, v153
	v_exp_f32_e32 v154, v154
	v_exp_f32_e32 v155, v155
	v_add_u32_e32 v138, 48, v175
	v_add_u32_e32 v139, 49, v175
	v_add_u32_e32 v140, 50, v175
	v_add_u32_e32 v141, 51, v175
	v_cmp_gt_u32_e64 s[70:71], s44, v138
	v_cmp_gt_u32_e64 s[72:73], s44, v139
	v_cmp_gt_u32_e64 s[74:75], s44, v140
	v_cmp_gt_u32_e64 s[76:77], s44, v141
	v_cndmask_b32_e64 v152, 0, v152, s[70:71]
	v_cndmask_b32_e64 v153, 0, v153, s[72:73]
	v_cndmask_b32_e64 v154, 0, v154, s[74:75]
	v_cndmask_b32_e64 v155, 0, v155, s[76:77]
	v_add_f32_e32 v132, v132, v152
	v_add_f32_e32 v132, v132, v153
	v_add_f32_e32 v132, v132, v154
	v_add_f32_e32 v132, v132, v155
	v_cvt_pk_bf16_f32 v118, v152, v153
	v_cvt_pk_bf16_f32 v119, v154, v155
	v_min_f32_e32 v152, 0x42a00000, v236
	v_min_f32_e32 v153, 0x42a00000, v237
	v_min_f32_e32 v154, 0x42a00000, v238
	v_min_f32_e32 v155, 0x42a00000, v239
	s_waitcnt vmcnt(4)
	v_mfma_f32_16x16x32_bf16 v[236:239], v[0:3], v[48:51], 0
	v_mfma_f32_16x16x32_bf16 v[236:239], v[4:7], v[52:55], v[236:239]
	v_mul_f32_e32 v152, 0x3fb8aa3b, v152
	v_mul_f32_e32 v153, 0x3fb8aa3b, v153
	v_mul_f32_e32 v154, 0x3fb8aa3b, v154
	v_mul_f32_e32 v155, 0x3fb8aa3b, v155
	v_exp_f32_e32 v152, v152
	v_exp_f32_e32 v153, v153
	v_exp_f32_e32 v154, v154
	v_exp_f32_e32 v155, v155
	v_add_u32_e32 v138, 64, v175
	v_add_u32_e32 v139, 0x41, v175
	v_add_u32_e32 v140, 0x42, v175
	v_add_u32_e32 v141, 0x43, v175
	v_cmp_gt_u32_e64 s[70:71], s44, v138
	v_cmp_gt_u32_e64 s[72:73], s44, v139
	v_cmp_gt_u32_e64 s[74:75], s44, v140
	v_cmp_gt_u32_e64 s[76:77], s44, v141
	v_cndmask_b32_e64 v152, 0, v152, s[70:71]
	v_cndmask_b32_e64 v153, 0, v153, s[72:73]
	v_cndmask_b32_e64 v154, 0, v154, s[74:75]
	v_cndmask_b32_e64 v155, 0, v155, s[76:77]
	v_add_f32_e32 v132, v132, v152
	v_add_f32_e32 v132, v132, v153
	v_add_f32_e32 v132, v132, v154
	v_add_f32_e32 v132, v132, v155
	v_cvt_pk_bf16_f32 v120, v152, v153
	v_cvt_pk_bf16_f32 v121, v154, v155
	v_min_f32_e32 v152, 0x42a00000, v240
	v_min_f32_e32 v153, 0x42a00000, v241
	v_min_f32_e32 v154, 0x42a00000, v242
	v_min_f32_e32 v155, 0x42a00000, v243
	s_waitcnt vmcnt(2)
	v_mfma_f32_16x16x32_bf16 v[240:243], v[8:11], v[48:51], 0
	v_mfma_f32_16x16x32_bf16 v[240:243], v[12:15], v[52:55], v[240:243]
	v_mul_f32_e32 v152, 0x3fb8aa3b, v152
	v_mul_f32_e32 v153, 0x3fb8aa3b, v153
	v_mul_f32_e32 v154, 0x3fb8aa3b, v154
	v_mul_f32_e32 v155, 0x3fb8aa3b, v155
	v_exp_f32_e32 v152, v152
	v_exp_f32_e32 v153, v153
	v_exp_f32_e32 v154, v154
	v_exp_f32_e32 v155, v155
	v_add_u32_e32 v138, 0x50, v175
	v_add_u32_e32 v139, 0x51, v175
	v_add_u32_e32 v140, 0x52, v175
	v_add_u32_e32 v141, 0x53, v175
	v_cmp_gt_u32_e64 s[70:71], s44, v138
	v_cmp_gt_u32_e64 s[72:73], s44, v139
	v_cmp_gt_u32_e64 s[74:75], s44, v140
	v_cmp_gt_u32_e64 s[76:77], s44, v141
	v_cndmask_b32_e64 v152, 0, v152, s[70:71]
	v_cndmask_b32_e64 v153, 0, v153, s[72:73]
	v_cndmask_b32_e64 v154, 0, v154, s[74:75]
	v_cndmask_b32_e64 v155, 0, v155, s[76:77]
	v_add_f32_e32 v132, v132, v152
	v_add_f32_e32 v132, v132, v153
	v_add_f32_e32 v132, v132, v154
	v_add_f32_e32 v132, v132, v155
	v_cvt_pk_bf16_f32 v122, v152, v153
	v_cvt_pk_bf16_f32 v123, v154, v155
	v_min_f32_e32 v152, 0x42a00000, v236
	v_min_f32_e32 v153, 0x42a00000, v237
	v_min_f32_e32 v154, 0x42a00000, v238
	v_min_f32_e32 v155, 0x42a00000, v239
	s_waitcnt vmcnt(0)
	v_mfma_f32_16x16x32_bf16 v[236:239], v[16:19], v[48:51], 0
	v_mfma_f32_16x16x32_bf16 v[236:239], v[20:23], v[52:55], v[236:239]
	v_mul_f32_e32 v152, 0x3fb8aa3b, v152
	v_mul_f32_e32 v153, 0x3fb8aa3b, v153
	v_mul_f32_e32 v154, 0x3fb8aa3b, v154
	v_mul_f32_e32 v155, 0x3fb8aa3b, v155
	v_exp_f32_e32 v152, v152
	v_exp_f32_e32 v153, v153
	v_exp_f32_e32 v154, v154
	v_exp_f32_e32 v155, v155
	v_add_u32_e32 v138, 0x60, v175
	v_add_u32_e32 v139, 0x61, v175
	v_add_u32_e32 v140, 0x62, v175
	v_add_u32_e32 v141, 0x63, v175
	v_cmp_gt_u32_e64 s[70:71], s44, v138
	v_cmp_gt_u32_e64 s[72:73], s44, v139
	v_cmp_gt_u32_e64 s[74:75], s44, v140
	v_cmp_gt_u32_e64 s[76:77], s44, v141
	v_cndmask_b32_e64 v152, 0, v152, s[70:71]
	v_cndmask_b32_e64 v153, 0, v153, s[72:73]
	v_cndmask_b32_e64 v154, 0, v154, s[74:75]
	v_cndmask_b32_e64 v155, 0, v155, s[76:77]
	v_add_f32_e32 v132, v132, v152
	v_add_f32_e32 v132, v132, v153
	v_add_f32_e32 v132, v132, v154
	v_add_f32_e32 v132, v132, v155
	v_cvt_pk_bf16_f32 v124, v152, v153
	v_cvt_pk_bf16_f32 v125, v154, v155
	v_min_f32_e32 v152, 0x42a00000, v240
	v_min_f32_e32 v153, 0x42a00000, v241
	v_min_f32_e32 v154, 0x42a00000, v242
	v_min_f32_e32 v155, 0x42a00000, v243
	v_mul_f32_e32 v152, 0x3fb8aa3b, v152
	v_mul_f32_e32 v153, 0x3fb8aa3b, v153
	v_mul_f32_e32 v154, 0x3fb8aa3b, v154
	v_mul_f32_e32 v155, 0x3fb8aa3b, v155
	v_exp_f32_e32 v152, v152
	v_exp_f32_e32 v153, v153
	v_exp_f32_e32 v154, v154
	v_exp_f32_e32 v155, v155
	v_add_u32_e32 v138, 0x70, v175
	v_add_u32_e32 v139, 0x71, v175
	v_add_u32_e32 v140, 0x72, v175
	v_add_u32_e32 v141, 0x73, v175
	v_cmp_gt_u32_e64 s[70:71], s44, v138
	v_cmp_gt_u32_e64 s[72:73], s44, v139
	v_cmp_gt_u32_e64 s[74:75], s44, v140
	v_cmp_gt_u32_e64 s[76:77], s44, v141
	v_cndmask_b32_e64 v152, 0, v152, s[70:71]
	v_cndmask_b32_e64 v153, 0, v153, s[72:73]
	v_cndmask_b32_e64 v154, 0, v154, s[74:75]
	v_cndmask_b32_e64 v155, 0, v155, s[76:77]
	v_add_f32_e32 v132, v132, v152
	v_add_f32_e32 v132, v132, v153
	v_add_f32_e32 v132, v132, v154
	v_add_f32_e32 v132, v132, v155
	v_cvt_pk_bf16_f32 v126, v152, v153
	v_cvt_pk_bf16_f32 v127, v154, v155
	v_min_f32_e32 v152, 0x42a00000, v236
	v_min_f32_e32 v153, 0x42a00000, v237
	v_min_f32_e32 v154, 0x42a00000, v238
	v_min_f32_e32 v155, 0x42a00000, v239
	v_mul_f32_e32 v152, 0x3fb8aa3b, v152
	v_mul_f32_e32 v153, 0x3fb8aa3b, v153
	v_mul_f32_e32 v154, 0x3fb8aa3b, v154
	v_mul_f32_e32 v155, 0x3fb8aa3b, v155
	v_exp_f32_e32 v152, v152
	v_exp_f32_e32 v153, v153
	v_exp_f32_e32 v154, v154
	v_exp_f32_e32 v155, v155
	v_add_u32_e32 v138, 0x80, v175
	v_add_u32_e32 v139, 0x81, v175
	v_add_u32_e32 v140, 0x82, v175
	v_add_u32_e32 v141, 0x83, v175
	v_cmp_gt_u32_e64 s[70:71], s44, v138
	v_cmp_gt_u32_e64 s[72:73], s44, v139
	v_cmp_gt_u32_e64 s[74:75], s44, v140
	v_cmp_gt_u32_e64 s[76:77], s44, v141
	v_cndmask_b32_e64 v152, 0, v152, s[62:63]
	v_cndmask_b32_e64 v153, 0, v153, s[64:65]
	v_cndmask_b32_e64 v154, 0, v154, s[66:67]
	v_cndmask_b32_e64 v155, 0, v155, s[68:69]
	v_cndmask_b32_e64 v152, 0, v152, s[70:71]
	v_cndmask_b32_e64 v153, 0, v153, s[72:73]
	v_cndmask_b32_e64 v154, 0, v154, s[74:75]
	v_cndmask_b32_e64 v155, 0, v155, s[76:77]
	v_add_f32_e32 v132, v132, v152
	v_add_f32_e32 v132, v132, v153
	v_add_f32_e32 v132, v132, v154
	v_add_f32_e32 v132, v132, v155
	v_cvt_pk_bf16_f32 v128, v152, v153
	v_cvt_pk_bf16_f32 v129, v154, v155
	v_add_u32_e32 v134, s42, v160
	v_lshlrev_b32_e32 v134, 4, v134
	v_add_u32_e32 v134, s43, v134
	v_subrev_u32_e32 v135, s15, v134
	v_lshrrev_b32_e32 v136, 4, v135
	v_add_u32_e32 v136, v136, v135
	v_mad_u32_u24 v176, v136, s79, v161
	v_lshl_add_u32 v177, v135, 2, s80
	s_sub_i32 s2, s42, 64
	v_add_u32_e32 v178, s2, v169
	v_and_b32_e32 v135, 3, v134
	v_lshlrev_b32_e32 v135, s13, v135
	v_lshrrev_b32_e32 v136, 2, v134
	v_add_u32_e32 v135, v135, v136
	v_lshl_add_u32 v135, v135, 7, v161
	global_load_dwordx4 v[48:51], v135, s[18:19]
	global_load_dwordx4 v[52:55], v135, s[18:19] offset:64
	v_subrev_u32_e32 v134, 0x400, v134
	v_and_b32_e32 v137, 3, v134
	v_lshlrev_b32_e32 v137, s13, v137
	v_bfe_u32 v135, v134, 2, 2
	v_add_u32_e32 v137, v137, v135
	v_lshl_add_u32 v183, v137, 7, v161
	v_ashrrev_i32_e32 v252, 4, v134
	v_med3_i32 v136, v252, 0, s14
	v_lshl_add_u32 v136, v136, 9, v183
	global_load_dwordx4 v[0:3], v136, s[20:21]
	global_load_dwordx4 v[4:7], v136, s[20:21] offset:64
	v_add_u32_e32 v135, 16, v252
	v_med3_i32 v135, v135, 0, s14
	v_lshl_add_u32 v135, v135, 9, v183
	global_load_dwordx4 v[8:11], v135, s[20:21]
	global_load_dwordx4 v[12:15], v135, s[20:21] offset:64
	v_add_u32_e32 v136, 32, v252
	v_med3_i32 v136, v136, 0, s14
	v_lshl_add_u32 v136, v136, 9, v183
	global_load_dwordx4 v[16:19], v136, s[20:21]
	global_load_dwordx4 v[20:23], v136, s[20:21] offset:64
	v_add_u32_e32 v135, 48, v252
	v_med3_i32 v135, v135, 0, s14
	v_lshl_add_u32 v135, v135, 9, v183
	global_load_dwordx4 v[24:27], v135, s[20:21]
	global_load_dwordx4 v[28:31], v135, s[20:21] offset:64
	v_add_u32_e32 v136, 64, v252
	v_med3_i32 v136, v136, 0, s14
	v_lshl_add_u32 v136, v136, 9, v183
	global_load_dwordx4 v[32:35], v136, s[20:21]
	global_load_dwordx4 v[36:39], v136, s[20:21] offset:64
	v_add_u32_e32 v135, 0x50, v252
	v_med3_i32 v135, v135, 0, s14
	v_lshl_add_u32 v135, v135, 9, v183
	global_load_dwordx4 v[40:43], v135, s[20:21]
	global_load_dwordx4 v[44:47], v135, s[20:21] offset:64
	ds_bpermute_b32 v142, v167, v132
	s_waitcnt lgkmcnt(0)
	v_add_f32_e32 v132, v132, v142
	ds_bpermute_b32 v142, v168, v132
	s_waitcnt lgkmcnt(0)
	v_add_f32_e32 v132, v132, v142
	s_waitcnt vmcnt(14)
	ds_write_b128 v165, v[64:67]
	ds_write_b128 v165, v[68:71] offset:1152
	ds_write_b128 v165, v[72:75] offset:2304
	ds_write_b128 v165, v[76:79] offset:3456
	s_waitcnt lgkmcnt(0)
	ds_read_b64_tr_b16 v[236:237], v166
	ds_read_b64_tr_b16 v[238:239], v166 offset:2304
	ds_read_b64_tr_b16 v[240:241], v166 offset:32
	ds_read_b64_tr_b16 v[242:243], v166 offset:2336
	ds_read_b64_tr_b16 v[244:245], v166 offset:64
	ds_read_b64_tr_b16 v[246:247], v166 offset:2368
	ds_read_b64_tr_b16 v[248:249], v166 offset:96
	ds_read_b64_tr_b16 v[250:251], v166 offset:2400
	s_waitcnt lgkmcnt(0)
	s_add_i32 s2, s40, 32
	v_add_u32_e32 v138, s2, v164
	v_lshlrev_b32_e32 v138, 4, v138
	v_add_u32_e32 v138, s41, v138
	v_and_b32_e32 v139, 3, v138
	v_lshlrev_b32_e32 v139, s39, v139
	v_bfe_u32 v140, v138, 2, 2
	v_add_u32_e32 v139, v139, v140
	v_lshl_add_u32 v139, v139, 7, v162
	v_ashrrev_i32_e32 v138, 4, v138
	v_med3_i32 v138, v138, 0, s38
	v_lshl_add_u32 v138, v138, 9, v139
	global_load_dwordx4 v[64:67], v138, s[26:27]
	s_add_i32 s2, s40, 40
	v_add_u32_e32 v138, s2, v164
	v_lshlrev_b32_e32 v138, 4, v138
	v_add_u32_e32 v138, s41, v138
	v_and_b32_e32 v139, 3, v138
	v_lshlrev_b32_e32 v139, s39, v139
	v_bfe_u32 v140, v138, 2, 2
	v_add_u32_e32 v139, v139, v140
	v_lshl_add_u32 v139, v139, 7, v162
	v_ashrrev_i32_e32 v138, 4, v138
	v_med3_i32 v138, v138, 0, s38
	v_lshl_add_u32 v138, v138, 9, v139
	global_load_dwordx4 v[68:71], v138, s[26:27]
	s_add_i32 s2, s40, 48
	v_add_u32_e32 v138, s2, v164
	v_lshlrev_b32_e32 v138, 4, v138
	v_add_u32_e32 v138, s41, v138
	v_and_b32_e32 v139, 3, v138
	v_lshlrev_b32_e32 v139, s39, v139
	v_bfe_u32 v140, v138, 2, 2
	v_add_u32_e32 v139, v139, v140
	v_lshl_add_u32 v139, v139, 7, v162
	v_ashrrev_i32_e32 v138, 4, v138
	v_med3_i32 v138, v138, 0, s38
	v_lshl_add_u32 v138, v138, 9, v139
	global_load_dwordx4 v[72:75], v138, s[26:27]
	s_add_i32 s2, s40, 56
	v_add_u32_e32 v138, s2, v164
	v_lshlrev_b32_e32 v138, 4, v138
	v_add_u32_e32 v138, s41, v138
	v_and_b32_e32 v139, 3, v138
	v_lshlrev_b32_e32 v139, s39, v139
	v_bfe_u32 v140, v138, 2, 2
	v_add_u32_e32 v139, v139, v140
	v_lshl_add_u32 v139, v139, 7, v162
	v_ashrrev_i32_e32 v138, 4, v138
	v_med3_i32 v138, v138, 0, s38
	v_lshl_add_u32 v138, v138, 9, v139
	global_load_dwordx4 v[76:79], v138, s[26:27]
	ds_write_b128 v165, v[80:83]
	ds_write_b128 v165, v[84:87] offset:1152
	ds_write_b128 v165, v[88:91] offset:2304
	ds_write_b128 v165, v[92:95] offset:3456
	v_mfma_f32_16x16x32_bf16 v[204:207], v[236:239], v[112:115], 0
	v_mfma_f32_16x16x32_bf16 v[208:211], v[240:243], v[112:115], 0
	v_mfma_f32_16x16x32_bf16 v[212:215], v[244:247], v[112:115], 0
	v_mfma_f32_16x16x32_bf16 v[216:219], v[248:251], v[112:115], 0
	s_waitcnt lgkmcnt(0)
	ds_read_b64_tr_b16 v[236:237], v166
	ds_read_b64_tr_b16 v[238:239], v166 offset:2304
	ds_read_b64_tr_b16 v[240:241], v166 offset:32
	ds_read_b64_tr_b16 v[242:243], v166 offset:2336
	ds_read_b64_tr_b16 v[244:245], v166 offset:64
	ds_read_b64_tr_b16 v[246:247], v166 offset:2368
	ds_read_b64_tr_b16 v[248:249], v166 offset:96
	ds_read_b64_tr_b16 v[250:251], v166 offset:2400
	s_waitcnt lgkmcnt(0)
	s_add_i32 s2, s40, 64
	v_add_u32_e32 v138, s2, v164
	v_lshlrev_b32_e32 v138, 4, v138
	v_add_u32_e32 v138, s41, v138
	v_and_b32_e32 v139, 3, v138
	v_lshlrev_b32_e32 v139, s39, v139
	v_bfe_u32 v140, v138, 2, 2
	v_add_u32_e32 v139, v139, v140
	v_lshl_add_u32 v139, v139, 7, v162
	v_ashrrev_i32_e32 v138, 4, v138
	v_med3_i32 v138, v138, 0, s38
	v_lshl_add_u32 v138, v138, 9, v139
	global_load_dwordx4 v[80:83], v138, s[26:27]
	s_add_i32 s2, s40, 72
	v_add_u32_e32 v138, s2, v164
	v_lshlrev_b32_e32 v138, 4, v138
	v_add_u32_e32 v138, s41, v138
	v_and_b32_e32 v139, 3, v138
	v_lshlrev_b32_e32 v139, s39, v139
	v_bfe_u32 v140, v138, 2, 2
	v_add_u32_e32 v139, v139, v140
	v_lshl_add_u32 v139, v139, 7, v162
	v_ashrrev_i32_e32 v138, 4, v138
	v_med3_i32 v138, v138, 0, s38
	v_lshl_add_u32 v138, v138, 9, v139
	global_load_dwordx4 v[84:87], v138, s[26:27]
	ds_write_b128 v165, v[96:99]
	ds_write_b128 v165, v[100:103] offset:1152
	ds_write_b128 v165, v[104:107] offset:2304
	ds_write_b128 v165, v[108:111] offset:3456
	v_mfma_f32_16x16x32_bf16 v[204:207], v[236:239], v[116:119], v[204:207]
	v_mfma_f32_16x16x32_bf16 v[208:211], v[240:243], v[116:119], v[208:211]
	v_mfma_f32_16x16x32_bf16 v[212:215], v[244:247], v[116:119], v[212:215]
	v_mfma_f32_16x16x32_bf16 v[216:219], v[248:251], v[116:119], v[216:219]
	s_waitcnt lgkmcnt(0)
	ds_read_b64_tr_b16 v[236:237], v166
	ds_read_b64_tr_b16 v[238:239], v166 offset:2304
	ds_read_b64_tr_b16 v[240:241], v166 offset:32
	ds_read_b64_tr_b16 v[242:243], v166 offset:2336
	ds_read_b64_tr_b16 v[244:245], v166 offset:64
	ds_read_b64_tr_b16 v[246:247], v166 offset:2368
	ds_read_b64_tr_b16 v[248:249], v166 offset:96
	ds_read_b64_tr_b16 v[250:251], v166 offset:2400
	s_waitcnt lgkmcnt(0)
	s_waitcnt vmcnt(2)
	ds_write_b128 v165, v[64:67]
	ds_write_b128 v165, v[68:71] offset:1152
	ds_write_b128 v165, v[72:75] offset:2304
	ds_write_b128 v165, v[76:79] offset:3456
	v_mfma_f32_16x16x32_bf16 v[204:207], v[236:239], v[120:123], v[204:207]
	v_mfma_f32_16x16x32_bf16 v[208:211], v[240:243], v[120:123], v[208:211]
	v_mfma_f32_16x16x32_bf16 v[212:215], v[244:247], v[120:123], v[212:215]
	v_mfma_f32_16x16x32_bf16 v[216:219], v[248:251], v[120:123], v[216:219]
	s_waitcnt lgkmcnt(0)
	ds_read_b64_tr_b16 v[236:237], v166
	ds_read_b64_tr_b16 v[238:239], v166 offset:2304
	ds_read_b64_tr_b16 v[240:241], v166 offset:32
	ds_read_b64_tr_b16 v[242:243], v166 offset:2336
	ds_read_b64_tr_b16 v[244:245], v166 offset:64
	ds_read_b64_tr_b16 v[246:247], v166 offset:2368
	ds_read_b64_tr_b16 v[248:249], v166 offset:96
	ds_read_b64_tr_b16 v[250:251], v166 offset:2400
	s_waitcnt lgkmcnt(0)
	s_waitcnt vmcnt(0)
	ds_write_b128 v165, v[80:83]
	ds_write_b128 v165, v[84:87] offset:1152
	v_mfma_f32_16x16x32_bf16 v[204:207], v[236:239], v[124:127], v[204:207]
	v_mfma_f32_16x16x32_bf16 v[208:211], v[240:243], v[124:127], v[208:211]
	v_mfma_f32_16x16x32_bf16 v[212:215], v[244:247], v[124:127], v[212:215]
	v_mfma_f32_16x16x32_bf16 v[216:219], v[248:251], v[124:127], v[216:219]
	s_waitcnt lgkmcnt(0)
	ds_read_b64_tr_b16 v[236:237], v166
	ds_read_b64_tr_b16 v[238:239], v166 offset:2304
	ds_read_b64_tr_b16 v[240:241], v166 offset:32
	ds_read_b64_tr_b16 v[242:243], v166 offset:2336
	ds_read_b64_tr_b16 v[244:245], v166 offset:64
	ds_read_b64_tr_b16 v[246:247], v166 offset:2368
	ds_read_b64_tr_b16 v[248:249], v166 offset:96
	ds_read_b64_tr_b16 v[250:251], v166 offset:2400
	s_waitcnt lgkmcnt(0)
	v_mfma_f32_16x16x32_bf16 v[204:207], v[236:239], v[128:131], v[204:207]
	v_mfma_f32_16x16x32_bf16 v[208:211], v[240:243], v[128:131], v[208:211]
	v_mfma_f32_16x16x32_bf16 v[212:215], v[244:247], v[128:131], v[212:215]
	v_mfma_f32_16x16x32_bf16 v[216:219], v[248:251], v[128:131], v[216:219]
	s_add_i32 s2, s42, -64
	v_add_u32_e32 v138, s2, v164
	v_lshlrev_b32_e32 v138, 4, v138
	v_add_u32_e32 v138, s43, v138
	v_and_b32_e32 v139, 3, v138
	v_lshlrev_b32_e32 v139, s13, v139
	v_bfe_u32 v140, v138, 2, 2
	v_add_u32_e32 v139, v139, v140
	v_lshl_add_u32 v139, v139, 7, v162
	v_ashrrev_i32_e32 v138, 4, v138
	v_med3_i32 v138, v138, 0, s14
	v_lshl_add_u32 v138, v138, 9, v139
	global_load_dwordx4 v[64:67], v138, s[22:23]
	s_add_i32 s2, s42, -56
	v_add_u32_e32 v138, s2, v164
	v_lshlrev_b32_e32 v138, 4, v138
	v_add_u32_e32 v138, s43, v138
	v_and_b32_e32 v139, 3, v138
	v_lshlrev_b32_e32 v139, s13, v139
	v_bfe_u32 v140, v138, 2, 2
	v_add_u32_e32 v139, v139, v140
	v_lshl_add_u32 v139, v139, 7, v162
	v_ashrrev_i32_e32 v138, 4, v138
	v_med3_i32 v138, v138, 0, s14
	v_lshl_add_u32 v138, v138, 9, v139
	global_load_dwordx4 v[68:71], v138, s[22:23]
	s_add_i32 s2, s42, -48
	v_add_u32_e32 v138, s2, v164
	v_lshlrev_b32_e32 v138, 4, v138
	v_add_u32_e32 v138, s43, v138
	v_and_b32_e32 v139, 3, v138
	v_lshlrev_b32_e32 v139, s13, v139
	v_bfe_u32 v140, v138, 2, 2
	v_add_u32_e32 v139, v139, v140
	v_lshl_add_u32 v139, v139, 7, v162
	v_ashrrev_i32_e32 v138, 4, v138
	v_med3_i32 v138, v138, 0, s14
	v_lshl_add_u32 v138, v138, 9, v139
	global_load_dwordx4 v[72:75], v138, s[22:23]
	s_add_i32 s2, s42, -40
	v_add_u32_e32 v138, s2, v164
	v_lshlrev_b32_e32 v138, 4, v138
	v_add_u32_e32 v138, s43, v138
	v_and_b32_e32 v139, 3, v138
	v_lshlrev_b32_e32 v139, s13, v139
	v_bfe_u32 v140, v138, 2, 2
	v_add_u32_e32 v139, v139, v140
	v_lshl_add_u32 v139, v139, 7, v162
	v_ashrrev_i32_e32 v138, 4, v138
	v_med3_i32 v138, v138, 0, s14
	v_lshl_add_u32 v138, v138, 9, v139
	global_load_dwordx4 v[76:79], v138, s[22:23]
	s_add_i32 s2, s42, -32
	v_add_u32_e32 v138, s2, v164
	v_lshlrev_b32_e32 v138, 4, v138
	v_add_u32_e32 v138, s43, v138
	v_and_b32_e32 v139, 3, v138
	v_lshlrev_b32_e32 v139, s13, v139
	v_bfe_u32 v140, v138, 2, 2
	v_add_u32_e32 v139, v139, v140
	v_lshl_add_u32 v139, v139, 7, v162
	v_ashrrev_i32_e32 v138, 4, v138
	v_med3_i32 v138, v138, 0, s14
	v_lshl_add_u32 v138, v138, 9, v139
	global_load_dwordx4 v[80:83], v138, s[22:23]
	s_add_i32 s2, s42, -24
	v_add_u32_e32 v138, s2, v164
	v_lshlrev_b32_e32 v138, 4, v138
	v_add_u32_e32 v138, s43, v138
	v_and_b32_e32 v139, 3, v138
	v_lshlrev_b32_e32 v139, s13, v139
	v_bfe_u32 v140, v138, 2, 2
	v_add_u32_e32 v139, v139, v140
	v_lshl_add_u32 v139, v139, 7, v162
	v_ashrrev_i32_e32 v138, 4, v138
	v_med3_i32 v138, v138, 0, s14
	v_lshl_add_u32 v138, v138, 9, v139
	global_load_dwordx4 v[84:87], v138, s[22:23]
	s_add_i32 s2, s42, -16
	v_add_u32_e32 v138, s2, v164
	v_lshlrev_b32_e32 v138, 4, v138
	v_add_u32_e32 v138, s43, v138
	v_and_b32_e32 v139, 3, v138
	v_lshlrev_b32_e32 v139, s13, v139
	v_bfe_u32 v140, v138, 2, 2
	v_add_u32_e32 v139, v139, v140
	v_lshl_add_u32 v139, v139, 7, v162
	v_ashrrev_i32_e32 v138, 4, v138
	v_med3_i32 v138, v138, 0, s14
	v_lshl_add_u32 v138, v138, 9, v139
	global_load_dwordx4 v[88:91], v138, s[22:23]
	s_add_i32 s2, s42, -8
	v_add_u32_e32 v138, s2, v164
	v_lshlrev_b32_e32 v138, 4, v138
	v_add_u32_e32 v138, s43, v138
	v_and_b32_e32 v139, 3, v138
	v_lshlrev_b32_e32 v139, s13, v139
	v_bfe_u32 v140, v138, 2, 2
	v_add_u32_e32 v139, v139, v140
	v_lshl_add_u32 v139, v139, 7, v162
	v_ashrrev_i32_e32 v138, 4, v138
	v_med3_i32 v138, v138, 0, s14
	v_lshl_add_u32 v138, v138, 9, v139
	global_load_dwordx4 v[92:95], v138, s[22:23]
	s_add_i32 s2, s42, 0
	v_add_u32_e32 v138, s2, v164
	v_lshlrev_b32_e32 v138, 4, v138
	v_add_u32_e32 v138, s43, v138
	v_and_b32_e32 v139, 3, v138
	v_lshlrev_b32_e32 v139, s13, v139
	v_bfe_u32 v140, v138, 2, 2
	v_add_u32_e32 v139, v139, v140
	v_lshl_add_u32 v139, v139, 7, v162
	v_ashrrev_i32_e32 v138, 4, v138
	v_med3_i32 v138, v138, 0, s14
	v_lshl_add_u32 v138, v138, 9, v139
	global_load_dwordx4 v[96:99], v138, s[22:23]
	s_add_i32 s2, s42, 8
	v_add_u32_e32 v138, s2, v164
	v_lshlrev_b32_e32 v138, 4, v138
	v_add_u32_e32 v138, s43, v138
	v_and_b32_e32 v139, 3, v138
	v_lshlrev_b32_e32 v139, s13, v139
	v_bfe_u32 v140, v138, 2, 2
	v_add_u32_e32 v139, v139, v140
	v_lshl_add_u32 v139, v139, 7, v162
	v_ashrrev_i32_e32 v138, 4, v138
	v_med3_i32 v138, v138, 0, s14
	v_lshl_add_u32 v138, v138, 9, v139
	global_load_dwordx4 v[100:103], v138, s[22:23]
	s_add_i32 s2, s42, 16
	v_add_u32_e32 v138, s2, v164
	v_lshlrev_b32_e32 v138, 4, v138
	v_add_u32_e32 v138, s43, v138
	v_and_b32_e32 v139, 3, v138
	v_lshlrev_b32_e32 v139, s13, v139
	v_bfe_u32 v140, v138, 2, 2
	v_add_u32_e32 v139, v139, v140
	v_lshl_add_u32 v139, v139, 7, v162
	v_ashrrev_i32_e32 v138, 4, v138
	v_med3_i32 v138, v138, 0, s14
	v_lshl_add_u32 v138, v138, 9, v139
	global_load_dwordx4 v[104:107], v138, s[22:23]
	s_add_i32 s2, s42, 24
	v_add_u32_e32 v138, s2, v164
	v_lshlrev_b32_e32 v138, 4, v138
	v_add_u32_e32 v138, s43, v138
	v_and_b32_e32 v139, 3, v138
	v_lshlrev_b32_e32 v139, s13, v139
	v_bfe_u32 v140, v138, 2, 2
	v_add_u32_e32 v139, v139, v140
	v_lshl_add_u32 v139, v139, 7, v162
	v_ashrrev_i32_e32 v138, 4, v138
	v_med3_i32 v138, v138, 0, s14
	v_lshl_add_u32 v138, v138, 9, v139
	global_load_dwordx4 v[108:111], v138, s[22:23]
	ds_read_b128 v[236:239], v173 offset:0
	ds_read_b128 v[240:243], v173 offset:64
	ds_read_b128 v[244:247], v173 offset:128
	ds_read_b128 v[248:251], v173 offset:192
	ds_read_b32 v142, v174 offset:0
	s_waitcnt lgkmcnt(0)
	v_add_f32_e32 v204, v236, v204
	v_add_f32_e32 v205, v237, v205
	v_add_f32_e32 v206, v238, v206
	v_add_f32_e32 v207, v239, v207
	v_add_f32_e32 v208, v240, v208
	v_add_f32_e32 v209, v241, v209
	v_add_f32_e32 v210, v242, v210
	v_add_f32_e32 v211, v243, v211
	v_add_f32_e32 v212, v244, v212
	v_add_f32_e32 v213, v245, v213
	v_add_f32_e32 v214, v246, v214
	v_add_f32_e32 v215, v247, v215
	v_add_f32_e32 v216, v248, v216
	v_add_f32_e32 v217, v249, v217
	v_add_f32_e32 v218, v250, v218
	v_add_f32_e32 v219, v251, v219
	v_add_f32_e32 v132, v142, v132
	ds_write_b128 v173, v[204:207] offset:0
	ds_write_b128 v173, v[208:211] offset:64
	ds_write_b128 v173, v[212:215] offset:128
	ds_write_b128 v173, v[216:219] offset:192
	ds_write_b32 v174, v132 offset:0
	s_mov_b32 s40, s42
	s_mov_b32 s41, s43
	v_mov_b32_e32 v173, v176
	v_mov_b32_e32 v174, v177
	v_mov_b32_e32 v175, v178
	v_mov_b32_e32 v179, v183
	v_mov_b32_e32 v182, v252
	s_lshr_b32 s44, s33, 4
	s_add_i32 s45, s10, s8
	s_cmp_lt_u32 s45, 0x800
	s_cbranch_scc1 .Latt_newunit
	s_mov_b32 s37, 1
	s_branch .Latt_ud_done

.Latt_ud_done:
	s_lshl_b32 s2, s0, 5
	s_add_i32 s42, s15, s2
	s_mov_b32 s43, 0
	s_waitcnt vmcnt(12)
	v_mov_b32_e32 v132, 0
	v_mfma_f32_16x16x32_bf16 v[236:239], v[0:3], v[48:51], 0
	v_mfma_f32_16x16x32_bf16 v[236:239], v[4:7], v[52:55], v[236:239]
	v_mfma_f32_16x16x32_bf16 v[240:243], v[8:11], v[48:51], 0
	v_mfma_f32_16x16x32_bf16 v[240:243], v[12:15], v[52:55], v[240:243]
	s_nop 7
	v_min_f32_e32 v152, 0x42a00000, v236
	v_min_f32_e32 v153, 0x42a00000, v237
	v_min_f32_e32 v154, 0x42a00000, v238
	v_min_f32_e32 v155, 0x42a00000, v239
	v_mfma_f32_16x16x32_bf16 v[236:239], v[16:19], v[48:51], 0
	v_mfma_f32_16x16x32_bf16 v[236:239], v[20:23], v[52:55], v[236:239]
	v_add_u32_e32 v136, 0x60, v182
	v_med3_i32 v136, v136, 0, s38
	v_lshl_add_u32 v136, v136, 9, v179
	global_load_dwordx4 v[0:3], v136, s[24:25]
	global_load_dwordx4 v[4:7], v136, s[24:25] offset:64
	v_mul_f32_e32 v152, 0x3fb8aa3b, v152
	v_mul_f32_e32 v153, 0x3fb8aa3b, v153
	v_mul_f32_e32 v154, 0x3fb8aa3b, v154
	v_mul_f32_e32 v155, 0x3fb8aa3b, v155
	v_exp_f32_e32 v152, v152
	v_exp_f32_e32 v153, v153
	v_exp_f32_e32 v154, v154
	v_exp_f32_e32 v155, v155
	v_add_u32_e32 v138, 0, v175
	v_add_u32_e32 v139, 1, v175
	v_add_u32_e32 v140, 2, v175
	v_add_u32_e32 v141, 3, v175
	v_cmp_gt_u32_e64 s[70:71], s44, v138
	v_cmp_gt_u32_e64 s[72:73], s44, v139
	v_cmp_gt_u32_e64 s[74:75], s44, v140
	v_cmp_gt_u32_e64 s[76:77], s44, v141
	v_cndmask_b32_e64 v152, 0, v152, s[54:55]
	v_cndmask_b32_e64 v153, 0, v153, s[56:57]
	v_cndmask_b32_e64 v154, 0, v154, s[58:59]
	v_cndmask_b32_e64 v155, 0, v155, s[60:61]
	v_cndmask_b32_e64 v152, 0, v152, s[70:71]
	v_cndmask_b32_e64 v153, 0, v153, s[72:73]
	v_cndmask_b32_e64 v154, 0, v154, s[74:75]
	v_cndmask_b32_e64 v155, 0, v155, s[76:77]
	v_add_f32_e32 v132, v132, v152
	v_add_f32_e32 v132, v132, v153
	v_add_f32_e32 v132, v132, v154
	v_add_f32_e32 v132, v132, v155
	v_cvt_pk_bf16_f32 v112, v152, v153
	v_cvt_pk_bf16_f32 v113, v154, v155
	v_min_f32_e32 v152, 0x42a00000, v240
	v_min_f32_e32 v153, 0x42a00000, v241
	v_min_f32_e32 v154, 0x42a00000, v242
	v_min_f32_e32 v155, 0x42a00000, v243
	v_mfma_f32_16x16x32_bf16 v[240:243], v[24:27], v[48:51], 0
	v_mfma_f32_16x16x32_bf16 v[240:243], v[28:31], v[52:55], v[240:243]
	v_add_u32_e32 v135, 0x70, v182
	v_med3_i32 v135, v135, 0, s38
	v_lshl_add_u32 v135, v135, 9, v179
	global_load_dwordx4 v[8:11], v135, s[24:25]
	global_load_dwordx4 v[12:15], v135, s[24:25] offset:64
	v_mul_f32_e32 v152, 0x3fb8aa3b, v152
	v_mul_f32_e32 v153, 0x3fb8aa3b, v153
	v_mul_f32_e32 v154, 0x3fb8aa3b, v154
	v_mul_f32_e32 v155, 0x3fb8aa3b, v155
	v_exp_f32_e32 v152, v152
	v_exp_f32_e32 v153, v153
	v_exp_f32_e32 v154, v154
	v_exp_f32_e32 v155, v155
	v_add_u32_e32 v138, 16, v175
	v_add_u32_e32 v139, 17, v175
	v_add_u32_e32 v140, 18, v175
	v_add_u32_e32 v141, 19, v175
	v_cmp_gt_u32_e64 s[70:71], s44, v138
	v_cmp_gt_u32_e64 s[72:73], s44, v139
	v_cmp_gt_u32_e64 s[74:75], s44, v140
	v_cmp_gt_u32_e64 s[76:77], s44, v141
	v_cndmask_b32_e64 v152, 0, v152, s[70:71]
	v_cndmask_b32_e64 v153, 0, v153, s[72:73]
	v_cndmask_b32_e64 v154, 0, v154, s[74:75]
	v_cndmask_b32_e64 v155, 0, v155, s[76:77]
	v_add_f32_e32 v132, v132, v152
	v_add_f32_e32 v132, v132, v153
	v_add_f32_e32 v132, v132, v154
	v_add_f32_e32 v132, v132, v155
	v_cvt_pk_bf16_f32 v114, v152, v153
	v_cvt_pk_bf16_f32 v115, v154, v155
	v_min_f32_e32 v152, 0x42a00000, v236
	v_min_f32_e32 v153, 0x42a00000, v237
	v_min_f32_e32 v154, 0x42a00000, v238
	v_min_f32_e32 v155, 0x42a00000, v239
	v_mfma_f32_16x16x32_bf16 v[236:239], v[32:35], v[48:51], 0
	v_mfma_f32_16x16x32_bf16 v[236:239], v[36:39], v[52:55], v[236:239]
	v_add_u32_e32 v136, 0x80, v182
	v_med3_i32 v136, v136, 0, s38
	v_lshl_add_u32 v136, v136, 9, v179
	global_load_dwordx4 v[16:19], v136, s[24:25]
	global_load_dwordx4 v[20:23], v136, s[24:25] offset:64
	v_mul_f32_e32 v152, 0x3fb8aa3b, v152
	v_mul_f32_e32 v153, 0x3fb8aa3b, v153
	v_mul_f32_e32 v154, 0x3fb8aa3b, v154
	v_mul_f32_e32 v155, 0x3fb8aa3b, v155
	v_exp_f32_e32 v152, v152
	v_exp_f32_e32 v153, v153
	v_exp_f32_e32 v154, v154
	v_exp_f32_e32 v155, v155
	v_add_u32_e32 v138, 32, v175
	v_add_u32_e32 v139, 33, v175
	v_add_u32_e32 v140, 34, v175
	v_add_u32_e32 v141, 35, v175
	v_cmp_gt_u32_e64 s[70:71], s44, v138
	v_cmp_gt_u32_e64 s[72:73], s44, v139
	v_cmp_gt_u32_e64 s[74:75], s44, v140
	v_cmp_gt_u32_e64 s[76:77], s44, v141
	v_cndmask_b32_e64 v152, 0, v152, s[70:71]
	v_cndmask_b32_e64 v153, 0, v153, s[72:73]
	v_cndmask_b32_e64 v154, 0, v154, s[74:75]
	v_cndmask_b32_e64 v155, 0, v155, s[76:77]
	v_add_f32_e32 v132, v132, v152
	v_add_f32_e32 v132, v132, v153
	v_add_f32_e32 v132, v132, v154
	v_add_f32_e32 v132, v132, v155
	v_cvt_pk_bf16_f32 v116, v152, v153
	v_cvt_pk_bf16_f32 v117, v154, v155
	v_min_f32_e32 v152, 0x42a00000, v240
	v_min_f32_e32 v153, 0x42a00000, v241
	v_min_f32_e32 v154, 0x42a00000, v242
	v_min_f32_e32 v155, 0x42a00000, v243
	v_mfma_f32_16x16x32_bf16 v[240:243], v[40:43], v[48:51], 0
	v_mfma_f32_16x16x32_bf16 v[240:243], v[44:47], v[52:55], v[240:243]
	v_mul_f32_e32 v152, 0x3fb8aa3b, v152
	v_mul_f32_e32 v153, 0x3fb8aa3b, v153
	v_mul_f32_e32 v154, 0x3fb8aa3b, v154
	v_mul_f32_e32 v155, 0x3fb8aa3b, v155
	v_exp_f32_e32 v152, v152
	v_exp_f32_e32 v153, v153
	v_exp_f32_e32 v154, v154
	v_exp_f32_e32 v155, v155
	v_add_u32_e32 v138, 48, v175
	v_add_u32_e32 v139, 49, v175
	v_add_u32_e32 v140, 50, v175
	v_add_u32_e32 v141, 51, v175
	v_cmp_gt_u32_e64 s[70:71], s44, v138
	v_cmp_gt_u32_e64 s[72:73], s44, v139
	v_cmp_gt_u32_e64 s[74:75], s44, v140
	v_cmp_gt_u32_e64 s[76:77], s44, v141
	v_cndmask_b32_e64 v152, 0, v152, s[70:71]
	v_cndmask_b32_e64 v153, 0, v153, s[72:73]
	v_cndmask_b32_e64 v154, 0, v154, s[74:75]
	v_cndmask_b32_e64 v155, 0, v155, s[76:77]
	v_add_f32_e32 v132, v132, v152
	v_add_f32_e32 v132, v132, v153
	v_add_f32_e32 v132, v132, v154
	v_add_f32_e32 v132, v132, v155
	v_cvt_pk_bf16_f32 v118, v152, v153
	v_cvt_pk_bf16_f32 v119, v154, v155
	v_min_f32_e32 v152, 0x42a00000, v236
	v_min_f32_e32 v153, 0x42a00000, v237
	v_min_f32_e32 v154, 0x42a00000, v238
	v_min_f32_e32 v155, 0x42a00000, v239
	s_waitcnt vmcnt(4)
	v_mfma_f32_16x16x32_bf16 v[236:239], v[0:3], v[48:51], 0
	v_mfma_f32_16x16x32_bf16 v[236:239], v[4:7], v[52:55], v[236:239]
	v_mul_f32_e32 v152, 0x3fb8aa3b, v152
	v_mul_f32_e32 v153, 0x3fb8aa3b, v153
	v_mul_f32_e32 v154, 0x3fb8aa3b, v154
	v_mul_f32_e32 v155, 0x3fb8aa3b, v155
	v_exp_f32_e32 v152, v152
	v_exp_f32_e32 v153, v153
	v_exp_f32_e32 v154, v154
	v_exp_f32_e32 v155, v155
	v_add_u32_e32 v138, 64, v175
	v_add_u32_e32 v139, 0x41, v175
	v_add_u32_e32 v140, 0x42, v175
	v_add_u32_e32 v141, 0x43, v175
	v_cmp_gt_u32_e64 s[70:71], s44, v138
	v_cmp_gt_u32_e64 s[72:73], s44, v139
	v_cmp_gt_u32_e64 s[74:75], s44, v140
	v_cmp_gt_u32_e64 s[76:77], s44, v141
	v_cndmask_b32_e64 v152, 0, v152, s[70:71]
	v_cndmask_b32_e64 v153, 0, v153, s[72:73]
	v_cndmask_b32_e64 v154, 0, v154, s[74:75]
	v_cndmask_b32_e64 v155, 0, v155, s[76:77]
	v_add_f32_e32 v132, v132, v152
	v_add_f32_e32 v132, v132, v153
	v_add_f32_e32 v132, v132, v154
	v_add_f32_e32 v132, v132, v155
	v_cvt_pk_bf16_f32 v120, v152, v153
	v_cvt_pk_bf16_f32 v121, v154, v155
	v_min_f32_e32 v152, 0x42a00000, v240
	v_min_f32_e32 v153, 0x42a00000, v241
	v_min_f32_e32 v154, 0x42a00000, v242
	v_min_f32_e32 v155, 0x42a00000, v243
	s_waitcnt vmcnt(2)
	v_mfma_f32_16x16x32_bf16 v[240:243], v[8:11], v[48:51], 0
	v_mfma_f32_16x16x32_bf16 v[240:243], v[12:15], v[52:55], v[240:243]
	v_mul_f32_e32 v152, 0x3fb8aa3b, v152
	v_mul_f32_e32 v153, 0x3fb8aa3b, v153
	v_mul_f32_e32 v154, 0x3fb8aa3b, v154
	v_mul_f32_e32 v155, 0x3fb8aa3b, v155
	v_exp_f32_e32 v152, v152
	v_exp_f32_e32 v153, v153
	v_exp_f32_e32 v154, v154
	v_exp_f32_e32 v155, v155
	v_add_u32_e32 v138, 0x50, v175
	v_add_u32_e32 v139, 0x51, v175
	v_add_u32_e32 v140, 0x52, v175
	v_add_u32_e32 v141, 0x53, v175
	v_cmp_gt_u32_e64 s[70:71], s44, v138
	v_cmp_gt_u32_e64 s[72:73], s44, v139
	v_cmp_gt_u32_e64 s[74:75], s44, v140
	v_cmp_gt_u32_e64 s[76:77], s44, v141
	v_cndmask_b32_e64 v152, 0, v152, s[70:71]
	v_cndmask_b32_e64 v153, 0, v153, s[72:73]
	v_cndmask_b32_e64 v154, 0, v154, s[74:75]
	v_cndmask_b32_e64 v155, 0, v155, s[76:77]
	v_add_f32_e32 v132, v132, v152
	v_add_f32_e32 v132, v132, v153
	v_add_f32_e32 v132, v132, v154
	v_add_f32_e32 v132, v132, v155
	v_cvt_pk_bf16_f32 v122, v152, v153
	v_cvt_pk_bf16_f32 v123, v154, v155
	v_min_f32_e32 v152, 0x42a00000, v236
	v_min_f32_e32 v153, 0x42a00000, v237
	v_min_f32_e32 v154, 0x42a00000, v238
	v_min_f32_e32 v155, 0x42a00000, v239
	s_waitcnt vmcnt(0)
	v_mfma_f32_16x16x32_bf16 v[236:239], v[16:19], v[48:51], 0
	v_mfma_f32_16x16x32_bf16 v[236:239], v[20:23], v[52:55], v[236:239]
	v_mul_f32_e32 v152, 0x3fb8aa3b, v152
	v_mul_f32_e32 v153, 0x3fb8aa3b, v153
	v_mul_f32_e32 v154, 0x3fb8aa3b, v154
	v_mul_f32_e32 v155, 0x3fb8aa3b, v155
	v_exp_f32_e32 v152, v152
	v_exp_f32_e32 v153, v153
	v_exp_f32_e32 v154, v154
	v_exp_f32_e32 v155, v155
	v_add_u32_e32 v138, 0x60, v175
	v_add_u32_e32 v139, 0x61, v175
	v_add_u32_e32 v140, 0x62, v175
	v_add_u32_e32 v141, 0x63, v175
	v_cmp_gt_u32_e64 s[70:71], s44, v138
	v_cmp_gt_u32_e64 s[72:73], s44, v139
	v_cmp_gt_u32_e64 s[74:75], s44, v140
	v_cmp_gt_u32_e64 s[76:77], s44, v141
	v_cndmask_b32_e64 v152, 0, v152, s[70:71]
	v_cndmask_b32_e64 v153, 0, v153, s[72:73]
	v_cndmask_b32_e64 v154, 0, v154, s[74:75]
	v_cndmask_b32_e64 v155, 0, v155, s[76:77]
	v_add_f32_e32 v132, v132, v152
	v_add_f32_e32 v132, v132, v153
	v_add_f32_e32 v132, v132, v154
	v_add_f32_e32 v132, v132, v155
	v_cvt_pk_bf16_f32 v124, v152, v153
	v_cvt_pk_bf16_f32 v125, v154, v155
	v_min_f32_e32 v152, 0x42a00000, v240
	v_min_f32_e32 v153, 0x42a00000, v241
	v_min_f32_e32 v154, 0x42a00000, v242
	v_min_f32_e32 v155, 0x42a00000, v243
	v_mul_f32_e32 v152, 0x3fb8aa3b, v152
	v_mul_f32_e32 v153, 0x3fb8aa3b, v153
	v_mul_f32_e32 v154, 0x3fb8aa3b, v154
	v_mul_f32_e32 v155, 0x3fb8aa3b, v155
	v_exp_f32_e32 v152, v152
	v_exp_f32_e32 v153, v153
	v_exp_f32_e32 v154, v154
	v_exp_f32_e32 v155, v155
	v_add_u32_e32 v138, 0x70, v175
	v_add_u32_e32 v139, 0x71, v175
	v_add_u32_e32 v140, 0x72, v175
	v_add_u32_e32 v141, 0x73, v175
	v_cmp_gt_u32_e64 s[70:71], s44, v138
	v_cmp_gt_u32_e64 s[72:73], s44, v139
	v_cmp_gt_u32_e64 s[74:75], s44, v140
	v_cmp_gt_u32_e64 s[76:77], s44, v141
	v_cndmask_b32_e64 v152, 0, v152, s[70:71]
	v_cndmask_b32_e64 v153, 0, v153, s[72:73]
	v_cndmask_b32_e64 v154, 0, v154, s[74:75]
	v_cndmask_b32_e64 v155, 0, v155, s[76:77]
	v_add_f32_e32 v132, v132, v152
	v_add_f32_e32 v132, v132, v153
	v_add_f32_e32 v132, v132, v154
	v_add_f32_e32 v132, v132, v155
	v_cvt_pk_bf16_f32 v126, v152, v153
	v_cvt_pk_bf16_f32 v127, v154, v155
	v_min_f32_e32 v152, 0x42a00000, v236
	v_min_f32_e32 v153, 0x42a00000, v237
	v_min_f32_e32 v154, 0x42a00000, v238
	v_min_f32_e32 v155, 0x42a00000, v239
	v_mul_f32_e32 v152, 0x3fb8aa3b, v152
	v_mul_f32_e32 v153, 0x3fb8aa3b, v153
	v_mul_f32_e32 v154, 0x3fb8aa3b, v154
	v_mul_f32_e32 v155, 0x3fb8aa3b, v155
	v_exp_f32_e32 v152, v152
	v_exp_f32_e32 v153, v153
	v_exp_f32_e32 v154, v154
	v_exp_f32_e32 v155, v155
	v_add_u32_e32 v138, 0x80, v175
	v_add_u32_e32 v139, 0x81, v175
	v_add_u32_e32 v140, 0x82, v175
	v_add_u32_e32 v141, 0x83, v175
	v_cmp_gt_u32_e64 s[70:71], s44, v138
	v_cmp_gt_u32_e64 s[72:73], s44, v139
	v_cmp_gt_u32_e64 s[74:75], s44, v140
	v_cmp_gt_u32_e64 s[76:77], s44, v141
	v_cndmask_b32_e64 v152, 0, v152, s[62:63]
	v_cndmask_b32_e64 v153, 0, v153, s[64:65]
	v_cndmask_b32_e64 v154, 0, v154, s[66:67]
	v_cndmask_b32_e64 v155, 0, v155, s[68:69]
	v_cndmask_b32_e64 v152, 0, v152, s[70:71]
	v_cndmask_b32_e64 v153, 0, v153, s[72:73]
	v_cndmask_b32_e64 v154, 0, v154, s[74:75]
	v_cndmask_b32_e64 v155, 0, v155, s[76:77]
	v_add_f32_e32 v132, v132, v152
	v_add_f32_e32 v132, v132, v153
	v_add_f32_e32 v132, v132, v154
	v_add_f32_e32 v132, v132, v155
	v_cvt_pk_bf16_f32 v128, v152, v153
	v_cvt_pk_bf16_f32 v129, v154, v155
	v_add_u32_e32 v134, s42, v160
	v_add_u32_e32 v134, s43, v134
	v_subrev_u32_e32 v135, s15, v134
	v_lshrrev_b32_e32 v136, 4, v135
	v_add_u32_e32 v136, v136, v135
	v_mad_u32_u24 v176, v136, s79, v161
	v_lshl_add_u32 v177, v135, 2, s80
	s_sub_i32 s2, s42, 64
	v_add_u32_e32 v178, s2, v169
	v_and_b32_e32 v135, 3, v134
	v_lshlrev_b32_e32 v135, s13, v135
	v_lshrrev_b32_e32 v136, 2, v134
	v_add_u32_e32 v135, v135, v136
	v_lshl_add_u32 v135, v135, 7, v161
	global_load_dwordx4 v[48:51], v135, s[18:19]
	global_load_dwordx4 v[52:55], v135, s[18:19] offset:64
	v_add_u32_e32 v137, 16, v134
	v_and_b32_e32 v135, 3, v137
	v_lshlrev_b32_e32 v135, s13, v135
	v_lshrrev_b32_e32 v136, 2, v137
	v_add_u32_e32 v135, v135, v136
	v_lshl_add_u32 v135, v135, 7, v161
	global_load_dwordx4 v[56:59], v135, s[18:19]
	global_load_dwordx4 v[60:63], v135, s[18:19] offset:64
	s_mul_i32 s2, s0, 48
	s_add_i32 s2, s2, s15
	s_add_i32 s2, s2, -64
	v_add_u32_e32 v138, s2, v164
	v_and_b32_e32 v139, 3, v138
	v_lshlrev_b32_e32 v139, s13, v139
	v_bfe_u32 v140, v138, 2, 2
	v_add_u32_e32 v139, v139, v140
	v_lshl_add_u32 v139, v139, 7, v162
	v_ashrrev_i32_e32 v138, 4, v138
	v_med3_i32 v138, v138, 0, s14
	v_lshl_add_u32 v138, v138, 9, v139
	global_load_dwordx4 v[0:3], v138, s[20:21]
	s_mul_i32 s2, s0, 48
	s_add_i32 s2, s2, s15
	s_add_i32 s2, s2, -56
	v_add_u32_e32 v138, s2, v164
	v_and_b32_e32 v139, 3, v138
	v_lshlrev_b32_e32 v139, s13, v139
	v_bfe_u32 v140, v138, 2, 2
	v_add_u32_e32 v139, v139, v140
	v_lshl_add_u32 v139, v139, 7, v162
	v_ashrrev_i32_e32 v138, 4, v138
	v_med3_i32 v138, v138, 0, s14
	v_lshl_add_u32 v138, v138, 9, v139
	global_load_dwordx4 v[4:7], v138, s[20:21]
	s_mul_i32 s2, s0, 48
	s_add_i32 s2, s2, s15
	s_add_i32 s2, s2, -48
	v_add_u32_e32 v138, s2, v164
	v_and_b32_e32 v139, 3, v138
	v_lshlrev_b32_e32 v139, s13, v139
	v_bfe_u32 v140, v138, 2, 2
	v_add_u32_e32 v139, v139, v140
	v_lshl_add_u32 v139, v139, 7, v162
	v_ashrrev_i32_e32 v138, 4, v138
	v_med3_i32 v138, v138, 0, s14
	v_lshl_add_u32 v138, v138, 9, v139
	global_load_dwordx4 v[8:11], v138, s[20:21]
	s_mul_i32 s2, s0, 48
	s_add_i32 s2, s2, s15
	s_add_i32 s2, s2, -40
	v_add_u32_e32 v138, s2, v164
	v_and_b32_e32 v139, 3, v138
	v_lshlrev_b32_e32 v139, s13, v139
	v_bfe_u32 v140, v138, 2, 2
	v_add_u32_e32 v139, v139, v140
	v_lshl_add_u32 v139, v139, 7, v162
	v_ashrrev_i32_e32 v138, 4, v138
	v_med3_i32 v138, v138, 0, s14
	v_lshl_add_u32 v138, v138, 9, v139
	global_load_dwordx4 v[12:15], v138, s[20:21]
	s_mul_i32 s2, s0, 48
	s_add_i32 s2, s2, s15
	s_add_i32 s2, s2, -32
	v_add_u32_e32 v138, s2, v164
	v_and_b32_e32 v139, 3, v138
	v_lshlrev_b32_e32 v139, s13, v139
	v_bfe_u32 v140, v138, 2, 2
	v_add_u32_e32 v139, v139, v140
	v_lshl_add_u32 v139, v139, 7, v162
	v_ashrrev_i32_e32 v138, 4, v138
	v_med3_i32 v138, v138, 0, s14
	v_lshl_add_u32 v138, v138, 9, v139
	global_load_dwordx4 v[16:19], v138, s[20:21]
	s_mul_i32 s2, s0, 48
	s_add_i32 s2, s2, s15
	s_add_i32 s2, s2, -24
	v_add_u32_e32 v138, s2, v164
	v_and_b32_e32 v139, 3, v138
	v_lshlrev_b32_e32 v139, s13, v139
	v_bfe_u32 v140, v138, 2, 2
	v_add_u32_e32 v139, v139, v140
	v_lshl_add_u32 v139, v139, 7, v162
	v_ashrrev_i32_e32 v138, 4, v138
	v_med3_i32 v138, v138, 0, s14
	v_lshl_add_u32 v138, v138, 9, v139
	global_load_dwordx4 v[20:23], v138, s[20:21]
	s_mul_i32 s2, s0, 48
	s_add_i32 s2, s2, s15
	s_add_i32 s2, s2, -64
	v_add_u32_e32 v138, s2, v164
	v_and_b32_e32 v139, 3, v138
	v_lshlrev_b32_e32 v139, s13, v139
	v_bfe_u32 v140, v138, 2, 2
	v_add_u32_e32 v139, v139, v140
	v_lshl_add_u32 v139, v139, 7, v162
	v_ashrrev_i32_e32 v138, 4, v138
	v_med3_i32 v138, v138, 0, s14
	v_lshl_add_u32 v138, v138, 9, v139
	global_load_dwordx4 v[24:27], v138, s[22:23]
	s_mul_i32 s2, s0, 48
	s_add_i32 s2, s2, s15
	s_add_i32 s2, s2, -56
	v_add_u32_e32 v138, s2, v164
	v_and_b32_e32 v139, 3, v138
	v_lshlrev_b32_e32 v139, s13, v139
	v_bfe_u32 v140, v138, 2, 2
	v_add_u32_e32 v139, v139, v140
	v_lshl_add_u32 v139, v139, 7, v162
	v_ashrrev_i32_e32 v138, 4, v138
	v_med3_i32 v138, v138, 0, s14
	v_lshl_add_u32 v138, v138, 9, v139
	global_load_dwordx4 v[28:31], v138, s[22:23]
	s_mul_i32 s2, s0, 48
	s_add_i32 s2, s2, s15
	s_add_i32 s2, s2, -48
	v_add_u32_e32 v138, s2, v164
	v_and_b32_e32 v139, 3, v138
	v_lshlrev_b32_e32 v139, s13, v139
	v_bfe_u32 v140, v138, 2, 2
	v_add_u32_e32 v139, v139, v140
	v_lshl_add_u32 v139, v139, 7, v162
	v_ashrrev_i32_e32 v138, 4, v138
	v_med3_i32 v138, v138, 0, s14
	v_lshl_add_u32 v138, v138, 9, v139
	global_load_dwordx4 v[32:35], v138, s[22:23]
	s_mul_i32 s2, s0, 48
	s_add_i32 s2, s2, s15
	s_add_i32 s2, s2, -40
	v_add_u32_e32 v138, s2, v164
	v_and_b32_e32 v139, 3, v138
	v_lshlrev_b32_e32 v139, s13, v139
	v_bfe_u32 v140, v138, 2, 2
	v_add_u32_e32 v139, v139, v140
	v_lshl_add_u32 v139, v139, 7, v162
	v_ashrrev_i32_e32 v138, 4, v138
	v_med3_i32 v138, v138, 0, s14
	v_lshl_add_u32 v138, v138, 9, v139
	global_load_dwordx4 v[36:39], v138, s[22:23]
	s_mul_i32 s2, s0, 48
	s_add_i32 s2, s2, s15
	s_add_i32 s2, s2, -32
	v_add_u32_e32 v138, s2, v164
	v_and_b32_e32 v139, 3, v138
	v_lshlrev_b32_e32 v139, s13, v139
	v_bfe_u32 v140, v138, 2, 2
	v_add_u32_e32 v139, v139, v140
	v_lshl_add_u32 v139, v139, 7, v162
	v_ashrrev_i32_e32 v138, 4, v138
	v_med3_i32 v138, v138, 0, s14
	v_lshl_add_u32 v138, v138, 9, v139
	global_load_dwordx4 v[40:43], v138, s[22:23]
	s_mul_i32 s2, s0, 48
	s_add_i32 s2, s2, s15
	s_add_i32 s2, s2, -24
	v_add_u32_e32 v138, s2, v164
	v_and_b32_e32 v139, 3, v138
	v_lshlrev_b32_e32 v139, s13, v139
	v_bfe_u32 v140, v138, 2, 2
	v_add_u32_e32 v139, v139, v140
	v_lshl_add_u32 v139, v139, 7, v162
	v_ashrrev_i32_e32 v138, 4, v138
	v_med3_i32 v138, v138, 0, s14
	v_lshl_add_u32 v138, v138, 9, v139
	global_load_dwordx4 v[44:47], v138, s[22:23]
	ds_bpermute_b32 v142, v167, v132
	s_waitcnt lgkmcnt(0)
	v_add_f32_e32 v132, v132, v142
	ds_bpermute_b32 v142, v168, v132
	s_waitcnt lgkmcnt(0)
	v_add_f32_e32 v132, v132, v142
	s_waitcnt vmcnt(16)
	ds_write_b128 v165, v[64:67]
	ds_write_b128 v165, v[68:71] offset:1152
	ds_write_b128 v165, v[72:75] offset:2304
	ds_write_b128 v165, v[76:79] offset:3456
	s_waitcnt lgkmcnt(0)
	ds_read_b64_tr_b16 v[236:237], v166
	ds_read_b64_tr_b16 v[238:239], v166 offset:2304
	ds_read_b64_tr_b16 v[240:241], v166 offset:32
	ds_read_b64_tr_b16 v[242:243], v166 offset:2336
	ds_read_b64_tr_b16 v[244:245], v166 offset:64
	ds_read_b64_tr_b16 v[246:247], v166 offset:2368
	ds_read_b64_tr_b16 v[248:249], v166 offset:96
	ds_read_b64_tr_b16 v[250:251], v166 offset:2400
	s_waitcnt lgkmcnt(0)
	s_add_i32 s2, s40, 32
	v_add_u32_e32 v138, s2, v164
	v_lshlrev_b32_e32 v138, 4, v138
	v_add_u32_e32 v138, s41, v138
	v_and_b32_e32 v139, 3, v138
	v_lshlrev_b32_e32 v139, s39, v139
	v_bfe_u32 v140, v138, 2, 2
	v_add_u32_e32 v139, v139, v140
	v_lshl_add_u32 v139, v139, 7, v162
	v_ashrrev_i32_e32 v138, 4, v138
	v_med3_i32 v138, v138, 0, s38
	v_lshl_add_u32 v138, v138, 9, v139
	global_load_dwordx4 v[64:67], v138, s[26:27]
	s_add_i32 s2, s40, 40
	v_add_u32_e32 v138, s2, v164
	v_lshlrev_b32_e32 v138, 4, v138
	v_add_u32_e32 v138, s41, v138
	v_and_b32_e32 v139, 3, v138
	v_lshlrev_b32_e32 v139, s39, v139
	v_bfe_u32 v140, v138, 2, 2
	v_add_u32_e32 v139, v139, v140
	v_lshl_add_u32 v139, v139, 7, v162
	v_ashrrev_i32_e32 v138, 4, v138
	v_med3_i32 v138, v138, 0, s38
	v_lshl_add_u32 v138, v138, 9, v139
	global_load_dwordx4 v[68:71], v138, s[26:27]
	s_add_i32 s2, s40, 48
	v_add_u32_e32 v138, s2, v164
	v_lshlrev_b32_e32 v138, 4, v138
	v_add_u32_e32 v138, s41, v138
	v_and_b32_e32 v139, 3, v138
	v_lshlrev_b32_e32 v139, s39, v139
	v_bfe_u32 v140, v138, 2, 2
	v_add_u32_e32 v139, v139, v140
	v_lshl_add_u32 v139, v139, 7, v162
	v_ashrrev_i32_e32 v138, 4, v138
	v_med3_i32 v138, v138, 0, s38
	v_lshl_add_u32 v138, v138, 9, v139
	global_load_dwordx4 v[72:75], v138, s[26:27]
	s_add_i32 s2, s40, 56
	v_add_u32_e32 v138, s2, v164
	v_lshlrev_b32_e32 v138, 4, v138
	v_add_u32_e32 v138, s41, v138
	v_and_b32_e32 v139, 3, v138
	v_lshlrev_b32_e32 v139, s39, v139
	v_bfe_u32 v140, v138, 2, 2
	v_add_u32_e32 v139, v139, v140
	v_lshl_add_u32 v139, v139, 7, v162
	v_ashrrev_i32_e32 v138, 4, v138
	v_med3_i32 v138, v138, 0, s38
	v_lshl_add_u32 v138, v138, 9, v139
	global_load_dwordx4 v[76:79], v138, s[26:27]
	ds_write_b128 v165, v[80:83]
	ds_write_b128 v165, v[84:87] offset:1152
	ds_write_b128 v165, v[88:91] offset:2304
	ds_write_b128 v165, v[92:95] offset:3456
	v_mfma_f32_16x16x32_bf16 v[204:207], v[236:239], v[112:115], 0
	v_mfma_f32_16x16x32_bf16 v[208:211], v[240:243], v[112:115], 0
	v_mfma_f32_16x16x32_bf16 v[212:215], v[244:247], v[112:115], 0
	v_mfma_f32_16x16x32_bf16 v[216:219], v[248:251], v[112:115], 0
	s_waitcnt lgkmcnt(0)
	ds_read_b64_tr_b16 v[236:237], v166
	ds_read_b64_tr_b16 v[238:239], v166 offset:2304
	ds_read_b64_tr_b16 v[240:241], v166 offset:32
	ds_read_b64_tr_b16 v[242:243], v166 offset:2336
	ds_read_b64_tr_b16 v[244:245], v166 offset:64
	ds_read_b64_tr_b16 v[246:247], v166 offset:2368
	ds_read_b64_tr_b16 v[248:249], v166 offset:96
	ds_read_b64_tr_b16 v[250:251], v166 offset:2400
	s_waitcnt lgkmcnt(0)
	s_add_i32 s2, s40, 64
	v_add_u32_e32 v138, s2, v164
	v_lshlrev_b32_e32 v138, 4, v138
	v_add_u32_e32 v138, s41, v138
	v_and_b32_e32 v139, 3, v138
	v_lshlrev_b32_e32 v139, s39, v139
	v_bfe_u32 v140, v138, 2, 2
	v_add_u32_e32 v139, v139, v140
	v_lshl_add_u32 v139, v139, 7, v162
	v_ashrrev_i32_e32 v138, 4, v138
	v_med3_i32 v138, v138, 0, s38
	v_lshl_add_u32 v138, v138, 9, v139
	global_load_dwordx4 v[80:83], v138, s[26:27]
	s_add_i32 s2, s40, 72
	v_add_u32_e32 v138, s2, v164
	v_lshlrev_b32_e32 v138, 4, v138
	v_add_u32_e32 v138, s41, v138
	v_and_b32_e32 v139, 3, v138
	v_lshlrev_b32_e32 v139, s39, v139
	v_bfe_u32 v140, v138, 2, 2
	v_add_u32_e32 v139, v139, v140
	v_lshl_add_u32 v139, v139, 7, v162
	v_ashrrev_i32_e32 v138, 4, v138
	v_med3_i32 v138, v138, 0, s38
	v_lshl_add_u32 v138, v138, 9, v139
	global_load_dwordx4 v[84:87], v138, s[26:27]
	ds_write_b128 v165, v[96:99]
	ds_write_b128 v165, v[100:103] offset:1152
	ds_write_b128 v165, v[104:107] offset:2304
	ds_write_b128 v165, v[108:111] offset:3456
	v_mfma_f32_16x16x32_bf16 v[204:207], v[236:239], v[116:119], v[204:207]
	v_mfma_f32_16x16x32_bf16 v[208:211], v[240:243], v[116:119], v[208:211]
	v_mfma_f32_16x16x32_bf16 v[212:215], v[244:247], v[116:119], v[212:215]
	v_mfma_f32_16x16x32_bf16 v[216:219], v[248:251], v[116:119], v[216:219]
	s_waitcnt lgkmcnt(0)
	ds_read_b64_tr_b16 v[236:237], v166
	ds_read_b64_tr_b16 v[238:239], v166 offset:2304
	ds_read_b64_tr_b16 v[240:241], v166 offset:32
	ds_read_b64_tr_b16 v[242:243], v166 offset:2336
	ds_read_b64_tr_b16 v[244:245], v166 offset:64
	ds_read_b64_tr_b16 v[246:247], v166 offset:2368
	ds_read_b64_tr_b16 v[248:249], v166 offset:96
	ds_read_b64_tr_b16 v[250:251], v166 offset:2400
	s_waitcnt lgkmcnt(0)
	s_waitcnt vmcnt(2)
	ds_write_b128 v165, v[64:67]
	ds_write_b128 v165, v[68:71] offset:1152
	ds_write_b128 v165, v[72:75] offset:2304
	ds_write_b128 v165, v[76:79] offset:3456
	v_mfma_f32_16x16x32_bf16 v[204:207], v[236:239], v[120:123], v[204:207]
	v_mfma_f32_16x16x32_bf16 v[208:211], v[240:243], v[120:123], v[208:211]
	v_mfma_f32_16x16x32_bf16 v[212:215], v[244:247], v[120:123], v[212:215]
	v_mfma_f32_16x16x32_bf16 v[216:219], v[248:251], v[120:123], v[216:219]
	s_waitcnt lgkmcnt(0)
	ds_read_b64_tr_b16 v[236:237], v166
	ds_read_b64_tr_b16 v[238:239], v166 offset:2304
	ds_read_b64_tr_b16 v[240:241], v166 offset:32
	ds_read_b64_tr_b16 v[242:243], v166 offset:2336
	ds_read_b64_tr_b16 v[244:245], v166 offset:64
	ds_read_b64_tr_b16 v[246:247], v166 offset:2368
	ds_read_b64_tr_b16 v[248:249], v166 offset:96
	ds_read_b64_tr_b16 v[250:251], v166 offset:2400
	s_waitcnt lgkmcnt(0)
	s_waitcnt vmcnt(0)
	ds_write_b128 v165, v[80:83]
	ds_write_b128 v165, v[84:87] offset:1152
	v_mfma_f32_16x16x32_bf16 v[204:207], v[236:239], v[124:127], v[204:207]
	v_mfma_f32_16x16x32_bf16 v[208:211], v[240:243], v[124:127], v[208:211]
	v_mfma_f32_16x16x32_bf16 v[212:215], v[244:247], v[124:127], v[212:215]
	v_mfma_f32_16x16x32_bf16 v[216:219], v[248:251], v[124:127], v[216:219]
	s_waitcnt lgkmcnt(0)
	ds_read_b64_tr_b16 v[236:237], v166
	ds_read_b64_tr_b16 v[238:239], v166 offset:2304
	ds_read_b64_tr_b16 v[240:241], v166 offset:32
	ds_read_b64_tr_b16 v[242:243], v166 offset:2336
	ds_read_b64_tr_b16 v[244:245], v166 offset:64
	ds_read_b64_tr_b16 v[246:247], v166 offset:2368
	ds_read_b64_tr_b16 v[248:249], v166 offset:96
	ds_read_b64_tr_b16 v[250:251], v166 offset:2400
	s_waitcnt lgkmcnt(0)
	v_mfma_f32_16x16x32_bf16 v[204:207], v[236:239], v[128:131], v[204:207]
	v_mfma_f32_16x16x32_bf16 v[208:211], v[240:243], v[128:131], v[208:211]
	v_mfma_f32_16x16x32_bf16 v[212:215], v[244:247], v[128:131], v[212:215]
	v_mfma_f32_16x16x32_bf16 v[216:219], v[248:251], v[128:131], v[216:219]
	ds_read_b128 v[236:239], v173 offset:0
	ds_read_b128 v[240:243], v173 offset:64
	ds_read_b128 v[244:247], v173 offset:128
	ds_read_b128 v[248:251], v173 offset:192
	ds_read_b32 v142, v174 offset:0
	s_waitcnt lgkmcnt(0)
	v_add_f32_e32 v204, v236, v204
	v_add_f32_e32 v205, v237, v205
	v_add_f32_e32 v206, v238, v206
	v_add_f32_e32 v207, v239, v207
	v_add_f32_e32 v208, v240, v208
	v_add_f32_e32 v209, v241, v209
	v_add_f32_e32 v210, v242, v210
	v_add_f32_e32 v211, v243, v211
	v_add_f32_e32 v212, v244, v212
	v_add_f32_e32 v213, v245, v213
	v_add_f32_e32 v214, v246, v214
	v_add_f32_e32 v215, v247, v215
	v_add_f32_e32 v216, v248, v216
	v_add_f32_e32 v217, v249, v217
	v_add_f32_e32 v218, v250, v218
	v_add_f32_e32 v219, v251, v219
	v_add_f32_e32 v132, v142, v132
	ds_write_b128 v173, v[204:207] offset:0
	ds_write_b128 v173, v[208:211] offset:64
	ds_write_b128 v173, v[212:215] offset:128
	ds_write_b128 v173, v[216:219] offset:192
	ds_write_b32 v174, v132 offset:0
	s_waitcnt lgkmcnt(0)
	s_barrier
	ds_read_b128 v[204:207], v170
	ds_read_b128 v[208:211], v170 offset:16
	ds_read_b128 v[212:215], v170 offset:32
	ds_read_b128 v[216:219], v170 offset:48
	ds_read_b128 v[220:223], v170 offset:64
	ds_read_b128 v[224:227], v170 offset:80
	ds_read_b128 v[228:231], v170 offset:96
	ds_read_b128 v[232:235], v170 offset:112
	ds_read_b32 v142, v171
	s_lshl_b32 s2, s35, 11
	s_lshl_b32 s3, s36, 7
	s_add_u32 s2, s2, s3
	s_add_u32 s90, s6, s2
	s_addc_u32 s91, s7, 0
	s_waitcnt lgkmcnt(0)
	v_div_scale_f32 v143, s[30:31], v142, v142, 1.0
	v_rcp_f32_e32 v147, v143
	v_div_scale_f32 v134, vcc, 1.0, v142, 1.0
	v_fma_f32 v135, -v143, v147, 1.0
	v_fmac_f32_e32 v147, v135, v147
	v_mul_f32_e32 v135, v134, v147
	v_fma_f32 v136, -v143, v135, v134
	v_fmac_f32_e32 v135, v136, v147
	v_fma_f32 v143, -v143, v135, v134
	v_div_fmas_f32 v143, v143, v147, v135
	v_div_fixup_f32 v142, v143, v142, 1.0
	v_mul_f32_e32 v204, v142, v204
	v_mul_f32_e32 v205, v142, v205
	v_mul_f32_e32 v206, v142, v206
	v_mul_f32_e32 v207, v142, v207
	v_mul_f32_e32 v208, v142, v208
	v_mul_f32_e32 v209, v142, v209
	v_mul_f32_e32 v210, v142, v210
	v_mul_f32_e32 v211, v142, v211
	v_mul_f32_e32 v212, v142, v212
	v_mul_f32_e32 v213, v142, v213
	v_mul_f32_e32 v214, v142, v214
	v_mul_f32_e32 v215, v142, v215
	v_mul_f32_e32 v216, v142, v216
	v_mul_f32_e32 v217, v142, v217
	v_mul_f32_e32 v218, v142, v218
	v_mul_f32_e32 v219, v142, v219
	v_mul_f32_e32 v220, v142, v220
	v_mul_f32_e32 v221, v142, v221
	v_mul_f32_e32 v222, v142, v222
	v_mul_f32_e32 v223, v142, v223
	v_mul_f32_e32 v224, v142, v224
	v_mul_f32_e32 v225, v142, v225
	v_mul_f32_e32 v226, v142, v226
	v_mul_f32_e32 v227, v142, v227
	v_mul_f32_e32 v228, v142, v228
	v_mul_f32_e32 v229, v142, v229
	v_mul_f32_e32 v230, v142, v230
	v_mul_f32_e32 v231, v142, v231
	v_mul_f32_e32 v232, v142, v232
	v_mul_f32_e32 v233, v142, v233
	v_mul_f32_e32 v234, v142, v234
	v_mul_f32_e32 v235, v142, v235
	v_cvt_pk_bf16_f32 v112, v204, v205
	v_cvt_pk_bf16_f32 v113, v206, v207
	v_cvt_pk_bf16_f32 v114, v208, v209
	v_cvt_pk_bf16_f32 v115, v210, v211
	v_cvt_pk_bf16_f32 v116, v212, v213
	v_cvt_pk_bf16_f32 v117, v214, v215
	v_cvt_pk_bf16_f32 v118, v216, v217
	v_cvt_pk_bf16_f32 v119, v218, v219
	v_cvt_pk_bf16_f32 v120, v220, v221
	v_cvt_pk_bf16_f32 v121, v222, v223
	v_cvt_pk_bf16_f32 v122, v224, v225
	v_cvt_pk_bf16_f32 v123, v226, v227
	v_cvt_pk_bf16_f32 v124, v228, v229
	v_cvt_pk_bf16_f32 v125, v230, v231
	v_cvt_pk_bf16_f32 v126, v232, v233
	v_cvt_pk_bf16_f32 v127, v234, v235
	global_store_dwordx4 v172, v[112:115], s[90:91] nt
	global_store_dwordx4 v172, v[116:119], s[90:91] offset:16 nt
	global_store_dwordx4 v172, v[120:123], s[90:91] offset:32 nt
	global_store_dwordx4 v172, v[124:127], s[90:91] offset:48 nt
	s_barrier
	s_cmp_eq_u32 s37, 0
	s_cbranch_scc1 .Latt_unit
	s_waitcnt vmcnt(0)
	s_branch .LBB0_365
